# GEMM K-loops: redundant s_waitcnt lgkmcnt(0) after the pre-MFMA barrier removed (the same wait already sits before that barrier)
# speedup vs baseline: 1.0120x; 1.0120x over previous
; #define PG8_STAGE(bufoff, gbase, voff) do { _Pragma("unroll") for (int _i = 0; _i < 2; ++_i) \
;         __builtin_amdgcn_global_load_lds((const unsigned*)((const char*)(gbase) + (voff)[_i]), (LAS unsigned*)(lds + (bufoff) + ldsw + _i * 8192), 16, 0, 0); } while (0)
; #define PG8_LDA(dst, b, h) do { _Pragma("unroll") for (int m = 0; m < 4; ++m) _Pragma("unroll") for (int k = 0; k < 2; ++k) dst[m][k] = *(const LAS bf16x8*)(lds + PG8_SA(b, h) + aoff + m * 2048 + k * 1024); } while (0)
; #define PG8_LDB(dst, b, h) do { _Pragma("unroll") for (int n = 0; n < 2; ++n) _Pragma("unroll") for (int k = 0; k < 2; ++k) dst[n][k] = *(const LAS bf16x8*)(lds + PG8_SB(b, h) + boff + n * 2048 + k * 1024); } while (0)
; #define PG8_MMA(ai, bj, At, Bt) do { __builtin_amdgcn_s_setprio(1); _Pragma("unroll") for (int m = 0; m < 4; ++m) _Pragma("unroll") for (int n = 0; n < 2; ++n) _Pragma("unroll") for (int k = 0; k < 2; ++k) \
;         acc[ai][bj][m][n] = __builtin_amdgcn_mfma_f32_16x16x32_bf16(Bt[n][k], At[m][k], acc[ai][bj][m][n], 0, 0, 0); __builtin_amdgcn_s_setprio(0); } while (0)
; #define PG8_WAIT_V(n) asm volatile("s_waitcnt vmcnt(" #n ")" ::: "memory")
; #define PG8_WAIT_L(n) asm volatile("s_waitcnt lgkmcnt(" #n ")" ::: "memory")
; template <class Epi, class Sched, bool ALIGN_EPI, bool LAST_FUSED = false, bool PERM = false, bool CARRY = false>
; __device__ __forceinline__ void gemm_phase(LAS unsigned char* lds, const int tid, const int K, const int lda, const int ldb, const Sched& S, const Epi& E) {
;     ...
;         for (int t = 0; t < nt; t += 2) {
;             const bool last = (t == nt - 2);
;             const char* a1 = cA + (size_t)(t + 1) * kstep;
;             const char* a2 = last ? nA : cA + (size_t)(t + 2) * kstep; const char* b2 = last ? nB : cB + (size_t)(t + 2) * kstep;
;             const char* a3 = a2 + kstep; const char* b3 = b2 + kstep;
;             PG8_LDB(B0, 0, 0); PG8_LDB(B1, 0, 1); PG8_SCHED; PG8_LDA(At, 0, 0); PG8_STAGE(PG8_SA(1, 1), a1 + hstepA, voffA);
;             PG8_WAIT_V(8); PG8_WAIT_L(0); PG8_BAR; PG8_MMA(0, 0, At, B0); PG8_MMA(0, 1, At, B1); PG8_BAR; PG8_SCHED;
;             PG8_LDA(At, 0, 1); PG8_STAGE(PG8_SB(0, 0), b2, voffB); PG8_STAGE(PG8_SB(0, 1), b2 + hstepB, voffB); PG8_STAGE(PG8_SA(0, 0), a2, voffA);
;             PG8_WAIT_V(8); PG8_WAIT_L(0); PG8_BAR; PG8_MMA(1, 0, At, B0); PG8_MMA(1, 1, At, B1); PG8_BAR; PG8_SCHED;
.LBB0_279:
	s_add_u32 s4, s2, 0xfff80080
	s_addc_u32 s5, s3, -1
	s_add_i32 s28, 0, 0x10000
	s_cmp_eq_u32 s27, 28
	s_cselect_b32 s37, s43, s5
	s_cselect_b32 s36, s42, s4
	s_cselect_b32 s5, s71, s23
	s_cselect_b32 s4, s70, s22
	s_add_i32 s31, 0, 0x14000
	v_add_u32_e32 v154, s28, v144
	v_add_u32_e32 v170, s31, v144
	ds_read_b128 v[136:139], v154
	ds_read_b128 v[146:149], v154 offset:1024
	ds_read_b128 v[150:153], v154 offset:2048
	ds_read_b128 v[154:157], v154 offset:3072
	ds_read_b128 v[158:161], v170
	ds_read_b128 v[162:165], v170 offset:1024
	ds_read_b128 v[166:169], v170 offset:2048
	ds_read_b128 v[170:173], v170 offset:3072
	v_lshl_add_u64 v[206:207], s[2:3], 0, v[132:133]
	s_add_i32 m0, s52, 0xc000
	ds_read_b128 v[174:177], v145
	ds_read_b128 v[178:181], v145 offset:1024
	ds_read_b128 v[182:185], v145 offset:2048
	ds_read_b128 v[186:189], v145 offset:3072
	ds_read_b128 v[190:193], v145 offset:4096
	ds_read_b128 v[194:197], v145 offset:5120
	ds_read_b128 v[198:201], v145 offset:6144
	ds_read_b128 v[202:205], v145 offset:7168
	global_load_lds_dwordx4 v[206:207], off
	v_lshl_add_u64 v[206:207], s[2:3], 0, v[134:135]
	s_add_i32 m0, s52, 0xe000
	s_nop 0
	global_load_lds_dwordx4 v[206:207], off
	s_waitcnt vmcnt(8)
	s_waitcnt lgkmcnt(0)
	s_barrier
	s_setprio 1
	v_mfma_f32_16x16x32_bf16 v[126:129], v[136:139], v[174:177], v[126:129]
	v_mfma_f32_16x16x32_bf16 v[122:125], v[150:153], v[174:177], v[122:125]
	v_mfma_f32_16x16x32_bf16 v[110:113], v[136:139], v[182:185], v[110:113]
	v_mfma_f32_16x16x32_bf16 v[106:109], v[150:153], v[182:185], v[106:109]
	v_mfma_f32_16x16x32_bf16 v[94:97], v[136:139], v[190:193], v[94:97]
	v_mfma_f32_16x16x32_bf16 v[90:93], v[150:153], v[190:193], v[90:93]
	v_mfma_f32_16x16x32_bf16 v[78:81], v[136:139], v[198:201], v[78:81]
	v_mfma_f32_16x16x32_bf16 v[74:77], v[150:153], v[198:201], v[74:77]
	v_mfma_f32_16x16x32_bf16 v[126:129], v[146:149], v[178:181], v[126:129]
	v_mfma_f32_16x16x32_bf16 v[122:125], v[154:157], v[178:181], v[122:125]
	v_mfma_f32_16x16x32_bf16 v[110:113], v[146:149], v[186:189], v[110:113]
	v_mfma_f32_16x16x32_bf16 v[106:109], v[154:157], v[186:189], v[106:109]
	v_mfma_f32_16x16x32_bf16 v[94:97], v[146:149], v[194:197], v[94:97]
	v_mfma_f32_16x16x32_bf16 v[90:93], v[154:157], v[194:197], v[90:93]
	v_mfma_f32_16x16x32_bf16 v[78:81], v[146:149], v[202:205], v[78:81]
	v_mfma_f32_16x16x32_bf16 v[74:77], v[154:157], v[202:205], v[74:77]
	s_setprio 0
	s_setprio 1
	v_mfma_f32_16x16x32_bf16 v[118:121], v[158:161], v[174:177], v[118:121]
	v_mfma_f32_16x16x32_bf16 v[114:117], v[166:169], v[174:177], v[114:117]
	v_mfma_f32_16x16x32_bf16 v[102:105], v[158:161], v[182:185], v[102:105]
	v_mfma_f32_16x16x32_bf16 v[98:101], v[166:169], v[182:185], v[98:101]
	v_mfma_f32_16x16x32_bf16 v[86:89], v[158:161], v[190:193], v[86:89]
	v_mfma_f32_16x16x32_bf16 v[82:85], v[166:169], v[190:193], v[82:85]
	v_mfma_f32_16x16x32_bf16 v[70:73], v[158:161], v[198:201], v[70:73]
	v_mfma_f32_16x16x32_bf16 v[66:69], v[166:169], v[198:201], v[66:69]
	v_mfma_f32_16x16x32_bf16 v[118:121], v[162:165], v[178:181], v[118:121]
	v_mfma_f32_16x16x32_bf16 v[114:117], v[170:173], v[178:181], v[114:117]
	v_mfma_f32_16x16x32_bf16 v[102:105], v[162:165], v[186:189], v[102:105]
	v_mfma_f32_16x16x32_bf16 v[98:101], v[170:173], v[186:189], v[98:101]
	v_mfma_f32_16x16x32_bf16 v[86:89], v[162:165], v[194:197], v[86:89]
	v_mfma_f32_16x16x32_bf16 v[82:85], v[170:173], v[194:197], v[82:85]
	v_mfma_f32_16x16x32_bf16 v[70:73], v[162:165], v[202:205], v[70:73]
	v_mfma_f32_16x16x32_bf16 v[66:69], v[170:173], v[202:205], v[66:69]
	s_setprio 0
	s_barrier
	s_add_i32 s28, s28, s51
	v_lshl_add_u64 v[206:207], s[4:5], 0, v[0:1]
	s_mov_b32 m0, s28
	ds_read_b128 v[174:177], v145 offset:16384
	ds_read_b128 v[178:181], v145 offset:17408
	ds_read_b128 v[182:185], v145 offset:18432
	ds_read_b128 v[186:189], v145 offset:19456
	ds_read_b128 v[190:193], v145 offset:20480
	ds_read_b128 v[194:197], v145 offset:21504
	ds_read_b128 v[198:201], v145 offset:22528
	ds_read_b128 v[202:205], v145 offset:23552
	global_load_lds_dwordx4 v[206:207], off
	s_add_i32 m0, s28, 0x2000
	s_add_u32 s28, s4, 0x80000
	v_lshl_add_u64 v[208:209], s[4:5], 0, v[130:131]
	s_addc_u32 s29, s5, 0
	s_add_i32 s31, s31, s51
	global_load_lds_dwordx4 v[208:209], off
	v_lshl_add_u64 v[210:211], s[28:29], 0, v[0:1]
	s_mov_b32 m0, s31
	v_lshl_add_u64 v[212:213], s[36:37], 0, v[130:131]
	global_load_lds_dwordx4 v[210:211], off
	v_lshl_add_u64 v[210:211], s[28:29], 0, v[130:131]
	s_add_i32 m0, s31, 0x2000
	s_nop 0
	global_load_lds_dwordx4 v[210:211], off
	v_lshl_add_u64 v[210:211], s[36:37], 0, v[0:1]
	s_mov_b32 m0, s52
	s_nop 0
	global_load_lds_dwordx4 v[210:211], off
	s_mov_b32 m0, s53
	s_nop 0
	global_load_lds_dwordx4 v[212:213], off
	s_waitcnt vmcnt(8)
	s_waitcnt lgkmcnt(0)
	s_barrier
; #define PG8_STAGE(bufoff, gbase, voff) do { _Pragma("unroll") for (int _i = 0; _i < 2; ++_i) \
;         __builtin_amdgcn_global_load_lds((const unsigned*)((const char*)(gbase) + (voff)[_i]), (LAS unsigned*)(lds + (bufoff) + ldsw + _i * 8192), 16, 0, 0); } while (0)
; #define PG8_LDA(dst, b, h) do { _Pragma("unroll") for (int m = 0; m < 4; ++m) _Pragma("unroll") for (int k = 0; k < 2; ++k) dst[m][k] = *(const LAS bf16x8*)(lds + PG8_SA(b, h) + aoff + m * 2048 + k * 1024); } while (0)
; #define PG8_LDB(dst, b, h) do { _Pragma("unroll") for (int n = 0; n < 2; ++n) _Pragma("unroll") for (int k = 0; k < 2; ++k) dst[n][k] = *(const LAS bf16x8*)(lds + PG8_SB(b, h) + boff + n * 2048 + k * 1024); } while (0)
; #define PG8_MMA(ai, bj, At, Bt) do { __builtin_amdgcn_s_setprio(1); _Pragma("unroll") for (int m = 0; m < 4; ++m) _Pragma("unroll") for (int n = 0; n < 2; ++n) _Pragma("unroll") for (int k = 0; k < 2; ++k) \
;         acc[ai][bj][m][n] = __builtin_amdgcn_mfma_f32_16x16x32_bf16(Bt[n][k], At[m][k], acc[ai][bj][m][n], 0, 0, 0); __builtin_amdgcn_s_setprio(0); } while (0)
; #define PG8_WAIT_V(n) asm volatile("s_waitcnt vmcnt(" #n ")" ::: "memory")
; #define PG8_WAIT_L(n) asm volatile("s_waitcnt lgkmcnt(" #n ")" ::: "memory")
; #define PG8_BAR __builtin_amdgcn_s_barrier()
; #define PG8_SCHED __builtin_amdgcn_sched_barrier(0)
; template <class Epi, class Sched, bool ALIGN_EPI, bool LAST_FUSED = false, bool PERM = false, bool CARRY = false>
; __device__ __forceinline__ void gemm_phase(LAS unsigned char* lds, const int tid, const int K, const int lda, const int ldb, const Sched& S, const Epi& E) {
;     ...
;             PG8_WAIT_V(8); PG8_WAIT_L(0); PG8_BAR; PG8_MMA(1, 0, At, B0); PG8_MMA(1, 1, At, B1); PG8_BAR; PG8_SCHED;
;             PG8_LDB(B0, 1, 0); PG8_LDB(B1, 1, 1); PG8_SCHED; PG8_LDA(At, 1, 0); PG8_STAGE(PG8_SA(0, 1), a2 + hstepA, voffA);
;             PG8_WAIT_V(8); PG8_WAIT_L(0); PG8_BAR; PG8_MMA(0, 0, At, B0); PG8_MMA(0, 1, At, B1); PG8_BAR; PG8_SCHED;
	s_setprio 1
	v_mfma_f32_16x16x32_bf16 v[62:65], v[136:139], v[174:177], v[62:65]
	v_mfma_f32_16x16x32_bf16 v[58:61], v[150:153], v[174:177], v[58:61]
	v_mfma_f32_16x16x32_bf16 v[46:49], v[136:139], v[182:185], v[46:49]
	v_mfma_f32_16x16x32_bf16 v[42:45], v[150:153], v[182:185], v[42:45]
	v_mfma_f32_16x16x32_bf16 v[30:33], v[136:139], v[190:193], v[30:33]
	v_mfma_f32_16x16x32_bf16 v[26:29], v[150:153], v[190:193], v[26:29]
	v_mfma_f32_16x16x32_bf16 v[14:17], v[136:139], v[198:201], v[14:17]
	v_mfma_f32_16x16x32_bf16 v[10:13], v[150:153], v[198:201], v[10:13]
	v_mfma_f32_16x16x32_bf16 v[62:65], v[146:149], v[178:181], v[62:65]
	v_mfma_f32_16x16x32_bf16 v[58:61], v[154:157], v[178:181], v[58:61]
	v_mfma_f32_16x16x32_bf16 v[46:49], v[146:149], v[186:189], v[46:49]
	v_mfma_f32_16x16x32_bf16 v[42:45], v[154:157], v[186:189], v[42:45]
	v_mfma_f32_16x16x32_bf16 v[30:33], v[146:149], v[194:197], v[30:33]
	v_mfma_f32_16x16x32_bf16 v[26:29], v[154:157], v[194:197], v[26:29]
	v_mfma_f32_16x16x32_bf16 v[14:17], v[146:149], v[202:205], v[14:17]
	v_mfma_f32_16x16x32_bf16 v[10:13], v[154:157], v[202:205], v[10:13]
	s_setprio 0
	s_setprio 1
	v_mfma_f32_16x16x32_bf16 v[54:57], v[158:161], v[174:177], v[54:57]
	v_mfma_f32_16x16x32_bf16 v[50:53], v[166:169], v[174:177], v[50:53]
	v_mfma_f32_16x16x32_bf16 v[38:41], v[158:161], v[182:185], v[38:41]
	v_mfma_f32_16x16x32_bf16 v[34:37], v[166:169], v[182:185], v[34:37]
	v_mfma_f32_16x16x32_bf16 v[22:25], v[158:161], v[190:193], v[22:25]
	v_mfma_f32_16x16x32_bf16 v[18:21], v[166:169], v[190:193], v[18:21]
	v_mfma_f32_16x16x32_bf16 v[6:9], v[158:161], v[198:201], v[6:9]
	v_mfma_f32_16x16x32_bf16 v[2:5], v[166:169], v[198:201], v[2:5]
	v_mfma_f32_16x16x32_bf16 v[54:57], v[162:165], v[178:181], v[54:57]
	v_mfma_f32_16x16x32_bf16 v[50:53], v[170:173], v[178:181], v[50:53]
	v_mfma_f32_16x16x32_bf16 v[38:41], v[162:165], v[186:189], v[38:41]
	v_mfma_f32_16x16x32_bf16 v[34:37], v[170:173], v[186:189], v[34:37]
	v_mfma_f32_16x16x32_bf16 v[22:25], v[162:165], v[194:197], v[22:25]
	v_mfma_f32_16x16x32_bf16 v[18:21], v[170:173], v[194:197], v[18:21]
	v_mfma_f32_16x16x32_bf16 v[6:9], v[162:165], v[202:205], v[6:9]
	v_mfma_f32_16x16x32_bf16 v[2:5], v[170:173], v[202:205], v[2:5]
	s_setprio 0
	s_barrier
	s_add_i32 s31, 0, 0x18000
	s_add_i32 s35, 0, 0x1c000
	v_add_u32_e32 v154, s31, v144
	v_add_u32_e32 v170, s35, v144
	ds_read_b128 v[136:139], v154
	ds_read_b128 v[146:149], v154 offset:1024
	ds_read_b128 v[150:153], v154 offset:2048
	ds_read_b128 v[154:157], v154 offset:3072
	ds_read_b128 v[158:161], v170
	ds_read_b128 v[162:165], v170 offset:1024
	ds_read_b128 v[166:169], v170 offset:2048
	ds_read_b128 v[170:173], v170 offset:3072
	s_add_u32 s28, s36, 0x80000
	s_addc_u32 s29, s37, 0
	s_mov_b32 m0, s54
	v_lshl_add_u64 v[214:215], s[28:29], 0, v[0:1]
	ds_read_b128 v[174:177], v145 offset:32768
	ds_read_b128 v[178:181], v145 offset:33792
	ds_read_b128 v[182:185], v145 offset:34816
	ds_read_b128 v[186:189], v145 offset:35840
	ds_read_b128 v[190:193], v145 offset:36864
	ds_read_b128 v[194:197], v145 offset:37888
	ds_read_b128 v[198:201], v145 offset:38912
	ds_read_b128 v[202:205], v145 offset:39936
	global_load_lds_dwordx4 v[214:215], off
	v_lshl_add_u64 v[214:215], s[28:29], 0, v[130:131]
	s_mov_b32 m0, s55
	s_nop 0
	global_load_lds_dwordx4 v[214:215], off
	s_waitcnt vmcnt(8)
	s_waitcnt lgkmcnt(0)
	s_barrier
	s_setprio 1
	v_mfma_f32_16x16x32_bf16 v[126:129], v[136:139], v[174:177], v[126:129]
	v_mfma_f32_16x16x32_bf16 v[122:125], v[150:153], v[174:177], v[122:125]
	v_mfma_f32_16x16x32_bf16 v[110:113], v[136:139], v[182:185], v[110:113]
	v_mfma_f32_16x16x32_bf16 v[106:109], v[150:153], v[182:185], v[106:109]
	v_mfma_f32_16x16x32_bf16 v[94:97], v[136:139], v[190:193], v[94:97]
	v_mfma_f32_16x16x32_bf16 v[90:93], v[150:153], v[190:193], v[90:93]
	v_mfma_f32_16x16x32_bf16 v[78:81], v[136:139], v[198:201], v[78:81]
	v_mfma_f32_16x16x32_bf16 v[74:77], v[150:153], v[198:201], v[74:77]
	v_mfma_f32_16x16x32_bf16 v[126:129], v[146:149], v[178:181], v[126:129]
	v_mfma_f32_16x16x32_bf16 v[122:125], v[154:157], v[178:181], v[122:125]
	v_mfma_f32_16x16x32_bf16 v[110:113], v[146:149], v[186:189], v[110:113]
	v_mfma_f32_16x16x32_bf16 v[106:109], v[154:157], v[186:189], v[106:109]
	v_mfma_f32_16x16x32_bf16 v[94:97], v[146:149], v[194:197], v[94:97]
	v_mfma_f32_16x16x32_bf16 v[90:93], v[154:157], v[194:197], v[90:93]
	v_mfma_f32_16x16x32_bf16 v[78:81], v[146:149], v[202:205], v[78:81]
	v_mfma_f32_16x16x32_bf16 v[74:77], v[154:157], v[202:205], v[74:77]
	s_setprio 0
	s_setprio 1
	v_mfma_f32_16x16x32_bf16 v[118:121], v[158:161], v[174:177], v[118:121]
	v_mfma_f32_16x16x32_bf16 v[114:117], v[166:169], v[174:177], v[114:117]
	v_mfma_f32_16x16x32_bf16 v[102:105], v[158:161], v[182:185], v[102:105]
	v_mfma_f32_16x16x32_bf16 v[98:101], v[166:169], v[182:185], v[98:101]
	v_mfma_f32_16x16x32_bf16 v[86:89], v[158:161], v[190:193], v[86:89]
	v_mfma_f32_16x16x32_bf16 v[82:85], v[166:169], v[190:193], v[82:85]
	v_mfma_f32_16x16x32_bf16 v[70:73], v[158:161], v[198:201], v[70:73]
	v_mfma_f32_16x16x32_bf16 v[66:69], v[166:169], v[198:201], v[66:69]
	v_mfma_f32_16x16x32_bf16 v[118:121], v[162:165], v[178:181], v[118:121]
	v_mfma_f32_16x16x32_bf16 v[114:117], v[170:173], v[178:181], v[114:117]
	v_mfma_f32_16x16x32_bf16 v[102:105], v[162:165], v[186:189], v[102:105]
	v_mfma_f32_16x16x32_bf16 v[98:101], v[170:173], v[186:189], v[98:101]
	v_mfma_f32_16x16x32_bf16 v[86:89], v[162:165], v[194:197], v[86:89]
	v_mfma_f32_16x16x32_bf16 v[82:85], v[170:173], v[194:197], v[82:85]
	v_mfma_f32_16x16x32_bf16 v[70:73], v[162:165], v[202:205], v[70:73]
	v_mfma_f32_16x16x32_bf16 v[66:69], v[170:173], v[202:205], v[66:69]
	s_setprio 0
	s_barrier
; #define PG8_STAGE(bufoff, gbase, voff) do { _Pragma("unroll") for (int _i = 0; _i < 2; ++_i) \
;         __builtin_amdgcn_global_load_lds((const unsigned*)((const char*)(gbase) + (voff)[_i]), (LAS unsigned*)(lds + (bufoff) + ldsw + _i * 8192), 16, 0, 0); } while (0)
; #define PG8_LDA(dst, b, h) do { _Pragma("unroll") for (int m = 0; m < 4; ++m) _Pragma("unroll") for (int k = 0; k < 2; ++k) dst[m][k] = *(const LAS bf16x8*)(lds + PG8_SA(b, h) + aoff + m * 2048 + k * 1024); } while (0)
; #define PG8_WAIT_V(n) asm volatile("s_waitcnt vmcnt(" #n ")" ::: "memory")
; #define PG8_WAIT_L(n) asm volatile("s_waitcnt lgkmcnt(" #n ")" ::: "memory")
; template <class Epi, class Sched, bool ALIGN_EPI, bool LAST_FUSED = false, bool PERM = false, bool CARRY = false>
; __device__ __forceinline__ void gemm_phase(LAS unsigned char* lds, const int tid, const int K, const int lda, const int ldb, const Sched& S, const Epi& E) {
;     ...
;         for (int t = 0; t < nt; t += 2) {
;             const bool last = (t == nt - 2);
;             const char* a1 = cA + (size_t)(t + 1) * kstep;
;             const char* a2 = last ? nA : cA + (size_t)(t + 2) * kstep; const char* b2 = last ? nB : cB + (size_t)(t + 2) * kstep;
;             const char* a3 = a2 + kstep; const char* b3 = b2 + kstep;
;             PG8_LDB(B0, 0, 0); PG8_LDB(B1, 0, 1); PG8_SCHED; PG8_LDA(At, 0, 0); PG8_STAGE(PG8_SA(1, 1), a1 + hstepA, voffA);
;             PG8_WAIT_V(8); PG8_WAIT_L(0); PG8_BAR; PG8_MMA(0, 0, At, B0); PG8_MMA(0, 1, At, B1); PG8_BAR; PG8_SCHED;
;             PG8_LDA(At, 0, 1); PG8_STAGE(PG8_SB(0, 0), b2, voffB); PG8_STAGE(PG8_SB(0, 1), b2 + hstepB, voffB); PG8_STAGE(PG8_SA(0, 0), a2, voffA);
;             PG8_WAIT_V(8); PG8_WAIT_L(0); PG8_BAR; PG8_MMA(1, 0, At, B0); PG8_MMA(1, 1, At, B1); PG8_BAR; PG8_SCHED;
;             PG8_LDB(B0, 1, 0); PG8_LDB(B1, 1, 1); PG8_SCHED; PG8_LDA(At, 1, 0); PG8_STAGE(PG8_SA(0, 1), a2 + hstepA, voffA);
;             PG8_WAIT_V(8); PG8_WAIT_L(0); PG8_BAR; PG8_MMA(0, 0, At, B0); PG8_MMA(0, 1, At, B1); PG8_BAR; PG8_SCHED;
;             PG8_LDA(At, 1, 1); PG8_STAGE(PG8_SB(1, 0), b3, voffB); PG8_STAGE(PG8_SB(1, 1), b3 + hstepB, voffB); PG8_STAGE(PG8_SA(1, 0), a3, voffA);
;             PG8_WAIT_V(8); PG8_WAIT_L(0); PG8_BAR; PG8_MMA(1, 0, At, B0); PG8_MMA(1, 1, At, B1); PG8_BAR; PG8_SCHED;
;         }
;         if constexpr (ALIGN_EPI) { if (wr == 0) PG8_BAR; }
	s_add_i32 s28, s31, s51
	v_lshl_add_u64 v[206:207], v[206:207], 0, s[68:69]
	s_mov_b32 m0, s28
	ds_read_b128 v[174:177], v145 offset:49152
	ds_read_b128 v[178:181], v145 offset:50176
	ds_read_b128 v[182:185], v145 offset:51200
	ds_read_b128 v[186:189], v145 offset:52224
	ds_read_b128 v[190:193], v145 offset:53248
	ds_read_b128 v[194:197], v145 offset:54272
	ds_read_b128 v[198:201], v145 offset:55296
	ds_read_b128 v[202:205], v145 offset:56320
	global_load_lds_dwordx4 v[206:207], off
	s_add_i32 m0, s28, 0x2000
	s_add_u32 s4, s4, 0x80080
	v_lshl_add_u64 v[206:207], v[208:209], 0, s[68:69]
	s_addc_u32 s5, s5, 0
	s_add_i32 s28, s35, s51
	global_load_lds_dwordx4 v[206:207], off
	v_lshl_add_u64 v[206:207], s[4:5], 0, v[0:1]
	s_mov_b32 m0, s28
	s_nop 0
	global_load_lds_dwordx4 v[206:207], off
	v_lshl_add_u64 v[206:207], s[4:5], 0, v[130:131]
	s_add_i32 m0, s28, 0x2000
	s_nop 0
	global_load_lds_dwordx4 v[206:207], off
	v_lshl_add_u64 v[206:207], v[210:211], 0, s[68:69]
	s_mov_b32 m0, s57
	s_nop 0
	global_load_lds_dwordx4 v[206:207], off
	v_lshl_add_u64 v[206:207], v[212:213], 0, s[68:69]
	s_mov_b32 m0, s58
	s_nop 0
	global_load_lds_dwordx4 v[206:207], off
	s_waitcnt vmcnt(8)
	s_waitcnt lgkmcnt(0)
	s_barrier
	s_setprio 1
	v_mfma_f32_16x16x32_bf16 v[62:65], v[136:139], v[174:177], v[62:65]
	v_mfma_f32_16x16x32_bf16 v[58:61], v[150:153], v[174:177], v[58:61]
	v_mfma_f32_16x16x32_bf16 v[46:49], v[136:139], v[182:185], v[46:49]
	v_mfma_f32_16x16x32_bf16 v[42:45], v[150:153], v[182:185], v[42:45]
	v_mfma_f32_16x16x32_bf16 v[30:33], v[136:139], v[190:193], v[30:33]
	v_mfma_f32_16x16x32_bf16 v[26:29], v[150:153], v[190:193], v[26:29]
	v_mfma_f32_16x16x32_bf16 v[14:17], v[136:139], v[198:201], v[14:17]
	v_mfma_f32_16x16x32_bf16 v[10:13], v[150:153], v[198:201], v[10:13]
	v_mfma_f32_16x16x32_bf16 v[62:65], v[146:149], v[178:181], v[62:65]
	v_mfma_f32_16x16x32_bf16 v[58:61], v[154:157], v[178:181], v[58:61]
	v_mfma_f32_16x16x32_bf16 v[46:49], v[146:149], v[186:189], v[46:49]
	v_mfma_f32_16x16x32_bf16 v[42:45], v[154:157], v[186:189], v[42:45]
	v_mfma_f32_16x16x32_bf16 v[30:33], v[146:149], v[194:197], v[30:33]
	v_mfma_f32_16x16x32_bf16 v[26:29], v[154:157], v[194:197], v[26:29]
	v_mfma_f32_16x16x32_bf16 v[14:17], v[146:149], v[202:205], v[14:17]
	v_mfma_f32_16x16x32_bf16 v[10:13], v[154:157], v[202:205], v[10:13]
	s_setprio 0
	s_setprio 1
	v_mfma_f32_16x16x32_bf16 v[54:57], v[158:161], v[174:177], v[54:57]
	v_mfma_f32_16x16x32_bf16 v[50:53], v[166:169], v[174:177], v[50:53]
	v_mfma_f32_16x16x32_bf16 v[38:41], v[158:161], v[182:185], v[38:41]
	v_mfma_f32_16x16x32_bf16 v[34:37], v[166:169], v[182:185], v[34:37]
	v_mfma_f32_16x16x32_bf16 v[22:25], v[158:161], v[190:193], v[22:25]
	v_mfma_f32_16x16x32_bf16 v[18:21], v[166:169], v[190:193], v[18:21]
	v_mfma_f32_16x16x32_bf16 v[6:9], v[158:161], v[198:201], v[6:9]
	v_mfma_f32_16x16x32_bf16 v[2:5], v[166:169], v[198:201], v[2:5]
	v_mfma_f32_16x16x32_bf16 v[54:57], v[162:165], v[178:181], v[54:57]
	v_mfma_f32_16x16x32_bf16 v[50:53], v[170:173], v[178:181], v[50:53]
	v_mfma_f32_16x16x32_bf16 v[38:41], v[162:165], v[186:189], v[38:41]
	v_mfma_f32_16x16x32_bf16 v[34:37], v[170:173], v[186:189], v[34:37]
	v_mfma_f32_16x16x32_bf16 v[22:25], v[162:165], v[194:197], v[22:25]
	v_mfma_f32_16x16x32_bf16 v[18:21], v[170:173], v[194:197], v[18:21]
	v_mfma_f32_16x16x32_bf16 v[6:9], v[162:165], v[202:205], v[6:9]
	v_mfma_f32_16x16x32_bf16 v[2:5], v[170:173], v[202:205], v[2:5]
	s_setprio 0
	s_barrier
	s_add_i32 s27, s27, 2
	s_add_u32 s2, s2, 0x100
	s_addc_u32 s3, s3, 0
	s_add_u32 s22, s22, 0x100
	s_addc_u32 s23, s23, 0
	s_cmp_gt_u32 s27, 29
	s_cbranch_scc0 .LBB0_279
	s_and_b64 vcc, exec, s[18:19]
	s_cbranch_vccz .LBB0_282
	s_barrier

; #define PG8_STAGE(bufoff, gbase, voff) do { _Pragma("unroll") for (int _i = 0; _i < 2; ++_i) \
;         __builtin_amdgcn_global_load_lds((const unsigned*)((const char*)(gbase) + (voff)[_i]), (LAS unsigned*)(lds + (bufoff) + ldsw + _i * 8192), 16, 0, 0); } while (0)
; #define PG8_LDA(dst, b, h) do { _Pragma("unroll") for (int m = 0; m < 4; ++m) _Pragma("unroll") for (int k = 0; k < 2; ++k) dst[m][k] = *(const LAS bf16x8*)(lds + PG8_SA(b, h) + aoff + m * 2048 + k * 1024); } while (0)
; #define PG8_LDB(dst, b, h) do { _Pragma("unroll") for (int n = 0; n < 2; ++n) _Pragma("unroll") for (int k = 0; k < 2; ++k) dst[n][k] = *(const LAS bf16x8*)(lds + PG8_SB(b, h) + boff + n * 2048 + k * 1024); } while (0)
; #define PG8_MMA(ai, bj, At, Bt) do { __builtin_amdgcn_s_setprio(1); _Pragma("unroll") for (int m = 0; m < 4; ++m) _Pragma("unroll") for (int n = 0; n < 2; ++n) _Pragma("unroll") for (int k = 0; k < 2; ++k) \
;         acc[ai][bj][m][n] = __builtin_amdgcn_mfma_f32_16x16x32_bf16(Bt[n][k], At[m][k], acc[ai][bj][m][n], 0, 0, 0); __builtin_amdgcn_s_setprio(0); } while (0)
; #define PG8_WAIT_V(n) asm volatile("s_waitcnt vmcnt(" #n ")" ::: "memory")
; #define PG8_WAIT_L(n) asm volatile("s_waitcnt lgkmcnt(" #n ")" ::: "memory")
; template <class Epi, class Sched, bool ALIGN_EPI, bool LAST_FUSED = false, bool PERM = false, bool CARRY = false>
; __device__ __forceinline__ void gemm_phase(LAS unsigned char* lds, const int tid, const int K, const int lda, const int ldb, const Sched& S, const Epi& E) {
;     ...
;         for (int t = 0; t < nt; t += 2) {
;             const bool last = (t == nt - 2);
;             const char* a1 = cA + (size_t)(t + 1) * kstep;
;             const char* a2 = last ? nA : cA + (size_t)(t + 2) * kstep; const char* b2 = last ? nB : cB + (size_t)(t + 2) * kstep;
;             const char* a3 = a2 + kstep; const char* b3 = b2 + kstep;
;             PG8_LDB(B0, 0, 0); PG8_LDB(B1, 0, 1); PG8_SCHED; PG8_LDA(At, 0, 0); PG8_STAGE(PG8_SA(1, 1), a1 + hstepA, voffA);
;             PG8_WAIT_V(8); PG8_WAIT_L(0); PG8_BAR; PG8_MMA(0, 0, At, B0); PG8_MMA(0, 1, At, B1); PG8_BAR; PG8_SCHED;
;             PG8_LDA(At, 0, 1); PG8_STAGE(PG8_SB(0, 0), b2, voffB); PG8_STAGE(PG8_SB(0, 1), b2 + hstepB, voffB); PG8_STAGE(PG8_SA(0, 0), a2, voffA);
;             PG8_WAIT_V(8); PG8_WAIT_L(0); PG8_BAR; PG8_MMA(1, 0, At, B0); PG8_MMA(1, 1, At, B1); PG8_BAR; PG8_SCHED;
.LBB0_512:
	s_add_u32 s28, s4, 0xfff80080
	s_addc_u32 s29, s5, -1
	s_add_i32 s31, 0, 0x10000
	s_cmp_eq_u32 s24, 28
	s_cselect_b32 s41, s87, s29
	s_cselect_b32 s40, s86, s28
	v_add_u32_e32 v148, s31, v160
	s_cselect_b32 s37, s39, s23
	s_cselect_b32 s36, s38, s22
	s_add_i32 s35, 0, 0x14000
	ds_read_b128 v[140:143], v148
	ds_read_b128 v[144:147], v148 offset:1024
	ds_read_b128 v[162:165], v148 offset:2048
	ds_read_b128 v[166:169], v148 offset:3072
	v_add_u32_e32 v148, s35, v160
	ds_read_b128 v[170:173], v148
	ds_read_b128 v[174:177], v148 offset:1024
	ds_read_b128 v[178:181], v148 offset:2048
	ds_read_b128 v[182:185], v148 offset:3072
	v_lshl_add_u64 v[148:149], s[4:5], 0, v[136:137]
	s_add_i32 m0, s54, 0xc000
	ds_read_b128 v[186:189], v161
	ds_read_b128 v[190:193], v161 offset:1024
	ds_read_b128 v[194:197], v161 offset:2048
	ds_read_b128 v[198:201], v161 offset:3072
	ds_read_b128 v[202:205], v161 offset:4096
	ds_read_b128 v[206:209], v161 offset:5120
	ds_read_b128 v[210:213], v161 offset:6144
	ds_read_b128 v[214:217], v161 offset:7168
	global_load_lds_dwordx4 v[148:149], off
	v_lshl_add_u64 v[148:149], s[4:5], 0, v[138:139]
	s_add_i32 m0, s54, 0xe000
	s_nop 0
	global_load_lds_dwordx4 v[148:149], off
	s_waitcnt vmcnt(8)
	s_waitcnt lgkmcnt(0)
	s_barrier
	s_setprio 1
	v_mfma_f32_16x16x32_bf16 v[126:129], v[140:143], v[186:189], v[126:129]
	v_mfma_f32_16x16x32_bf16 v[122:125], v[162:165], v[186:189], v[122:125]
	v_mfma_f32_16x16x32_bf16 v[110:113], v[140:143], v[194:197], v[110:113]
	v_mfma_f32_16x16x32_bf16 v[106:109], v[162:165], v[194:197], v[106:109]
	v_mfma_f32_16x16x32_bf16 v[94:97], v[140:143], v[202:205], v[94:97]
	v_mfma_f32_16x16x32_bf16 v[90:93], v[162:165], v[202:205], v[90:93]
	v_mfma_f32_16x16x32_bf16 v[78:81], v[140:143], v[210:213], v[78:81]
	v_mfma_f32_16x16x32_bf16 v[74:77], v[162:165], v[210:213], v[74:77]
	v_mfma_f32_16x16x32_bf16 v[126:129], v[144:147], v[190:193], v[126:129]
	v_mfma_f32_16x16x32_bf16 v[122:125], v[166:169], v[190:193], v[122:125]
	v_mfma_f32_16x16x32_bf16 v[110:113], v[144:147], v[198:201], v[110:113]
	v_mfma_f32_16x16x32_bf16 v[106:109], v[166:169], v[198:201], v[106:109]
	v_mfma_f32_16x16x32_bf16 v[94:97], v[144:147], v[206:209], v[94:97]
	v_mfma_f32_16x16x32_bf16 v[90:93], v[166:169], v[206:209], v[90:93]
	v_mfma_f32_16x16x32_bf16 v[78:81], v[144:147], v[214:217], v[78:81]
	v_mfma_f32_16x16x32_bf16 v[74:77], v[166:169], v[214:217], v[74:77]
	s_setprio 0
	s_setprio 1
	v_mfma_f32_16x16x32_bf16 v[118:121], v[170:173], v[186:189], v[118:121]
	v_mfma_f32_16x16x32_bf16 v[114:117], v[178:181], v[186:189], v[114:117]
	v_mfma_f32_16x16x32_bf16 v[102:105], v[170:173], v[194:197], v[102:105]
	v_mfma_f32_16x16x32_bf16 v[98:101], v[178:181], v[194:197], v[98:101]
	v_mfma_f32_16x16x32_bf16 v[86:89], v[170:173], v[202:205], v[86:89]
	v_mfma_f32_16x16x32_bf16 v[82:85], v[178:181], v[202:205], v[82:85]
	v_mfma_f32_16x16x32_bf16 v[70:73], v[170:173], v[210:213], v[70:73]
	v_mfma_f32_16x16x32_bf16 v[66:69], v[178:181], v[210:213], v[66:69]
	v_mfma_f32_16x16x32_bf16 v[118:121], v[174:177], v[190:193], v[118:121]
	v_mfma_f32_16x16x32_bf16 v[114:117], v[182:185], v[190:193], v[114:117]
	v_mfma_f32_16x16x32_bf16 v[102:105], v[174:177], v[198:201], v[102:105]
	v_mfma_f32_16x16x32_bf16 v[98:101], v[182:185], v[198:201], v[98:101]
	v_mfma_f32_16x16x32_bf16 v[86:89], v[174:177], v[206:209], v[86:89]
	v_mfma_f32_16x16x32_bf16 v[82:85], v[182:185], v[206:209], v[82:85]
	v_mfma_f32_16x16x32_bf16 v[70:73], v[174:177], v[214:217], v[70:73]
	v_mfma_f32_16x16x32_bf16 v[66:69], v[182:185], v[214:217], v[66:69]
	s_setprio 0
	s_barrier
	s_add_i32 s28, s31, s52
	v_lshl_add_u64 v[148:149], s[36:37], 0, v[0:1]
	s_mov_b32 m0, s28
	ds_read_b128 v[186:189], v161 offset:16384
	ds_read_b128 v[190:193], v161 offset:17408
	ds_read_b128 v[194:197], v161 offset:18432
	ds_read_b128 v[198:201], v161 offset:19456
	ds_read_b128 v[202:205], v161 offset:20480
	ds_read_b128 v[206:209], v161 offset:21504
	ds_read_b128 v[210:213], v161 offset:22528
	ds_read_b128 v[214:217], v161 offset:23552
	global_load_lds_dwordx4 v[148:149], off
	s_add_i32 m0, s28, 0x2000
	s_add_u32 s28, s36, 0x80000
	v_lshl_add_u64 v[152:153], s[36:37], 0, v[130:131]
	s_addc_u32 s29, s37, 0
	s_add_i32 s31, s35, s52
	global_load_lds_dwordx4 v[152:153], off
	v_lshl_add_u64 v[156:157], s[28:29], 0, v[0:1]
	s_mov_b32 m0, s31
	v_lshl_add_u64 v[218:219], s[40:41], 0, v[132:133]
	global_load_lds_dwordx4 v[156:157], off
	v_lshl_add_u64 v[156:157], s[28:29], 0, v[130:131]
	s_add_i32 m0, s31, 0x2000
	s_nop 0
	global_load_lds_dwordx4 v[156:157], off
	v_lshl_add_u64 v[156:157], s[40:41], 0, v[134:135]
	s_mov_b32 m0, s54
	s_nop 0
	global_load_lds_dwordx4 v[156:157], off
	s_mov_b32 m0, s55
	s_nop 0
	global_load_lds_dwordx4 v[218:219], off
	s_waitcnt vmcnt(8)
	s_waitcnt lgkmcnt(0)
	s_barrier
; #define PG8_STAGE(bufoff, gbase, voff) do { _Pragma("unroll") for (int _i = 0; _i < 2; ++_i) \
;         __builtin_amdgcn_global_load_lds((const unsigned*)((const char*)(gbase) + (voff)[_i]), (LAS unsigned*)(lds + (bufoff) + ldsw + _i * 8192), 16, 0, 0); } while (0)
; #define PG8_LDA(dst, b, h) do { _Pragma("unroll") for (int m = 0; m < 4; ++m) _Pragma("unroll") for (int k = 0; k < 2; ++k) dst[m][k] = *(const LAS bf16x8*)(lds + PG8_SA(b, h) + aoff + m * 2048 + k * 1024); } while (0)
; #define PG8_LDB(dst, b, h) do { _Pragma("unroll") for (int n = 0; n < 2; ++n) _Pragma("unroll") for (int k = 0; k < 2; ++k) dst[n][k] = *(const LAS bf16x8*)(lds + PG8_SB(b, h) + boff + n * 2048 + k * 1024); } while (0)
; #define PG8_MMA(ai, bj, At, Bt) do { __builtin_amdgcn_s_setprio(1); _Pragma("unroll") for (int m = 0; m < 4; ++m) _Pragma("unroll") for (int n = 0; n < 2; ++n) _Pragma("unroll") for (int k = 0; k < 2; ++k) \
;         acc[ai][bj][m][n] = __builtin_amdgcn_mfma_f32_16x16x32_bf16(Bt[n][k], At[m][k], acc[ai][bj][m][n], 0, 0, 0); __builtin_amdgcn_s_setprio(0); } while (0)
; #define PG8_WAIT_V(n) asm volatile("s_waitcnt vmcnt(" #n ")" ::: "memory")
; #define PG8_WAIT_L(n) asm volatile("s_waitcnt lgkmcnt(" #n ")" ::: "memory")
; #define PG8_BAR __builtin_amdgcn_s_barrier()
; #define PG8_SCHED __builtin_amdgcn_sched_barrier(0)
; template <class Epi, class Sched, bool ALIGN_EPI, bool LAST_FUSED = false, bool PERM = false, bool CARRY = false>
; __device__ __forceinline__ void gemm_phase(LAS unsigned char* lds, const int tid, const int K, const int lda, const int ldb, const Sched& S, const Epi& E) {
;     ...
;             PG8_WAIT_V(8); PG8_WAIT_L(0); PG8_BAR; PG8_MMA(1, 0, At, B0); PG8_MMA(1, 1, At, B1); PG8_BAR; PG8_SCHED;
;             PG8_LDB(B0, 1, 0); PG8_LDB(B1, 1, 1); PG8_SCHED; PG8_LDA(At, 1, 0); PG8_STAGE(PG8_SA(0, 1), a2 + hstepA, voffA);
;             PG8_WAIT_V(8); PG8_WAIT_L(0); PG8_BAR; PG8_MMA(0, 0, At, B0); PG8_MMA(0, 1, At, B1); PG8_BAR; PG8_SCHED;
	s_setprio 1
	v_mfma_f32_16x16x32_bf16 v[62:65], v[140:143], v[186:189], v[62:65]
	v_mfma_f32_16x16x32_bf16 v[58:61], v[162:165], v[186:189], v[58:61]
	v_mfma_f32_16x16x32_bf16 v[46:49], v[140:143], v[194:197], v[46:49]
	v_mfma_f32_16x16x32_bf16 v[42:45], v[162:165], v[194:197], v[42:45]
	v_mfma_f32_16x16x32_bf16 v[30:33], v[140:143], v[202:205], v[30:33]
	v_mfma_f32_16x16x32_bf16 v[26:29], v[162:165], v[202:205], v[26:29]
	v_mfma_f32_16x16x32_bf16 v[14:17], v[140:143], v[210:213], v[14:17]
	v_mfma_f32_16x16x32_bf16 v[10:13], v[162:165], v[210:213], v[10:13]
	v_mfma_f32_16x16x32_bf16 v[62:65], v[144:147], v[190:193], v[62:65]
	v_mfma_f32_16x16x32_bf16 v[58:61], v[166:169], v[190:193], v[58:61]
	v_mfma_f32_16x16x32_bf16 v[46:49], v[144:147], v[198:201], v[46:49]
	v_mfma_f32_16x16x32_bf16 v[42:45], v[166:169], v[198:201], v[42:45]
	v_mfma_f32_16x16x32_bf16 v[30:33], v[144:147], v[206:209], v[30:33]
	v_mfma_f32_16x16x32_bf16 v[26:29], v[166:169], v[206:209], v[26:29]
	v_mfma_f32_16x16x32_bf16 v[14:17], v[144:147], v[214:217], v[14:17]
	v_mfma_f32_16x16x32_bf16 v[10:13], v[166:169], v[214:217], v[10:13]
	s_setprio 0
	s_setprio 1
	v_mfma_f32_16x16x32_bf16 v[54:57], v[170:173], v[186:189], v[54:57]
	v_mfma_f32_16x16x32_bf16 v[50:53], v[178:181], v[186:189], v[50:53]
	v_mfma_f32_16x16x32_bf16 v[38:41], v[170:173], v[194:197], v[38:41]
	v_mfma_f32_16x16x32_bf16 v[34:37], v[178:181], v[194:197], v[34:37]
	v_mfma_f32_16x16x32_bf16 v[22:25], v[170:173], v[202:205], v[22:25]
	v_mfma_f32_16x16x32_bf16 v[18:21], v[178:181], v[202:205], v[18:21]
	v_mfma_f32_16x16x32_bf16 v[6:9], v[170:173], v[210:213], v[6:9]
	v_mfma_f32_16x16x32_bf16 v[2:5], v[178:181], v[210:213], v[2:5]
	v_mfma_f32_16x16x32_bf16 v[54:57], v[174:177], v[190:193], v[54:57]
	v_mfma_f32_16x16x32_bf16 v[50:53], v[182:185], v[190:193], v[50:53]
	v_mfma_f32_16x16x32_bf16 v[38:41], v[174:177], v[198:201], v[38:41]
	v_mfma_f32_16x16x32_bf16 v[34:37], v[182:185], v[198:201], v[34:37]
	v_mfma_f32_16x16x32_bf16 v[22:25], v[174:177], v[206:209], v[22:25]
	v_mfma_f32_16x16x32_bf16 v[18:21], v[182:185], v[206:209], v[18:21]
	v_mfma_f32_16x16x32_bf16 v[6:9], v[174:177], v[214:217], v[6:9]
	v_mfma_f32_16x16x32_bf16 v[2:5], v[182:185], v[214:217], v[2:5]
	s_setprio 0
	s_barrier
	s_add_i32 s31, 0, 0x18000
	v_add_u32_e32 v150, s31, v160
	s_add_i32 s35, 0, 0x1c000
	ds_read_b128 v[140:143], v150
	ds_read_b128 v[144:147], v150 offset:1024
	ds_read_b128 v[162:165], v150 offset:2048
	ds_read_b128 v[166:169], v150 offset:3072
	v_add_u32_e32 v150, s35, v160
	ds_read_b128 v[170:173], v150
	ds_read_b128 v[174:177], v150 offset:1024
	ds_read_b128 v[178:181], v150 offset:2048
	ds_read_b128 v[182:185], v150 offset:3072
	s_add_u32 s28, s40, 0x80000
	s_addc_u32 s29, s41, 0
	s_mov_b32 m0, s56
	v_lshl_add_u64 v[220:221], s[28:29], 0, v[134:135]
	ds_read_b128 v[186:189], v161 offset:32768
	ds_read_b128 v[190:193], v161 offset:33792
	ds_read_b128 v[194:197], v161 offset:34816
	ds_read_b128 v[198:201], v161 offset:35840
	ds_read_b128 v[202:205], v161 offset:36864
	ds_read_b128 v[206:209], v161 offset:37888
	ds_read_b128 v[210:213], v161 offset:38912
	ds_read_b128 v[214:217], v161 offset:39936
	global_load_lds_dwordx4 v[220:221], off
	v_lshl_add_u64 v[220:221], s[28:29], 0, v[132:133]
	s_mov_b32 m0, s57
	s_nop 0
	global_load_lds_dwordx4 v[220:221], off
	s_waitcnt vmcnt(8)
	s_waitcnt lgkmcnt(0)
	s_barrier
	s_setprio 1
	v_mfma_f32_16x16x32_bf16 v[126:129], v[140:143], v[186:189], v[126:129]
	v_mfma_f32_16x16x32_bf16 v[122:125], v[162:165], v[186:189], v[122:125]
	v_mfma_f32_16x16x32_bf16 v[110:113], v[140:143], v[194:197], v[110:113]
	v_mfma_f32_16x16x32_bf16 v[106:109], v[162:165], v[194:197], v[106:109]
	v_mfma_f32_16x16x32_bf16 v[94:97], v[140:143], v[202:205], v[94:97]
	v_mfma_f32_16x16x32_bf16 v[90:93], v[162:165], v[202:205], v[90:93]
	v_mfma_f32_16x16x32_bf16 v[78:81], v[140:143], v[210:213], v[78:81]
	v_mfma_f32_16x16x32_bf16 v[74:77], v[162:165], v[210:213], v[74:77]
	v_mfma_f32_16x16x32_bf16 v[126:129], v[144:147], v[190:193], v[126:129]
	v_mfma_f32_16x16x32_bf16 v[122:125], v[166:169], v[190:193], v[122:125]
	v_mfma_f32_16x16x32_bf16 v[110:113], v[144:147], v[198:201], v[110:113]
	v_mfma_f32_16x16x32_bf16 v[106:109], v[166:169], v[198:201], v[106:109]
	v_mfma_f32_16x16x32_bf16 v[94:97], v[144:147], v[206:209], v[94:97]
	v_mfma_f32_16x16x32_bf16 v[90:93], v[166:169], v[206:209], v[90:93]
	v_mfma_f32_16x16x32_bf16 v[78:81], v[144:147], v[214:217], v[78:81]
	v_mfma_f32_16x16x32_bf16 v[74:77], v[166:169], v[214:217], v[74:77]
	s_setprio 0
	s_setprio 1
	v_mfma_f32_16x16x32_bf16 v[118:121], v[170:173], v[186:189], v[118:121]
	v_mfma_f32_16x16x32_bf16 v[114:117], v[178:181], v[186:189], v[114:117]
	v_mfma_f32_16x16x32_bf16 v[102:105], v[170:173], v[194:197], v[102:105]
	v_mfma_f32_16x16x32_bf16 v[98:101], v[178:181], v[194:197], v[98:101]
	v_mfma_f32_16x16x32_bf16 v[86:89], v[170:173], v[202:205], v[86:89]
	v_mfma_f32_16x16x32_bf16 v[82:85], v[178:181], v[202:205], v[82:85]
	v_mfma_f32_16x16x32_bf16 v[70:73], v[170:173], v[210:213], v[70:73]
	v_mfma_f32_16x16x32_bf16 v[66:69], v[178:181], v[210:213], v[66:69]
	v_mfma_f32_16x16x32_bf16 v[118:121], v[174:177], v[190:193], v[118:121]
	v_mfma_f32_16x16x32_bf16 v[114:117], v[182:185], v[190:193], v[114:117]
	v_mfma_f32_16x16x32_bf16 v[102:105], v[174:177], v[198:201], v[102:105]
	v_mfma_f32_16x16x32_bf16 v[98:101], v[182:185], v[198:201], v[98:101]
	v_mfma_f32_16x16x32_bf16 v[86:89], v[174:177], v[206:209], v[86:89]
	v_mfma_f32_16x16x32_bf16 v[82:85], v[182:185], v[206:209], v[82:85]
	v_mfma_f32_16x16x32_bf16 v[70:73], v[174:177], v[214:217], v[70:73]
	v_mfma_f32_16x16x32_bf16 v[66:69], v[182:185], v[214:217], v[66:69]
	s_setprio 0
	s_barrier
; #define PG8_STAGE(bufoff, gbase, voff) do { _Pragma("unroll") for (int _i = 0; _i < 2; ++_i) \
;         __builtin_amdgcn_global_load_lds((const unsigned*)((const char*)(gbase) + (voff)[_i]), (LAS unsigned*)(lds + (bufoff) + ldsw + _i * 8192), 16, 0, 0); } while (0)
; #define PG8_LDA(dst, b, h) do { _Pragma("unroll") for (int m = 0; m < 4; ++m) _Pragma("unroll") for (int k = 0; k < 2; ++k) dst[m][k] = *(const LAS bf16x8*)(lds + PG8_SA(b, h) + aoff + m * 2048 + k * 1024); } while (0)
; #define PG8_WAIT_V(n) asm volatile("s_waitcnt vmcnt(" #n ")" ::: "memory")
; #define PG8_WAIT_L(n) asm volatile("s_waitcnt lgkmcnt(" #n ")" ::: "memory")
; template <class Epi, class Sched, bool ALIGN_EPI, bool LAST_FUSED = false, bool PERM = false, bool CARRY = false>
; __device__ __forceinline__ void gemm_phase(LAS unsigned char* lds, const int tid, const int K, const int lda, const int ldb, const Sched& S, const Epi& E) {
;     ...
;         for (int t = 0; t < nt; t += 2) {
;             const bool last = (t == nt - 2);
;             const char* a1 = cA + (size_t)(t + 1) * kstep;
;             const char* a2 = last ? nA : cA + (size_t)(t + 2) * kstep; const char* b2 = last ? nB : cB + (size_t)(t + 2) * kstep;
;             const char* a3 = a2 + kstep; const char* b3 = b2 + kstep;
;             PG8_LDB(B0, 0, 0); PG8_LDB(B1, 0, 1); PG8_SCHED; PG8_LDA(At, 0, 0); PG8_STAGE(PG8_SA(1, 1), a1 + hstepA, voffA);
;             PG8_WAIT_V(8); PG8_WAIT_L(0); PG8_BAR; PG8_MMA(0, 0, At, B0); PG8_MMA(0, 1, At, B1); PG8_BAR; PG8_SCHED;
;             PG8_LDA(At, 0, 1); PG8_STAGE(PG8_SB(0, 0), b2, voffB); PG8_STAGE(PG8_SB(0, 1), b2 + hstepB, voffB); PG8_STAGE(PG8_SA(0, 0), a2, voffA);
;             PG8_WAIT_V(8); PG8_WAIT_L(0); PG8_BAR; PG8_MMA(1, 0, At, B0); PG8_MMA(1, 1, At, B1); PG8_BAR; PG8_SCHED;
;             PG8_LDB(B0, 1, 0); PG8_LDB(B1, 1, 1); PG8_SCHED; PG8_LDA(At, 1, 0); PG8_STAGE(PG8_SA(0, 1), a2 + hstepA, voffA);
;             PG8_WAIT_V(8); PG8_WAIT_L(0); PG8_BAR; PG8_MMA(0, 0, At, B0); PG8_MMA(0, 1, At, B1); PG8_BAR; PG8_SCHED;
;             PG8_LDA(At, 1, 1); PG8_STAGE(PG8_SB(1, 0), b3, voffB); PG8_STAGE(PG8_SB(1, 1), b3 + hstepB, voffB); PG8_STAGE(PG8_SA(1, 0), a3, voffA);
;             PG8_WAIT_V(8); PG8_WAIT_L(0); PG8_BAR; PG8_MMA(1, 0, At, B0); PG8_MMA(1, 1, At, B1); PG8_BAR; PG8_SCHED;
;         }
;         if constexpr (ALIGN_EPI) { if (wr == 0) PG8_BAR; }
	s_add_i32 s28, s31, s52
	v_lshl_add_u64 v[148:149], v[148:149], 0, s[68:69]
	s_mov_b32 m0, s28
	ds_read_b128 v[186:189], v161 offset:49152
	ds_read_b128 v[190:193], v161 offset:50176
	ds_read_b128 v[194:197], v161 offset:51200
	ds_read_b128 v[198:201], v161 offset:52224
	ds_read_b128 v[202:205], v161 offset:53248
	ds_read_b128 v[206:209], v161 offset:54272
	ds_read_b128 v[210:213], v161 offset:55296
	ds_read_b128 v[214:217], v161 offset:56320
	global_load_lds_dwordx4 v[148:149], off
	s_add_i32 m0, s28, 0x2000
	s_add_u32 s28, s36, 0x80080
	v_lshl_add_u64 v[148:149], v[152:153], 0, s[68:69]
	s_addc_u32 s29, s37, 0
	s_add_i32 s31, s35, s52
	global_load_lds_dwordx4 v[148:149], off
	v_lshl_add_u64 v[148:149], s[28:29], 0, v[0:1]
	s_mov_b32 m0, s31
	s_nop 0
	global_load_lds_dwordx4 v[148:149], off
	v_lshl_add_u64 v[148:149], s[28:29], 0, v[130:131]
	s_add_i32 m0, s31, 0x2000
	s_nop 0
	global_load_lds_dwordx4 v[148:149], off
	v_lshl_add_u64 v[148:149], v[156:157], 0, s[68:69]
	s_mov_b32 m0, s59
	s_nop 0
	global_load_lds_dwordx4 v[148:149], off
	v_lshl_add_u64 v[148:149], v[218:219], 0, s[68:69]
	s_mov_b32 m0, s60
	s_nop 0
	global_load_lds_dwordx4 v[148:149], off
	s_waitcnt vmcnt(8)
	s_waitcnt lgkmcnt(0)
	s_barrier
	s_setprio 1
	v_mfma_f32_16x16x32_bf16 v[62:65], v[140:143], v[186:189], v[62:65]
	v_mfma_f32_16x16x32_bf16 v[58:61], v[162:165], v[186:189], v[58:61]
	v_mfma_f32_16x16x32_bf16 v[46:49], v[140:143], v[194:197], v[46:49]
	v_mfma_f32_16x16x32_bf16 v[42:45], v[162:165], v[194:197], v[42:45]
	v_mfma_f32_16x16x32_bf16 v[30:33], v[140:143], v[202:205], v[30:33]
	v_mfma_f32_16x16x32_bf16 v[26:29], v[162:165], v[202:205], v[26:29]
	v_mfma_f32_16x16x32_bf16 v[14:17], v[140:143], v[210:213], v[14:17]
	v_mfma_f32_16x16x32_bf16 v[10:13], v[162:165], v[210:213], v[10:13]
	v_mfma_f32_16x16x32_bf16 v[62:65], v[144:147], v[190:193], v[62:65]
	v_mfma_f32_16x16x32_bf16 v[58:61], v[166:169], v[190:193], v[58:61]
	v_mfma_f32_16x16x32_bf16 v[46:49], v[144:147], v[198:201], v[46:49]
	v_mfma_f32_16x16x32_bf16 v[42:45], v[166:169], v[198:201], v[42:45]
	v_mfma_f32_16x16x32_bf16 v[30:33], v[144:147], v[206:209], v[30:33]
	v_mfma_f32_16x16x32_bf16 v[26:29], v[166:169], v[206:209], v[26:29]
	v_mfma_f32_16x16x32_bf16 v[14:17], v[144:147], v[214:217], v[14:17]
	v_mfma_f32_16x16x32_bf16 v[10:13], v[166:169], v[214:217], v[10:13]
	s_setprio 0
	s_setprio 1
	v_mfma_f32_16x16x32_bf16 v[54:57], v[170:173], v[186:189], v[54:57]
	v_mfma_f32_16x16x32_bf16 v[50:53], v[178:181], v[186:189], v[50:53]
	v_mfma_f32_16x16x32_bf16 v[38:41], v[170:173], v[194:197], v[38:41]
	v_mfma_f32_16x16x32_bf16 v[34:37], v[178:181], v[194:197], v[34:37]
	v_mfma_f32_16x16x32_bf16 v[22:25], v[170:173], v[202:205], v[22:25]
	v_mfma_f32_16x16x32_bf16 v[18:21], v[178:181], v[202:205], v[18:21]
	v_mfma_f32_16x16x32_bf16 v[6:9], v[170:173], v[210:213], v[6:9]
	v_mfma_f32_16x16x32_bf16 v[2:5], v[178:181], v[210:213], v[2:5]
	v_mfma_f32_16x16x32_bf16 v[54:57], v[174:177], v[190:193], v[54:57]
	v_mfma_f32_16x16x32_bf16 v[50:53], v[182:185], v[190:193], v[50:53]
	v_mfma_f32_16x16x32_bf16 v[38:41], v[174:177], v[198:201], v[38:41]
	v_mfma_f32_16x16x32_bf16 v[34:37], v[182:185], v[198:201], v[34:37]
	v_mfma_f32_16x16x32_bf16 v[22:25], v[174:177], v[206:209], v[22:25]
	v_mfma_f32_16x16x32_bf16 v[18:21], v[182:185], v[206:209], v[18:21]
	v_mfma_f32_16x16x32_bf16 v[6:9], v[174:177], v[214:217], v[6:9]
	v_mfma_f32_16x16x32_bf16 v[2:5], v[182:185], v[214:217], v[2:5]
	s_setprio 0
	s_barrier
	s_add_i32 s24, s24, 2
	s_add_u32 s4, s4, 0x100
	s_addc_u32 s5, s5, 0
	s_add_u32 s22, s22, 0x100
	s_addc_u32 s23, s23, 0
	s_cmp_gt_u32 s24, 29
	s_cbranch_scc0 .LBB0_512
	s_and_b64 vcc, exec, s[78:79]
	s_cbranch_vccz .LBB0_515
	s_barrier

; #define PG8_STAGE(bufoff, gbase, voff) do { _Pragma("unroll") for (int _i = 0; _i < 2; ++_i) \
;         __builtin_amdgcn_global_load_lds((const unsigned*)((const char*)(gbase) + (voff)[_i]), (LAS unsigned*)(lds + (bufoff) + ldsw + _i * 8192), 16, 0, 0); } while (0)
; #define PG8_LDA(dst, b, h) do { _Pragma("unroll") for (int m = 0; m < 4; ++m) _Pragma("unroll") for (int k = 0; k < 2; ++k) dst[m][k] = *(const LAS bf16x8*)(lds + PG8_SA(b, h) + aoff + m * 2048 + k * 1024); } while (0)
; #define PG8_LDB(dst, b, h) do { _Pragma("unroll") for (int n = 0; n < 2; ++n) _Pragma("unroll") for (int k = 0; k < 2; ++k) dst[n][k] = *(const LAS bf16x8*)(lds + PG8_SB(b, h) + boff + n * 2048 + k * 1024); } while (0)
; #define PG8_MMA(ai, bj, At, Bt) do { __builtin_amdgcn_s_setprio(1); _Pragma("unroll") for (int m = 0; m < 4; ++m) _Pragma("unroll") for (int n = 0; n < 2; ++n) _Pragma("unroll") for (int k = 0; k < 2; ++k) \
;         acc[ai][bj][m][n] = __builtin_amdgcn_mfma_f32_16x16x32_bf16(Bt[n][k], At[m][k], acc[ai][bj][m][n], 0, 0, 0); __builtin_amdgcn_s_setprio(0); } while (0)
; #define PG8_WAIT_V(n) asm volatile("s_waitcnt vmcnt(" #n ")" ::: "memory")
; #define PG8_WAIT_L(n) asm volatile("s_waitcnt lgkmcnt(" #n ")" ::: "memory")
; template <class Epi, class Sched, bool ALIGN_EPI, bool LAST_FUSED = false, bool PERM = false, bool CARRY = false>
; __device__ __forceinline__ void gemm_phase(LAS unsigned char* lds, const int tid, const int K, const int lda, const int ldb, const Sched& S, const Epi& E) {
;     ...
;         for (int t = 0; t < nt; t += 2) {
;             const bool last = (t == nt - 2);
;             const char* a1 = cA + (size_t)(t + 1) * kstep;
;             const char* a2 = last ? nA : cA + (size_t)(t + 2) * kstep; const char* b2 = last ? nB : cB + (size_t)(t + 2) * kstep;
;             const char* a3 = a2 + kstep; const char* b3 = b2 + kstep;
;             PG8_LDB(B0, 0, 0); PG8_LDB(B1, 0, 1); PG8_SCHED; PG8_LDA(At, 0, 0); PG8_STAGE(PG8_SA(1, 1), a1 + hstepA, voffA);
;             PG8_WAIT_V(8); PG8_WAIT_L(0); PG8_BAR; PG8_MMA(0, 0, At, B0); PG8_MMA(0, 1, At, B1); PG8_BAR; PG8_SCHED;
;             PG8_LDA(At, 0, 1); PG8_STAGE(PG8_SB(0, 0), b2, voffB); PG8_STAGE(PG8_SB(0, 1), b2 + hstepB, voffB); PG8_STAGE(PG8_SA(0, 0), a2, voffA);
;             PG8_WAIT_V(8); PG8_WAIT_L(0); PG8_BAR; PG8_MMA(1, 0, At, B0); PG8_MMA(1, 1, At, B1); PG8_BAR; PG8_SCHED;
.LBB0_601:
	s_add_u32 s23, s30, s15
	s_addc_u32 s27, s31, 0
	s_add_u32 s35, s23, 0x100
	s_addc_u32 s42, s27, 0
	s_and_b64 s[28:29], s[40:41], exec
	s_cselect_b32 s47, s17, s42
	s_cselect_b32 s46, s16, s35
	s_add_u32 s15, s36, s15
	s_addc_u32 s28, s37, 0
	s_add_u32 s15, s15, 0x100
	s_addc_u32 s35, s28, 0
	s_add_i32 s75, 0, 0x10000
	s_and_b64 s[28:29], s[40:41], exec
	s_cselect_b32 s49, s19, s35
	s_cselect_b32 s48, s18, s15
	s_add_i32 s41, 0, 0x14000
	s_add_u32 s52, s23, 0x80080
	s_addc_u32 s53, s27, 0
	s_add_i32 s45, s75, s59
	s_add_i32 m0, s60, 0xc000
	s_add_i32 s77, s60, 0xe000
	s_add_i32 s29, s45, 0x2000
	s_add_u32 s50, s48, 0x80000
	v_add_u32_e32 v154, s75, v144
	v_add_u32_e32 v170, s41, v144
	s_addc_u32 s51, s49, 0
	s_add_i32 s44, s41, s59
	ds_read_b128 v[136:139], v154
	ds_read_b128 v[146:149], v154 offset:1024
	ds_read_b128 v[150:153], v154 offset:2048
	ds_read_b128 v[154:157], v154 offset:3072
	ds_read_b128 v[158:161], v170
	ds_read_b128 v[162:165], v170 offset:1024
	ds_read_b128 v[166:169], v170 offset:2048
	ds_read_b128 v[170:173], v170 offset:3072
	s_add_i32 s35, s44, 0x2000
	s_add_i32 s28, 0, 0x18000
	s_add_i32 s27, 0, 0x1c000
	s_add_u32 s42, s46, 0x80000
	s_addc_u32 s43, s47, 0
	s_add_i32 s23, s28, s59
	s_add_i32 s15, s23, 0x2000
	s_add_u32 s40, s48, 0x80080
	s_addc_u32 s41, s49, 0
	s_add_i32 s76, s27, s59
	s_add_i32 s75, s76, 0x2000
	v_lshl_add_u64 v[206:207], s[52:53], 0, v[134:135]
	ds_read_b128 v[174:177], v145
	ds_read_b128 v[178:181], v145 offset:1024
	ds_read_b128 v[182:185], v145 offset:2048
	ds_read_b128 v[186:189], v145 offset:3072
	ds_read_b128 v[190:193], v145 offset:4096
	ds_read_b128 v[194:197], v145 offset:5120
	ds_read_b128 v[198:201], v145 offset:6144
	ds_read_b128 v[202:205], v145 offset:7168
	global_load_lds_dwordx4 v[206:207], off
	v_lshl_add_u64 v[206:207], s[52:53], 0, v[132:133]
	s_mov_b32 m0, s77
	s_nop 0
	global_load_lds_dwordx4 v[206:207], off
	s_waitcnt vmcnt(8)
	s_waitcnt lgkmcnt(0)
	s_barrier
	s_setprio 1
	v_mfma_f32_16x16x32_bf16 v[126:129], v[136:139], v[174:177], v[126:129]
	v_mfma_f32_16x16x32_bf16 v[122:125], v[150:153], v[174:177], v[122:125]
	v_mfma_f32_16x16x32_bf16 v[110:113], v[136:139], v[182:185], v[110:113]
	v_mfma_f32_16x16x32_bf16 v[106:109], v[150:153], v[182:185], v[106:109]
	v_mfma_f32_16x16x32_bf16 v[94:97], v[136:139], v[190:193], v[94:97]
	v_mfma_f32_16x16x32_bf16 v[90:93], v[150:153], v[190:193], v[90:93]
	v_mfma_f32_16x16x32_bf16 v[78:81], v[136:139], v[198:201], v[78:81]
	v_mfma_f32_16x16x32_bf16 v[74:77], v[150:153], v[198:201], v[74:77]
	v_mfma_f32_16x16x32_bf16 v[126:129], v[146:149], v[178:181], v[126:129]
	v_mfma_f32_16x16x32_bf16 v[122:125], v[154:157], v[178:181], v[122:125]
	v_mfma_f32_16x16x32_bf16 v[110:113], v[146:149], v[186:189], v[110:113]
	v_mfma_f32_16x16x32_bf16 v[106:109], v[154:157], v[186:189], v[106:109]
	v_mfma_f32_16x16x32_bf16 v[94:97], v[146:149], v[194:197], v[94:97]
	v_mfma_f32_16x16x32_bf16 v[90:93], v[154:157], v[194:197], v[90:93]
	v_mfma_f32_16x16x32_bf16 v[78:81], v[146:149], v[202:205], v[78:81]
	v_mfma_f32_16x16x32_bf16 v[74:77], v[154:157], v[202:205], v[74:77]
	s_setprio 0
	s_setprio 1
	v_mfma_f32_16x16x32_bf16 v[118:121], v[158:161], v[174:177], v[118:121]
	v_mfma_f32_16x16x32_bf16 v[114:117], v[166:169], v[174:177], v[114:117]
	v_mfma_f32_16x16x32_bf16 v[102:105], v[158:161], v[182:185], v[102:105]
	v_mfma_f32_16x16x32_bf16 v[98:101], v[166:169], v[182:185], v[98:101]
	v_mfma_f32_16x16x32_bf16 v[86:89], v[158:161], v[190:193], v[86:89]
	v_mfma_f32_16x16x32_bf16 v[82:85], v[166:169], v[190:193], v[82:85]
	v_mfma_f32_16x16x32_bf16 v[70:73], v[158:161], v[198:201], v[70:73]
	v_mfma_f32_16x16x32_bf16 v[66:69], v[166:169], v[198:201], v[66:69]
	v_mfma_f32_16x16x32_bf16 v[118:121], v[162:165], v[178:181], v[118:121]
	v_mfma_f32_16x16x32_bf16 v[114:117], v[170:173], v[178:181], v[114:117]
	v_mfma_f32_16x16x32_bf16 v[102:105], v[162:165], v[186:189], v[102:105]
	v_mfma_f32_16x16x32_bf16 v[98:101], v[170:173], v[186:189], v[98:101]
	v_mfma_f32_16x16x32_bf16 v[86:89], v[162:165], v[194:197], v[86:89]
	v_mfma_f32_16x16x32_bf16 v[82:85], v[170:173], v[194:197], v[82:85]
	v_mfma_f32_16x16x32_bf16 v[70:73], v[162:165], v[202:205], v[70:73]
	v_mfma_f32_16x16x32_bf16 v[66:69], v[170:173], v[202:205], v[66:69]
	s_setprio 0
	s_barrier
	s_mov_b32 m0, s45
	v_lshl_add_u64 v[206:207], s[48:49], 0, v[0:1]
	ds_read_b128 v[174:177], v145 offset:16384
	ds_read_b128 v[178:181], v145 offset:17408
	ds_read_b128 v[182:185], v145 offset:18432
	ds_read_b128 v[186:189], v145 offset:19456
	ds_read_b128 v[190:193], v145 offset:20480
	ds_read_b128 v[194:197], v145 offset:21504
	ds_read_b128 v[198:201], v145 offset:22528
	ds_read_b128 v[202:205], v145 offset:23552
	global_load_lds_dwordx4 v[206:207], off
	v_lshl_add_u64 v[208:209], s[48:49], 0, v[130:131]
	s_mov_b32 m0, s29
	v_lshl_add_u64 v[210:211], s[50:51], 0, v[0:1]
	global_load_lds_dwordx4 v[208:209], off
	s_mov_b32 m0, s44
	v_lshl_add_u64 v[212:213], s[46:47], 0, v[132:133]
	global_load_lds_dwordx4 v[210:211], off
	v_lshl_add_u64 v[210:211], s[50:51], 0, v[130:131]
	s_mov_b32 m0, s35
	s_nop 0
	global_load_lds_dwordx4 v[210:211], off
	v_lshl_add_u64 v[210:211], s[46:47], 0, v[134:135]
	s_mov_b32 m0, s60
	s_nop 0
	global_load_lds_dwordx4 v[210:211], off
	s_mov_b32 m0, s61
	s_nop 0
	global_load_lds_dwordx4 v[212:213], off
	s_waitcnt vmcnt(8)
	s_waitcnt lgkmcnt(0)
	s_barrier
; #define PG8_STAGE(bufoff, gbase, voff) do { _Pragma("unroll") for (int _i = 0; _i < 2; ++_i) \
;         __builtin_amdgcn_global_load_lds((const unsigned*)((const char*)(gbase) + (voff)[_i]), (LAS unsigned*)(lds + (bufoff) + ldsw + _i * 8192), 16, 0, 0); } while (0)
; #define PG8_LDA(dst, b, h) do { _Pragma("unroll") for (int m = 0; m < 4; ++m) _Pragma("unroll") for (int k = 0; k < 2; ++k) dst[m][k] = *(const LAS bf16x8*)(lds + PG8_SA(b, h) + aoff + m * 2048 + k * 1024); } while (0)
; #define PG8_LDB(dst, b, h) do { _Pragma("unroll") for (int n = 0; n < 2; ++n) _Pragma("unroll") for (int k = 0; k < 2; ++k) dst[n][k] = *(const LAS bf16x8*)(lds + PG8_SB(b, h) + boff + n * 2048 + k * 1024); } while (0)
; #define PG8_MMA(ai, bj, At, Bt) do { __builtin_amdgcn_s_setprio(1); _Pragma("unroll") for (int m = 0; m < 4; ++m) _Pragma("unroll") for (int n = 0; n < 2; ++n) _Pragma("unroll") for (int k = 0; k < 2; ++k) \
;         acc[ai][bj][m][n] = __builtin_amdgcn_mfma_f32_16x16x32_bf16(Bt[n][k], At[m][k], acc[ai][bj][m][n], 0, 0, 0); __builtin_amdgcn_s_setprio(0); } while (0)
; #define PG8_WAIT_V(n) asm volatile("s_waitcnt vmcnt(" #n ")" ::: "memory")
; #define PG8_WAIT_L(n) asm volatile("s_waitcnt lgkmcnt(" #n ")" ::: "memory")
; #define PG8_BAR __builtin_amdgcn_s_barrier()
; #define PG8_SCHED __builtin_amdgcn_sched_barrier(0)
; template <class Epi, class Sched, bool ALIGN_EPI, bool LAST_FUSED = false, bool PERM = false, bool CARRY = false>
; __device__ __forceinline__ void gemm_phase(LAS unsigned char* lds, const int tid, const int K, const int lda, const int ldb, const Sched& S, const Epi& E) {
;     ...
;             PG8_WAIT_V(8); PG8_WAIT_L(0); PG8_BAR; PG8_MMA(1, 0, At, B0); PG8_MMA(1, 1, At, B1); PG8_BAR; PG8_SCHED;
;             PG8_LDB(B0, 1, 0); PG8_LDB(B1, 1, 1); PG8_SCHED; PG8_LDA(At, 1, 0); PG8_STAGE(PG8_SA(0, 1), a2 + hstepA, voffA);
;             PG8_WAIT_V(8); PG8_WAIT_L(0); PG8_BAR; PG8_MMA(0, 0, At, B0); PG8_MMA(0, 1, At, B1); PG8_BAR; PG8_SCHED;
	s_setprio 1
	v_mfma_f32_16x16x32_bf16 v[62:65], v[136:139], v[174:177], v[62:65]
	v_mfma_f32_16x16x32_bf16 v[58:61], v[150:153], v[174:177], v[58:61]
	v_mfma_f32_16x16x32_bf16 v[46:49], v[136:139], v[182:185], v[46:49]
	v_mfma_f32_16x16x32_bf16 v[42:45], v[150:153], v[182:185], v[42:45]
	v_mfma_f32_16x16x32_bf16 v[30:33], v[136:139], v[190:193], v[30:33]
	v_mfma_f32_16x16x32_bf16 v[26:29], v[150:153], v[190:193], v[26:29]
	v_mfma_f32_16x16x32_bf16 v[14:17], v[136:139], v[198:201], v[14:17]
	v_mfma_f32_16x16x32_bf16 v[10:13], v[150:153], v[198:201], v[10:13]
	v_mfma_f32_16x16x32_bf16 v[62:65], v[146:149], v[178:181], v[62:65]
	v_mfma_f32_16x16x32_bf16 v[58:61], v[154:157], v[178:181], v[58:61]
	v_mfma_f32_16x16x32_bf16 v[46:49], v[146:149], v[186:189], v[46:49]
	v_mfma_f32_16x16x32_bf16 v[42:45], v[154:157], v[186:189], v[42:45]
	v_mfma_f32_16x16x32_bf16 v[30:33], v[146:149], v[194:197], v[30:33]
	v_mfma_f32_16x16x32_bf16 v[26:29], v[154:157], v[194:197], v[26:29]
	v_mfma_f32_16x16x32_bf16 v[14:17], v[146:149], v[202:205], v[14:17]
	v_mfma_f32_16x16x32_bf16 v[10:13], v[154:157], v[202:205], v[10:13]
	s_setprio 0
	s_setprio 1
	v_mfma_f32_16x16x32_bf16 v[54:57], v[158:161], v[174:177], v[54:57]
	v_mfma_f32_16x16x32_bf16 v[50:53], v[166:169], v[174:177], v[50:53]
	v_mfma_f32_16x16x32_bf16 v[38:41], v[158:161], v[182:185], v[38:41]
	v_mfma_f32_16x16x32_bf16 v[34:37], v[166:169], v[182:185], v[34:37]
	v_mfma_f32_16x16x32_bf16 v[22:25], v[158:161], v[190:193], v[22:25]
	v_mfma_f32_16x16x32_bf16 v[18:21], v[166:169], v[190:193], v[18:21]
	v_mfma_f32_16x16x32_bf16 v[6:9], v[158:161], v[198:201], v[6:9]
	v_mfma_f32_16x16x32_bf16 v[2:5], v[166:169], v[198:201], v[2:5]
	v_mfma_f32_16x16x32_bf16 v[54:57], v[162:165], v[178:181], v[54:57]
	v_mfma_f32_16x16x32_bf16 v[50:53], v[170:173], v[178:181], v[50:53]
	v_mfma_f32_16x16x32_bf16 v[38:41], v[162:165], v[186:189], v[38:41]
	v_mfma_f32_16x16x32_bf16 v[34:37], v[170:173], v[186:189], v[34:37]
	v_mfma_f32_16x16x32_bf16 v[22:25], v[162:165], v[194:197], v[22:25]
	v_mfma_f32_16x16x32_bf16 v[18:21], v[170:173], v[194:197], v[18:21]
	v_mfma_f32_16x16x32_bf16 v[6:9], v[162:165], v[202:205], v[6:9]
	v_mfma_f32_16x16x32_bf16 v[2:5], v[170:173], v[202:205], v[2:5]
	s_setprio 0
	s_barrier
	v_add_u32_e32 v154, s28, v144
	v_add_u32_e32 v170, s27, v144
	ds_read_b128 v[136:139], v154
	ds_read_b128 v[146:149], v154 offset:1024
	ds_read_b128 v[150:153], v154 offset:2048
	ds_read_b128 v[154:157], v154 offset:3072
	ds_read_b128 v[158:161], v170
	ds_read_b128 v[162:165], v170 offset:1024
	ds_read_b128 v[166:169], v170 offset:2048
	ds_read_b128 v[170:173], v170 offset:3072
	s_mov_b32 m0, s62
	v_lshl_add_u64 v[214:215], s[42:43], 0, v[134:135]
	ds_read_b128 v[174:177], v145 offset:32768
	ds_read_b128 v[178:181], v145 offset:33792
	ds_read_b128 v[182:185], v145 offset:34816
	ds_read_b128 v[186:189], v145 offset:35840
	ds_read_b128 v[190:193], v145 offset:36864
	ds_read_b128 v[194:197], v145 offset:37888
	ds_read_b128 v[198:201], v145 offset:38912
	ds_read_b128 v[202:205], v145 offset:39936
	global_load_lds_dwordx4 v[214:215], off
	v_lshl_add_u64 v[214:215], s[42:43], 0, v[132:133]
	s_mov_b32 m0, s63
	s_nop 0
	global_load_lds_dwordx4 v[214:215], off
	s_waitcnt vmcnt(8)
	s_waitcnt lgkmcnt(0)
	s_barrier
	s_setprio 1
	v_mfma_f32_16x16x32_bf16 v[126:129], v[136:139], v[174:177], v[126:129]
	v_mfma_f32_16x16x32_bf16 v[122:125], v[150:153], v[174:177], v[122:125]
	v_mfma_f32_16x16x32_bf16 v[110:113], v[136:139], v[182:185], v[110:113]
	v_mfma_f32_16x16x32_bf16 v[106:109], v[150:153], v[182:185], v[106:109]
	v_mfma_f32_16x16x32_bf16 v[94:97], v[136:139], v[190:193], v[94:97]
	v_mfma_f32_16x16x32_bf16 v[90:93], v[150:153], v[190:193], v[90:93]
	v_mfma_f32_16x16x32_bf16 v[78:81], v[136:139], v[198:201], v[78:81]
	v_mfma_f32_16x16x32_bf16 v[74:77], v[150:153], v[198:201], v[74:77]
	v_mfma_f32_16x16x32_bf16 v[126:129], v[146:149], v[178:181], v[126:129]
	v_mfma_f32_16x16x32_bf16 v[122:125], v[154:157], v[178:181], v[122:125]
	v_mfma_f32_16x16x32_bf16 v[110:113], v[146:149], v[186:189], v[110:113]
	v_mfma_f32_16x16x32_bf16 v[106:109], v[154:157], v[186:189], v[106:109]
	v_mfma_f32_16x16x32_bf16 v[94:97], v[146:149], v[194:197], v[94:97]
	v_mfma_f32_16x16x32_bf16 v[90:93], v[154:157], v[194:197], v[90:93]
	v_mfma_f32_16x16x32_bf16 v[78:81], v[146:149], v[202:205], v[78:81]
	v_mfma_f32_16x16x32_bf16 v[74:77], v[154:157], v[202:205], v[74:77]
	s_setprio 0
	s_setprio 1
	v_mfma_f32_16x16x32_bf16 v[118:121], v[158:161], v[174:177], v[118:121]
	v_mfma_f32_16x16x32_bf16 v[114:117], v[166:169], v[174:177], v[114:117]
	v_mfma_f32_16x16x32_bf16 v[102:105], v[158:161], v[182:185], v[102:105]
	v_mfma_f32_16x16x32_bf16 v[98:101], v[166:169], v[182:185], v[98:101]
	v_mfma_f32_16x16x32_bf16 v[86:89], v[158:161], v[190:193], v[86:89]
	v_mfma_f32_16x16x32_bf16 v[82:85], v[166:169], v[190:193], v[82:85]
	v_mfma_f32_16x16x32_bf16 v[70:73], v[158:161], v[198:201], v[70:73]
	v_mfma_f32_16x16x32_bf16 v[66:69], v[166:169], v[198:201], v[66:69]
	v_mfma_f32_16x16x32_bf16 v[118:121], v[162:165], v[178:181], v[118:121]
	v_mfma_f32_16x16x32_bf16 v[114:117], v[170:173], v[178:181], v[114:117]
	v_mfma_f32_16x16x32_bf16 v[102:105], v[162:165], v[186:189], v[102:105]
	v_mfma_f32_16x16x32_bf16 v[98:101], v[170:173], v[186:189], v[98:101]
	v_mfma_f32_16x16x32_bf16 v[86:89], v[162:165], v[194:197], v[86:89]
	v_mfma_f32_16x16x32_bf16 v[82:85], v[170:173], v[194:197], v[82:85]
	v_mfma_f32_16x16x32_bf16 v[70:73], v[162:165], v[202:205], v[70:73]
	v_mfma_f32_16x16x32_bf16 v[66:69], v[170:173], v[202:205], v[66:69]
	s_setprio 0
	s_barrier
; #define PG8_STAGE(bufoff, gbase, voff) do { _Pragma("unroll") for (int _i = 0; _i < 2; ++_i) \
;         __builtin_amdgcn_global_load_lds((const unsigned*)((const char*)(gbase) + (voff)[_i]), (LAS unsigned*)(lds + (bufoff) + ldsw + _i * 8192), 16, 0, 0); } while (0)
; #define PG8_LDA(dst, b, h) do { _Pragma("unroll") for (int m = 0; m < 4; ++m) _Pragma("unroll") for (int k = 0; k < 2; ++k) dst[m][k] = *(const LAS bf16x8*)(lds + PG8_SA(b, h) + aoff + m * 2048 + k * 1024); } while (0)
; #define PG8_WAIT_V(n) asm volatile("s_waitcnt vmcnt(" #n ")" ::: "memory")
; #define PG8_WAIT_L(n) asm volatile("s_waitcnt lgkmcnt(" #n ")" ::: "memory")
; template <class Epi, class Sched, bool ALIGN_EPI, bool LAST_FUSED = false, bool PERM = false, bool CARRY = false>
; __device__ __forceinline__ void gemm_phase(LAS unsigned char* lds, const int tid, const int K, const int lda, const int ldb, const Sched& S, const Epi& E) {
;     ...
;         for (int t = 0; t < nt; t += 2) {
;             const bool last = (t == nt - 2);
;             const char* a1 = cA + (size_t)(t + 1) * kstep;
;             const char* a2 = last ? nA : cA + (size_t)(t + 2) * kstep; const char* b2 = last ? nB : cB + (size_t)(t + 2) * kstep;
;             const char* a3 = a2 + kstep; const char* b3 = b2 + kstep;
;             PG8_LDB(B0, 0, 0); PG8_LDB(B1, 0, 1); PG8_SCHED; PG8_LDA(At, 0, 0); PG8_STAGE(PG8_SA(1, 1), a1 + hstepA, voffA);
;             PG8_WAIT_V(8); PG8_WAIT_L(0); PG8_BAR; PG8_MMA(0, 0, At, B0); PG8_MMA(0, 1, At, B1); PG8_BAR; PG8_SCHED;
;             PG8_LDA(At, 0, 1); PG8_STAGE(PG8_SB(0, 0), b2, voffB); PG8_STAGE(PG8_SB(0, 1), b2 + hstepB, voffB); PG8_STAGE(PG8_SA(0, 0), a2, voffA);
;             PG8_WAIT_V(8); PG8_WAIT_L(0); PG8_BAR; PG8_MMA(1, 0, At, B0); PG8_MMA(1, 1, At, B1); PG8_BAR; PG8_SCHED;
;             PG8_LDB(B0, 1, 0); PG8_LDB(B1, 1, 1); PG8_SCHED; PG8_LDA(At, 1, 0); PG8_STAGE(PG8_SA(0, 1), a2 + hstepA, voffA);
;             PG8_WAIT_V(8); PG8_WAIT_L(0); PG8_BAR; PG8_MMA(0, 0, At, B0); PG8_MMA(0, 1, At, B1); PG8_BAR; PG8_SCHED;
;             PG8_LDA(At, 1, 1); PG8_STAGE(PG8_SB(1, 0), b3, voffB); PG8_STAGE(PG8_SB(1, 1), b3 + hstepB, voffB); PG8_STAGE(PG8_SA(1, 0), a3, voffA);
;             PG8_WAIT_V(8); PG8_WAIT_L(0); PG8_BAR; PG8_MMA(1, 0, At, B0); PG8_MMA(1, 1, At, B1); PG8_BAR; PG8_SCHED;
;         }
;         if constexpr (ALIGN_EPI) { if (wr == 0) PG8_BAR; }
	s_mov_b32 m0, s23
	v_lshl_add_u64 v[206:207], v[206:207], 0, s[68:69]
	ds_read_b128 v[174:177], v145 offset:49152
	ds_read_b128 v[178:181], v145 offset:50176
	ds_read_b128 v[182:185], v145 offset:51200
	ds_read_b128 v[186:189], v145 offset:52224
	ds_read_b128 v[190:193], v145 offset:53248
	ds_read_b128 v[194:197], v145 offset:54272
	ds_read_b128 v[198:201], v145 offset:55296
	ds_read_b128 v[202:205], v145 offset:56320
	global_load_lds_dwordx4 v[206:207], off
	v_lshl_add_u64 v[206:207], v[208:209], 0, s[68:69]
	s_mov_b32 m0, s15
	s_nop 0
	global_load_lds_dwordx4 v[206:207], off
	v_lshl_add_u64 v[206:207], s[40:41], 0, v[0:1]
	s_mov_b32 m0, s76
	s_nop 0
	global_load_lds_dwordx4 v[206:207], off
	v_lshl_add_u64 v[206:207], s[40:41], 0, v[130:131]
	s_mov_b32 m0, s75
	s_nop 0
	global_load_lds_dwordx4 v[206:207], off
	v_lshl_add_u64 v[206:207], v[210:211], 0, s[68:69]
	s_mov_b32 m0, s66
	s_nop 0
	global_load_lds_dwordx4 v[206:207], off
	v_lshl_add_u64 v[206:207], v[212:213], 0, s[68:69]
	s_mov_b32 m0, s67
	s_nop 0
	global_load_lds_dwordx4 v[206:207], off
	s_waitcnt vmcnt(8)
	s_waitcnt lgkmcnt(0)
	s_barrier
	s_setprio 1
	v_mfma_f32_16x16x32_bf16 v[62:65], v[136:139], v[174:177], v[62:65]
	v_mfma_f32_16x16x32_bf16 v[58:61], v[150:153], v[174:177], v[58:61]
	v_mfma_f32_16x16x32_bf16 v[46:49], v[136:139], v[182:185], v[46:49]
	v_mfma_f32_16x16x32_bf16 v[42:45], v[150:153], v[182:185], v[42:45]
	v_mfma_f32_16x16x32_bf16 v[30:33], v[136:139], v[190:193], v[30:33]
	v_mfma_f32_16x16x32_bf16 v[26:29], v[150:153], v[190:193], v[26:29]
	v_mfma_f32_16x16x32_bf16 v[14:17], v[136:139], v[198:201], v[14:17]
	v_mfma_f32_16x16x32_bf16 v[10:13], v[150:153], v[198:201], v[10:13]
	v_mfma_f32_16x16x32_bf16 v[62:65], v[146:149], v[178:181], v[62:65]
	v_mfma_f32_16x16x32_bf16 v[58:61], v[154:157], v[178:181], v[58:61]
	v_mfma_f32_16x16x32_bf16 v[46:49], v[146:149], v[186:189], v[46:49]
	v_mfma_f32_16x16x32_bf16 v[42:45], v[154:157], v[186:189], v[42:45]
	v_mfma_f32_16x16x32_bf16 v[30:33], v[146:149], v[194:197], v[30:33]
	v_mfma_f32_16x16x32_bf16 v[26:29], v[154:157], v[194:197], v[26:29]
	v_mfma_f32_16x16x32_bf16 v[14:17], v[146:149], v[202:205], v[14:17]
	v_mfma_f32_16x16x32_bf16 v[10:13], v[154:157], v[202:205], v[10:13]
	s_setprio 0
	s_setprio 1
	v_mfma_f32_16x16x32_bf16 v[54:57], v[158:161], v[174:177], v[54:57]
	v_mfma_f32_16x16x32_bf16 v[50:53], v[166:169], v[174:177], v[50:53]
	v_mfma_f32_16x16x32_bf16 v[38:41], v[158:161], v[182:185], v[38:41]
	v_mfma_f32_16x16x32_bf16 v[34:37], v[166:169], v[182:185], v[34:37]
	v_mfma_f32_16x16x32_bf16 v[22:25], v[158:161], v[190:193], v[22:25]
	v_mfma_f32_16x16x32_bf16 v[18:21], v[166:169], v[190:193], v[18:21]
	v_mfma_f32_16x16x32_bf16 v[6:9], v[158:161], v[198:201], v[6:9]
	v_mfma_f32_16x16x32_bf16 v[2:5], v[166:169], v[198:201], v[2:5]
	v_mfma_f32_16x16x32_bf16 v[54:57], v[162:165], v[178:181], v[54:57]
	v_mfma_f32_16x16x32_bf16 v[50:53], v[170:173], v[178:181], v[50:53]
	v_mfma_f32_16x16x32_bf16 v[38:41], v[162:165], v[186:189], v[38:41]
	v_mfma_f32_16x16x32_bf16 v[34:37], v[170:173], v[186:189], v[34:37]
	v_mfma_f32_16x16x32_bf16 v[22:25], v[162:165], v[194:197], v[22:25]
	v_mfma_f32_16x16x32_bf16 v[18:21], v[170:173], v[194:197], v[18:21]
	v_mfma_f32_16x16x32_bf16 v[6:9], v[162:165], v[202:205], v[6:9]
	v_mfma_f32_16x16x32_bf16 v[2:5], v[170:173], v[202:205], v[2:5]
	s_setprio 0
	s_barrier
	s_movk_i32 s15, 0x100
	s_andn2_b64 vcc, exec, s[38:39]
	s_mov_b64 s[40:41], -1
	s_mov_b64 s[38:39], 0
	s_cbranch_vccz .LBB0_601
	s_and_b64 vcc, exec, s[12:13]
	s_cbranch_vccz .LBB0_604
	s_barrier

; #define PG8_STAGE(bufoff, gbase, voff) do { _Pragma("unroll") for (int _i = 0; _i < 2; ++_i) \
;         __builtin_amdgcn_global_load_lds((const unsigned*)((const char*)(gbase) + (voff)[_i]), (LAS unsigned*)(lds + (bufoff) + ldsw + _i * 8192), 16, 0, 0); } while (0)
; #define PG8_LDA(dst, b, h) do { _Pragma("unroll") for (int m = 0; m < 4; ++m) _Pragma("unroll") for (int k = 0; k < 2; ++k) dst[m][k] = *(const LAS bf16x8*)(lds + PG8_SA(b, h) + aoff + m * 2048 + k * 1024); } while (0)
; #define PG8_LDB(dst, b, h) do { _Pragma("unroll") for (int n = 0; n < 2; ++n) _Pragma("unroll") for (int k = 0; k < 2; ++k) dst[n][k] = *(const LAS bf16x8*)(lds + PG8_SB(b, h) + boff + n * 2048 + k * 1024); } while (0)
; #define PG8_MMA(ai, bj, At, Bt) do { __builtin_amdgcn_s_setprio(1); _Pragma("unroll") for (int m = 0; m < 4; ++m) _Pragma("unroll") for (int n = 0; n < 2; ++n) _Pragma("unroll") for (int k = 0; k < 2; ++k) \
;         acc[ai][bj][m][n] = __builtin_amdgcn_mfma_f32_16x16x32_bf16(Bt[n][k], At[m][k], acc[ai][bj][m][n], 0, 0, 0); __builtin_amdgcn_s_setprio(0); } while (0)
; #define PG8_WAIT_V(n) asm volatile("s_waitcnt vmcnt(" #n ")" ::: "memory")
; #define PG8_WAIT_L(n) asm volatile("s_waitcnt lgkmcnt(" #n ")" ::: "memory")
; template <class Epi, class Sched, bool ALIGN_EPI, bool LAST_FUSED = false, bool PERM = false, bool CARRY = false>
; __device__ __forceinline__ void gemm_phase(LAS unsigned char* lds, const int tid, const int K, const int lda, const int ldb, const Sched& S, const Epi& E) {
;     ...
;         for (int t = 0; t < nt; t += 2) {
;             const bool last = (t == nt - 2);
;             const char* a1 = cA + (size_t)(t + 1) * kstep;
;             const char* a2 = last ? nA : cA + (size_t)(t + 2) * kstep; const char* b2 = last ? nB : cB + (size_t)(t + 2) * kstep;
;             const char* a3 = a2 + kstep; const char* b3 = b2 + kstep;
;             PG8_LDB(B0, 0, 0); PG8_LDB(B1, 0, 1); PG8_SCHED; PG8_LDA(At, 0, 0); PG8_STAGE(PG8_SA(1, 1), a1 + hstepA, voffA);
;             PG8_WAIT_V(8); PG8_WAIT_L(0); PG8_BAR; PG8_MMA(0, 0, At, B0); PG8_MMA(0, 1, At, B1); PG8_BAR; PG8_SCHED;
;             PG8_LDA(At, 0, 1); PG8_STAGE(PG8_SB(0, 0), b2, voffB); PG8_STAGE(PG8_SB(0, 1), b2 + hstepB, voffB); PG8_STAGE(PG8_SA(0, 0), a2, voffA);
;             PG8_WAIT_V(8); PG8_WAIT_L(0); PG8_BAR; PG8_MMA(1, 0, At, B0); PG8_MMA(1, 1, At, B1); PG8_BAR; PG8_SCHED;
.LBB0_622:
	s_add_u32 s48, s30, s24
	s_addc_u32 s49, s31, 0
	s_add_u32 s42, s48, 0x100
	s_addc_u32 s43, s49, 0
	s_and_b64 s[40:41], s[38:39], exec
	s_cselect_b32 s43, s15, s43
	s_cselect_b32 s42, s14, s42
	s_add_u32 s24, s26, s24
	s_addc_u32 s40, s27, 0
	s_add_u32 s24, s24, 0x100
	s_addc_u32 s40, s40, 0
	s_add_i32 s62, 0, 0x10000
	s_and_b64 s[38:39], s[38:39], exec
	s_cselect_b32 s47, s17, s40
	s_cselect_b32 s46, s16, s24
	s_add_i32 s39, 0, 0x14000
	s_add_u32 s64, s48, 0x30080
	s_addc_u32 s65, s49, 0
	s_add_i32 s67, s62, s29
	s_add_i32 m0, s45, 0xc000
	s_add_i32 s66, s45, 0xe000
	s_add_i32 s70, s67, 0x2000
	s_add_u32 s48, s46, 0x10000
	v_add_u32_e32 v152, s62, v140
	v_add_u32_e32 v168, s39, v140
	s_addc_u32 s49, s47, 0
	s_add_i32 s71, s39, s29
	ds_read_b128 v[136:139], v152
	ds_read_b128 v[144:147], v152 offset:1024
	ds_read_b128 v[148:151], v152 offset:2048
	ds_read_b128 v[152:155], v152 offset:3072
	ds_read_b128 v[156:159], v168
	ds_read_b128 v[160:163], v168 offset:1024
	ds_read_b128 v[164:167], v168 offset:2048
	ds_read_b128 v[168:171], v168 offset:3072
	s_add_i32 s74, s71, 0x2000
	s_add_i32 s75, 0, 0x18000
	s_add_i32 s76, 0, 0x1c000
	s_add_u32 s40, s42, 0x30000
	s_addc_u32 s41, s43, 0
	s_add_i32 s61, s75, s29
	s_add_i32 s24, s61, 0x2000
	s_add_u32 s38, s46, 0x10080
	s_addc_u32 s39, s47, 0
	s_add_i32 s63, s76, s29
	s_add_i32 s62, s63, 0x2000
	v_lshl_add_u64 v[204:205], s[64:65], 0, v[130:131]
	ds_read_b128 v[172:175], v143
	ds_read_b128 v[176:179], v143 offset:1024
	ds_read_b128 v[180:183], v143 offset:2048
	ds_read_b128 v[184:187], v143 offset:3072
	ds_read_b128 v[188:191], v143 offset:4096
	ds_read_b128 v[192:195], v143 offset:5120
	ds_read_b128 v[196:199], v143 offset:6144
	ds_read_b128 v[200:203], v143 offset:7168
	global_load_lds_dwordx4 v[204:205], off
	v_lshl_add_u64 v[204:205], s[64:65], 0, v[132:133]
	s_mov_b32 m0, s66
	s_nop 0
	global_load_lds_dwordx4 v[204:205], off
	s_waitcnt vmcnt(8)
	s_waitcnt lgkmcnt(0)
	s_barrier
	s_setprio 1
	v_mfma_f32_16x16x32_bf16 v[126:129], v[136:139], v[172:175], v[126:129]
	v_mfma_f32_16x16x32_bf16 v[122:125], v[148:151], v[172:175], v[122:125]
	v_mfma_f32_16x16x32_bf16 v[118:121], v[136:139], v[180:183], v[118:121]
	v_mfma_f32_16x16x32_bf16 v[114:117], v[148:151], v[180:183], v[114:117]
	v_mfma_f32_16x16x32_bf16 v[110:113], v[136:139], v[188:191], v[110:113]
	v_mfma_f32_16x16x32_bf16 v[106:109], v[148:151], v[188:191], v[106:109]
	v_mfma_f32_16x16x32_bf16 v[102:105], v[136:139], v[196:199], v[102:105]
	v_mfma_f32_16x16x32_bf16 v[98:101], v[148:151], v[196:199], v[98:101]
	v_mfma_f32_16x16x32_bf16 v[126:129], v[144:147], v[176:179], v[126:129]
	v_mfma_f32_16x16x32_bf16 v[122:125], v[152:155], v[176:179], v[122:125]
	v_mfma_f32_16x16x32_bf16 v[118:121], v[144:147], v[184:187], v[118:121]
	v_mfma_f32_16x16x32_bf16 v[114:117], v[152:155], v[184:187], v[114:117]
	v_mfma_f32_16x16x32_bf16 v[110:113], v[144:147], v[192:195], v[110:113]
	v_mfma_f32_16x16x32_bf16 v[106:109], v[152:155], v[192:195], v[106:109]
	v_mfma_f32_16x16x32_bf16 v[102:105], v[144:147], v[200:203], v[102:105]
	v_mfma_f32_16x16x32_bf16 v[98:101], v[152:155], v[200:203], v[98:101]
	s_setprio 0
	s_setprio 1
	v_mfma_f32_16x16x32_bf16 v[94:97], v[156:159], v[172:175], v[94:97]
	v_mfma_f32_16x16x32_bf16 v[90:93], v[164:167], v[172:175], v[90:93]
	v_mfma_f32_16x16x32_bf16 v[86:89], v[156:159], v[180:183], v[86:89]
	v_mfma_f32_16x16x32_bf16 v[82:85], v[164:167], v[180:183], v[82:85]
	v_mfma_f32_16x16x32_bf16 v[78:81], v[156:159], v[188:191], v[78:81]
	v_mfma_f32_16x16x32_bf16 v[74:77], v[164:167], v[188:191], v[74:77]
	v_mfma_f32_16x16x32_bf16 v[70:73], v[156:159], v[196:199], v[70:73]
	v_mfma_f32_16x16x32_bf16 v[66:69], v[164:167], v[196:199], v[66:69]
	v_mfma_f32_16x16x32_bf16 v[94:97], v[160:163], v[176:179], v[94:97]
	v_mfma_f32_16x16x32_bf16 v[90:93], v[168:171], v[176:179], v[90:93]
	v_mfma_f32_16x16x32_bf16 v[86:89], v[160:163], v[184:187], v[86:89]
	v_mfma_f32_16x16x32_bf16 v[82:85], v[168:171], v[184:187], v[82:85]
	v_mfma_f32_16x16x32_bf16 v[78:81], v[160:163], v[192:195], v[78:81]
	v_mfma_f32_16x16x32_bf16 v[74:77], v[168:171], v[192:195], v[74:77]
	v_mfma_f32_16x16x32_bf16 v[70:73], v[160:163], v[200:203], v[70:73]
	v_mfma_f32_16x16x32_bf16 v[66:69], v[168:171], v[200:203], v[66:69]
	s_setprio 0
	s_barrier
	s_mov_b32 m0, s67
	v_lshl_add_u64 v[204:205], s[46:47], 0, v[0:1]
	ds_read_b128 v[172:175], v143 offset:16384
	ds_read_b128 v[176:179], v143 offset:17408
	ds_read_b128 v[180:183], v143 offset:18432
	ds_read_b128 v[184:187], v143 offset:19456
	ds_read_b128 v[188:191], v143 offset:20480
	ds_read_b128 v[192:195], v143 offset:21504
	ds_read_b128 v[196:199], v143 offset:22528
	ds_read_b128 v[200:203], v143 offset:23552
	global_load_lds_dwordx4 v[204:205], off
	v_lshl_add_u64 v[206:207], s[46:47], 0, v[134:135]
	s_mov_b32 m0, s70
	v_lshl_add_u64 v[208:209], s[48:49], 0, v[0:1]
	global_load_lds_dwordx4 v[206:207], off
	s_mov_b32 m0, s71
	v_lshl_add_u64 v[210:211], s[42:43], 0, v[132:133]
	global_load_lds_dwordx4 v[208:209], off
	v_lshl_add_u64 v[208:209], s[48:49], 0, v[134:135]
	s_mov_b32 m0, s74
	s_nop 0
	global_load_lds_dwordx4 v[208:209], off
	v_lshl_add_u64 v[208:209], s[42:43], 0, v[130:131]
	s_mov_b32 m0, s45
	s_nop 0
	global_load_lds_dwordx4 v[208:209], off
	s_mov_b32 m0, s50
	s_nop 0
	global_load_lds_dwordx4 v[210:211], off
	s_waitcnt vmcnt(8)
	s_waitcnt lgkmcnt(0)
	s_barrier
; #define PG8_STAGE(bufoff, gbase, voff) do { _Pragma("unroll") for (int _i = 0; _i < 2; ++_i) \
;         __builtin_amdgcn_global_load_lds((const unsigned*)((const char*)(gbase) + (voff)[_i]), (LAS unsigned*)(lds + (bufoff) + ldsw + _i * 8192), 16, 0, 0); } while (0)
; #define PG8_LDA(dst, b, h) do { _Pragma("unroll") for (int m = 0; m < 4; ++m) _Pragma("unroll") for (int k = 0; k < 2; ++k) dst[m][k] = *(const LAS bf16x8*)(lds + PG8_SA(b, h) + aoff + m * 2048 + k * 1024); } while (0)
; #define PG8_LDB(dst, b, h) do { _Pragma("unroll") for (int n = 0; n < 2; ++n) _Pragma("unroll") for (int k = 0; k < 2; ++k) dst[n][k] = *(const LAS bf16x8*)(lds + PG8_SB(b, h) + boff + n * 2048 + k * 1024); } while (0)
; #define PG8_MMA(ai, bj, At, Bt) do { __builtin_amdgcn_s_setprio(1); _Pragma("unroll") for (int m = 0; m < 4; ++m) _Pragma("unroll") for (int n = 0; n < 2; ++n) _Pragma("unroll") for (int k = 0; k < 2; ++k) \
;         acc[ai][bj][m][n] = __builtin_amdgcn_mfma_f32_16x16x32_bf16(Bt[n][k], At[m][k], acc[ai][bj][m][n], 0, 0, 0); __builtin_amdgcn_s_setprio(0); } while (0)
; #define PG8_WAIT_V(n) asm volatile("s_waitcnt vmcnt(" #n ")" ::: "memory")
; #define PG8_WAIT_L(n) asm volatile("s_waitcnt lgkmcnt(" #n ")" ::: "memory")
; #define PG8_BAR __builtin_amdgcn_s_barrier()
; #define PG8_SCHED __builtin_amdgcn_sched_barrier(0)
; template <class Epi, class Sched, bool ALIGN_EPI, bool LAST_FUSED = false, bool PERM = false, bool CARRY = false>
; __device__ __forceinline__ void gemm_phase(LAS unsigned char* lds, const int tid, const int K, const int lda, const int ldb, const Sched& S, const Epi& E) {
;     ...
;             PG8_WAIT_V(8); PG8_WAIT_L(0); PG8_BAR; PG8_MMA(1, 0, At, B0); PG8_MMA(1, 1, At, B1); PG8_BAR; PG8_SCHED;
;             PG8_LDB(B0, 1, 0); PG8_LDB(B1, 1, 1); PG8_SCHED; PG8_LDA(At, 1, 0); PG8_STAGE(PG8_SA(0, 1), a2 + hstepA, voffA);
;             PG8_WAIT_V(8); PG8_WAIT_L(0); PG8_BAR; PG8_MMA(0, 0, At, B0); PG8_MMA(0, 1, At, B1); PG8_BAR; PG8_SCHED;
	s_setprio 1
	v_mfma_f32_16x16x32_bf16 v[62:65], v[136:139], v[172:175], v[62:65]
	v_mfma_f32_16x16x32_bf16 v[58:61], v[148:151], v[172:175], v[58:61]
	v_mfma_f32_16x16x32_bf16 v[54:57], v[136:139], v[180:183], v[54:57]
	v_mfma_f32_16x16x32_bf16 v[50:53], v[148:151], v[180:183], v[50:53]
	v_mfma_f32_16x16x32_bf16 v[46:49], v[136:139], v[188:191], v[46:49]
	v_mfma_f32_16x16x32_bf16 v[42:45], v[148:151], v[188:191], v[42:45]
	v_mfma_f32_16x16x32_bf16 v[38:41], v[136:139], v[196:199], v[38:41]
	v_mfma_f32_16x16x32_bf16 v[34:37], v[148:151], v[196:199], v[34:37]
	v_mfma_f32_16x16x32_bf16 v[62:65], v[144:147], v[176:179], v[62:65]
	v_mfma_f32_16x16x32_bf16 v[58:61], v[152:155], v[176:179], v[58:61]
	v_mfma_f32_16x16x32_bf16 v[54:57], v[144:147], v[184:187], v[54:57]
	v_mfma_f32_16x16x32_bf16 v[50:53], v[152:155], v[184:187], v[50:53]
	v_mfma_f32_16x16x32_bf16 v[46:49], v[144:147], v[192:195], v[46:49]
	v_mfma_f32_16x16x32_bf16 v[42:45], v[152:155], v[192:195], v[42:45]
	v_mfma_f32_16x16x32_bf16 v[38:41], v[144:147], v[200:203], v[38:41]
	v_mfma_f32_16x16x32_bf16 v[34:37], v[152:155], v[200:203], v[34:37]
	s_setprio 0
	s_setprio 1
	v_mfma_f32_16x16x32_bf16 v[30:33], v[156:159], v[172:175], v[30:33]
	v_mfma_f32_16x16x32_bf16 v[26:29], v[164:167], v[172:175], v[26:29]
	v_mfma_f32_16x16x32_bf16 v[22:25], v[156:159], v[180:183], v[22:25]
	v_mfma_f32_16x16x32_bf16 v[18:21], v[164:167], v[180:183], v[18:21]
	v_mfma_f32_16x16x32_bf16 v[14:17], v[156:159], v[188:191], v[14:17]
	v_mfma_f32_16x16x32_bf16 v[10:13], v[164:167], v[188:191], v[10:13]
	v_mfma_f32_16x16x32_bf16 v[6:9], v[156:159], v[196:199], v[6:9]
	v_mfma_f32_16x16x32_bf16 v[2:5], v[164:167], v[196:199], v[2:5]
	v_mfma_f32_16x16x32_bf16 v[30:33], v[160:163], v[176:179], v[30:33]
	v_mfma_f32_16x16x32_bf16 v[26:29], v[168:171], v[176:179], v[26:29]
	v_mfma_f32_16x16x32_bf16 v[22:25], v[160:163], v[184:187], v[22:25]
	v_mfma_f32_16x16x32_bf16 v[18:21], v[168:171], v[184:187], v[18:21]
	v_mfma_f32_16x16x32_bf16 v[14:17], v[160:163], v[192:195], v[14:17]
	v_mfma_f32_16x16x32_bf16 v[10:13], v[168:171], v[192:195], v[10:13]
	v_mfma_f32_16x16x32_bf16 v[6:9], v[160:163], v[200:203], v[6:9]
	v_mfma_f32_16x16x32_bf16 v[2:5], v[168:171], v[200:203], v[2:5]
	s_setprio 0
	s_barrier
	v_add_u32_e32 v152, s75, v140
	v_add_u32_e32 v168, s76, v140
	ds_read_b128 v[136:139], v152
	ds_read_b128 v[144:147], v152 offset:1024
	ds_read_b128 v[148:151], v152 offset:2048
	ds_read_b128 v[152:155], v152 offset:3072
	ds_read_b128 v[156:159], v168
	ds_read_b128 v[160:163], v168 offset:1024
	ds_read_b128 v[164:167], v168 offset:2048
	ds_read_b128 v[168:171], v168 offset:3072
	s_mov_b32 m0, s51
	v_lshl_add_u64 v[212:213], s[40:41], 0, v[130:131]
	ds_read_b128 v[172:175], v143 offset:32768
	ds_read_b128 v[176:179], v143 offset:33792
	ds_read_b128 v[180:183], v143 offset:34816
	ds_read_b128 v[184:187], v143 offset:35840
	ds_read_b128 v[188:191], v143 offset:36864
	ds_read_b128 v[192:195], v143 offset:37888
	ds_read_b128 v[196:199], v143 offset:38912
	ds_read_b128 v[200:203], v143 offset:39936
	global_load_lds_dwordx4 v[212:213], off
	v_lshl_add_u64 v[212:213], s[40:41], 0, v[132:133]
	s_mov_b32 m0, s52
	s_nop 0
	global_load_lds_dwordx4 v[212:213], off
	s_waitcnt vmcnt(8)
	s_waitcnt lgkmcnt(0)
	s_barrier
	s_setprio 1
	v_mfma_f32_16x16x32_bf16 v[126:129], v[136:139], v[172:175], v[126:129]
	v_mfma_f32_16x16x32_bf16 v[122:125], v[148:151], v[172:175], v[122:125]
	v_mfma_f32_16x16x32_bf16 v[118:121], v[136:139], v[180:183], v[118:121]
	v_mfma_f32_16x16x32_bf16 v[114:117], v[148:151], v[180:183], v[114:117]
	v_mfma_f32_16x16x32_bf16 v[110:113], v[136:139], v[188:191], v[110:113]
	v_mfma_f32_16x16x32_bf16 v[106:109], v[148:151], v[188:191], v[106:109]
	v_mfma_f32_16x16x32_bf16 v[102:105], v[136:139], v[196:199], v[102:105]
	v_mfma_f32_16x16x32_bf16 v[98:101], v[148:151], v[196:199], v[98:101]
	v_mfma_f32_16x16x32_bf16 v[126:129], v[144:147], v[176:179], v[126:129]
	v_mfma_f32_16x16x32_bf16 v[122:125], v[152:155], v[176:179], v[122:125]
	v_mfma_f32_16x16x32_bf16 v[118:121], v[144:147], v[184:187], v[118:121]
	v_mfma_f32_16x16x32_bf16 v[114:117], v[152:155], v[184:187], v[114:117]
	v_mfma_f32_16x16x32_bf16 v[110:113], v[144:147], v[192:195], v[110:113]
	v_mfma_f32_16x16x32_bf16 v[106:109], v[152:155], v[192:195], v[106:109]
	v_mfma_f32_16x16x32_bf16 v[102:105], v[144:147], v[200:203], v[102:105]
	v_mfma_f32_16x16x32_bf16 v[98:101], v[152:155], v[200:203], v[98:101]
	s_setprio 0
	s_setprio 1
	v_mfma_f32_16x16x32_bf16 v[94:97], v[156:159], v[172:175], v[94:97]
	v_mfma_f32_16x16x32_bf16 v[90:93], v[164:167], v[172:175], v[90:93]
	v_mfma_f32_16x16x32_bf16 v[86:89], v[156:159], v[180:183], v[86:89]
	v_mfma_f32_16x16x32_bf16 v[82:85], v[164:167], v[180:183], v[82:85]
	v_mfma_f32_16x16x32_bf16 v[78:81], v[156:159], v[188:191], v[78:81]
	v_mfma_f32_16x16x32_bf16 v[74:77], v[164:167], v[188:191], v[74:77]
	v_mfma_f32_16x16x32_bf16 v[70:73], v[156:159], v[196:199], v[70:73]
	v_mfma_f32_16x16x32_bf16 v[66:69], v[164:167], v[196:199], v[66:69]
	v_mfma_f32_16x16x32_bf16 v[94:97], v[160:163], v[176:179], v[94:97]
	v_mfma_f32_16x16x32_bf16 v[90:93], v[168:171], v[176:179], v[90:93]
	v_mfma_f32_16x16x32_bf16 v[86:89], v[160:163], v[184:187], v[86:89]
	v_mfma_f32_16x16x32_bf16 v[82:85], v[168:171], v[184:187], v[82:85]
	v_mfma_f32_16x16x32_bf16 v[78:81], v[160:163], v[192:195], v[78:81]
	v_mfma_f32_16x16x32_bf16 v[74:77], v[168:171], v[192:195], v[74:77]
	v_mfma_f32_16x16x32_bf16 v[70:73], v[160:163], v[200:203], v[70:73]
	v_mfma_f32_16x16x32_bf16 v[66:69], v[168:171], v[200:203], v[66:69]
	s_setprio 0
	s_barrier
; #define PG8_STAGE(bufoff, gbase, voff) do { _Pragma("unroll") for (int _i = 0; _i < 2; ++_i) \
;         __builtin_amdgcn_global_load_lds((const unsigned*)((const char*)(gbase) + (voff)[_i]), (LAS unsigned*)(lds + (bufoff) + ldsw + _i * 8192), 16, 0, 0); } while (0)
; #define PG8_LDA(dst, b, h) do { _Pragma("unroll") for (int m = 0; m < 4; ++m) _Pragma("unroll") for (int k = 0; k < 2; ++k) dst[m][k] = *(const LAS bf16x8*)(lds + PG8_SA(b, h) + aoff + m * 2048 + k * 1024); } while (0)
; #define PG8_MMA(ai, bj, At, Bt) do { __builtin_amdgcn_s_setprio(1); _Pragma("unroll") for (int m = 0; m < 4; ++m) _Pragma("unroll") for (int n = 0; n < 2; ++n) _Pragma("unroll") for (int k = 0; k < 2; ++k) \
;         acc[ai][bj][m][n] = __builtin_amdgcn_mfma_f32_16x16x32_bf16(Bt[n][k], At[m][k], acc[ai][bj][m][n], 0, 0, 0); __builtin_amdgcn_s_setprio(0); } while (0)
; #define PG8_WAIT_V(n) asm volatile("s_waitcnt vmcnt(" #n ")" ::: "memory")
; #define PG8_WAIT_L(n) asm volatile("s_waitcnt lgkmcnt(" #n ")" ::: "memory")
; #define PG8_BAR __builtin_amdgcn_s_barrier()
; #define PG8_SCHED __builtin_amdgcn_sched_barrier(0)
; template <class Epi, class Sched, bool ALIGN_EPI, bool LAST_FUSED = false, bool PERM = false, bool CARRY = false>
; __device__ __forceinline__ void gemm_phase(LAS unsigned char* lds, const int tid, const int K, const int lda, const int ldb, const Sched& S, const Epi& E) {
;     ...
;             PG8_LDA(At, 1, 1); PG8_STAGE(PG8_SB(1, 0), b3, voffB); PG8_STAGE(PG8_SB(1, 1), b3 + hstepB, voffB); PG8_STAGE(PG8_SA(1, 0), a3, voffA);
;             PG8_WAIT_V(8); PG8_WAIT_L(0); PG8_BAR; PG8_MMA(1, 0, At, B0); PG8_MMA(1, 1, At, B1); PG8_BAR; PG8_SCHED;
;         }
;         if constexpr (ALIGN_EPI) { if (wr == 0) PG8_BAR; }
	s_mov_b32 m0, s61
	v_lshl_add_u64 v[204:205], v[204:205], 0, s[68:69]
	ds_read_b128 v[172:175], v143 offset:49152
	ds_read_b128 v[176:179], v143 offset:50176
	ds_read_b128 v[180:183], v143 offset:51200
	ds_read_b128 v[184:187], v143 offset:52224
	ds_read_b128 v[188:191], v143 offset:53248
	ds_read_b128 v[192:195], v143 offset:54272
	ds_read_b128 v[196:199], v143 offset:55296
	ds_read_b128 v[200:203], v143 offset:56320
	global_load_lds_dwordx4 v[204:205], off
	v_lshl_add_u64 v[204:205], v[206:207], 0, s[68:69]
	s_mov_b32 m0, s24
	s_nop 0
	global_load_lds_dwordx4 v[204:205], off
	v_lshl_add_u64 v[204:205], s[38:39], 0, v[0:1]
	s_mov_b32 m0, s63
	s_nop 0
	global_load_lds_dwordx4 v[204:205], off
	v_lshl_add_u64 v[204:205], s[38:39], 0, v[134:135]
	s_mov_b32 m0, s62
	s_nop 0
	global_load_lds_dwordx4 v[204:205], off
	v_lshl_add_u64 v[204:205], v[208:209], 0, s[68:69]
	s_mov_b32 m0, s55
	s_nop 0
	global_load_lds_dwordx4 v[204:205], off
	v_lshl_add_u64 v[204:205], v[210:211], 0, s[68:69]
	s_mov_b32 m0, s56
	s_nop 0
	global_load_lds_dwordx4 v[204:205], off
	s_waitcnt vmcnt(8)
	s_waitcnt lgkmcnt(0)
	s_barrier
	s_setprio 1
	v_mfma_f32_16x16x32_bf16 v[62:65], v[136:139], v[172:175], v[62:65]
	v_mfma_f32_16x16x32_bf16 v[58:61], v[148:151], v[172:175], v[58:61]
	v_mfma_f32_16x16x32_bf16 v[54:57], v[136:139], v[180:183], v[54:57]
	v_mfma_f32_16x16x32_bf16 v[50:53], v[148:151], v[180:183], v[50:53]
	v_mfma_f32_16x16x32_bf16 v[46:49], v[136:139], v[188:191], v[46:49]
	v_mfma_f32_16x16x32_bf16 v[42:45], v[148:151], v[188:191], v[42:45]
	v_mfma_f32_16x16x32_bf16 v[38:41], v[136:139], v[196:199], v[38:41]
	v_mfma_f32_16x16x32_bf16 v[34:37], v[148:151], v[196:199], v[34:37]
	v_mfma_f32_16x16x32_bf16 v[62:65], v[144:147], v[176:179], v[62:65]
	v_mfma_f32_16x16x32_bf16 v[58:61], v[152:155], v[176:179], v[58:61]
	v_mfma_f32_16x16x32_bf16 v[54:57], v[144:147], v[184:187], v[54:57]
	v_mfma_f32_16x16x32_bf16 v[50:53], v[152:155], v[184:187], v[50:53]
	v_mfma_f32_16x16x32_bf16 v[46:49], v[144:147], v[192:195], v[46:49]
	v_mfma_f32_16x16x32_bf16 v[42:45], v[152:155], v[192:195], v[42:45]
	v_mfma_f32_16x16x32_bf16 v[38:41], v[144:147], v[200:203], v[38:41]
	v_mfma_f32_16x16x32_bf16 v[34:37], v[152:155], v[200:203], v[34:37]
	s_setprio 0
	s_setprio 1
	v_mfma_f32_16x16x32_bf16 v[30:33], v[156:159], v[172:175], v[30:33]
	v_mfma_f32_16x16x32_bf16 v[26:29], v[164:167], v[172:175], v[26:29]
	v_mfma_f32_16x16x32_bf16 v[22:25], v[156:159], v[180:183], v[22:25]
	v_mfma_f32_16x16x32_bf16 v[18:21], v[164:167], v[180:183], v[18:21]
	v_mfma_f32_16x16x32_bf16 v[14:17], v[156:159], v[188:191], v[14:17]
	v_mfma_f32_16x16x32_bf16 v[10:13], v[164:167], v[188:191], v[10:13]
	v_mfma_f32_16x16x32_bf16 v[6:9], v[156:159], v[196:199], v[6:9]
	v_mfma_f32_16x16x32_bf16 v[2:5], v[164:167], v[196:199], v[2:5]
	v_mfma_f32_16x16x32_bf16 v[30:33], v[160:163], v[176:179], v[30:33]
	v_mfma_f32_16x16x32_bf16 v[26:29], v[168:171], v[176:179], v[26:29]
	v_mfma_f32_16x16x32_bf16 v[22:25], v[160:163], v[184:187], v[22:25]
	v_mfma_f32_16x16x32_bf16 v[18:21], v[168:171], v[184:187], v[18:21]
	v_mfma_f32_16x16x32_bf16 v[14:17], v[160:163], v[192:195], v[14:17]
	v_mfma_f32_16x16x32_bf16 v[10:13], v[168:171], v[192:195], v[10:13]
	v_mfma_f32_16x16x32_bf16 v[6:9], v[160:163], v[200:203], v[6:9]
	v_mfma_f32_16x16x32_bf16 v[2:5], v[168:171], v[200:203], v[2:5]
	s_setprio 0
	s_barrier
	s_movk_i32 s24, 0x100
	s_andn2_b64 vcc, exec, s[36:37]
	s_mov_b64 s[38:39], -1
	s_mov_b64 s[36:37], 0
	s_cbranch_vccz .LBB0_622
	s_and_b64 vcc, exec, s[10:11]
	s_cbranch_vccz .LBB0_625
	s_barrier

; #define PG8_STAGE(bufoff, gbase, voff) do { _Pragma("unroll") for (int _i = 0; _i < 2; ++_i) \
;         __builtin_amdgcn_global_load_lds((const unsigned*)((const char*)(gbase) + (voff)[_i]), (LAS unsigned*)(lds + (bufoff) + ldsw + _i * 8192), 16, 0, 0); } while (0)
; #define PG8_LDA(dst, b, h) do { _Pragma("unroll") for (int m = 0; m < 4; ++m) _Pragma("unroll") for (int k = 0; k < 2; ++k) dst[m][k] = *(const LAS bf16x8*)(lds + PG8_SA(b, h) + aoff + m * 2048 + k * 1024); } while (0)
; #define PG8_LDB(dst, b, h) do { _Pragma("unroll") for (int n = 0; n < 2; ++n) _Pragma("unroll") for (int k = 0; k < 2; ++k) dst[n][k] = *(const LAS bf16x8*)(lds + PG8_SB(b, h) + boff + n * 2048 + k * 1024); } while (0)
; #define PG8_MMA(ai, bj, At, Bt) do { __builtin_amdgcn_s_setprio(1); _Pragma("unroll") for (int m = 0; m < 4; ++m) _Pragma("unroll") for (int n = 0; n < 2; ++n) _Pragma("unroll") for (int k = 0; k < 2; ++k) \
;         acc[ai][bj][m][n] = __builtin_amdgcn_mfma_f32_16x16x32_bf16(Bt[n][k], At[m][k], acc[ai][bj][m][n], 0, 0, 0); __builtin_amdgcn_s_setprio(0); } while (0)
; #define PG8_WAIT_V(n) asm volatile("s_waitcnt vmcnt(" #n ")" ::: "memory")
; #define PG8_WAIT_L(n) asm volatile("s_waitcnt lgkmcnt(" #n ")" ::: "memory")
; #define PG8_BAR __builtin_amdgcn_s_barrier()
; template <class Epi, class Sched, bool ALIGN_EPI, bool LAST_FUSED = false, bool PERM = false, bool CARRY = false>
; __device__ __forceinline__ void gemm_phase(LAS unsigned char* lds, const int tid, const int K, const int lda, const int ldb, const Sched& S, const Epi& E) {
;     ...
;             const bool last = (t == nt - 2);
;             const char* a1 = cA + (size_t)(t + 1) * kstep;
;             const char* a2 = last ? nA : cA + (size_t)(t + 2) * kstep; const char* b2 = last ? nB : cB + (size_t)(t + 2) * kstep;
;             const char* a3 = a2 + kstep; const char* b3 = b2 + kstep;
;             PG8_LDB(B0, 0, 0); PG8_LDB(B1, 0, 1); PG8_SCHED; PG8_LDA(At, 0, 0); PG8_STAGE(PG8_SA(1, 1), a1 + hstepA, voffA);
;             PG8_WAIT_V(8); PG8_WAIT_L(0); PG8_BAR; PG8_MMA(0, 0, At, B0); PG8_MMA(0, 1, At, B1); PG8_BAR; PG8_SCHED;
;             PG8_LDA(At, 0, 1); PG8_STAGE(PG8_SB(0, 0), b2, voffB); PG8_STAGE(PG8_SB(0, 1), b2 + hstepB, voffB); PG8_STAGE(PG8_SA(0, 0), a2, voffA);
;             PG8_WAIT_V(8); PG8_WAIT_L(0); PG8_BAR; PG8_MMA(1, 0, At, B0); PG8_MMA(1, 1, At, B1); PG8_BAR; PG8_SCHED;
.LBB0_705:
	s_add_u32 s30, s26, 0x100
	s_addc_u32 s31, s27, 0
	s_add_i32 s54, 0, 0x10000
	s_cmp_eq_u32 s53, 8
	s_cselect_b32 s39, s15, s31
	s_cselect_b32 s38, s14, s30
	v_add_u32_e32 v140, s54, v144
	s_cselect_b32 s37, s17, s52
	s_cselect_b32 s36, s16, s13
	s_add_i32 s55, 0, 0x14000
	ds_read_b128 v[146:149], v140
	ds_read_b128 v[150:153], v140 offset:1024
	ds_read_b128 v[154:157], v140 offset:2048
	ds_read_b128 v[158:161], v140 offset:3072
	v_add_u32_e32 v140, s55, v144
	ds_read_b128 v[162:165], v140
	ds_read_b128 v[166:169], v140 offset:1024
	ds_read_b128 v[170:173], v140 offset:2048
	ds_read_b128 v[174:177], v140 offset:3072
	v_lshl_add_u64 v[140:141], s[26:27], 0, v[136:137]
	s_add_i32 m0, s19, 0xc000
	ds_read_b128 v[178:181], v145
	ds_read_b128 v[182:185], v145 offset:1024
	ds_read_b128 v[186:189], v145 offset:2048
	ds_read_b128 v[190:193], v145 offset:3072
	ds_read_b128 v[194:197], v145 offset:4096
	ds_read_b128 v[198:201], v145 offset:5120
	ds_read_b128 v[202:205], v145 offset:6144
	ds_read_b128 v[206:209], v145 offset:7168
	global_load_lds_dwordx4 v[140:141], off
	v_lshl_add_u64 v[140:141], s[26:27], 0, v[138:139]
	s_add_i32 m0, s19, 0xe000
	s_nop 0
	global_load_lds_dwordx4 v[140:141], off
	s_waitcnt vmcnt(8)
	s_waitcnt lgkmcnt(0)
	s_barrier
	s_setprio 1
	v_mfma_f32_16x16x32_bf16 v[126:129], v[146:149], v[178:181], v[126:129]
	v_mfma_f32_16x16x32_bf16 v[122:125], v[154:157], v[178:181], v[122:125]
	v_mfma_f32_16x16x32_bf16 v[118:121], v[146:149], v[186:189], v[118:121]
	v_mfma_f32_16x16x32_bf16 v[110:113], v[154:157], v[186:189], v[110:113]
	v_mfma_f32_16x16x32_bf16 v[102:105], v[146:149], v[194:197], v[102:105]
	v_mfma_f32_16x16x32_bf16 v[94:97], v[154:157], v[194:197], v[94:97]
	v_mfma_f32_16x16x32_bf16 v[86:89], v[146:149], v[202:205], v[86:89]
	v_mfma_f32_16x16x32_bf16 v[78:81], v[154:157], v[202:205], v[78:81]
	v_mfma_f32_16x16x32_bf16 v[126:129], v[150:153], v[182:185], v[126:129]
	v_mfma_f32_16x16x32_bf16 v[122:125], v[158:161], v[182:185], v[122:125]
	v_mfma_f32_16x16x32_bf16 v[118:121], v[150:153], v[190:193], v[118:121]
	v_mfma_f32_16x16x32_bf16 v[110:113], v[158:161], v[190:193], v[110:113]
	v_mfma_f32_16x16x32_bf16 v[102:105], v[150:153], v[198:201], v[102:105]
	v_mfma_f32_16x16x32_bf16 v[94:97], v[158:161], v[198:201], v[94:97]
	v_mfma_f32_16x16x32_bf16 v[86:89], v[150:153], v[206:209], v[86:89]
	v_mfma_f32_16x16x32_bf16 v[78:81], v[158:161], v[206:209], v[78:81]
	s_setprio 0
	s_setprio 1
	v_mfma_f32_16x16x32_bf16 v[114:117], v[162:165], v[178:181], v[114:117]
	v_mfma_f32_16x16x32_bf16 v[106:109], v[170:173], v[178:181], v[106:109]
	v_mfma_f32_16x16x32_bf16 v[98:101], v[162:165], v[186:189], v[98:101]
	v_mfma_f32_16x16x32_bf16 v[90:93], v[170:173], v[186:189], v[90:93]
	v_mfma_f32_16x16x32_bf16 v[82:85], v[162:165], v[194:197], v[82:85]
	v_mfma_f32_16x16x32_bf16 v[74:77], v[170:173], v[194:197], v[74:77]
	v_mfma_f32_16x16x32_bf16 v[70:73], v[162:165], v[202:205], v[70:73]
	v_mfma_f32_16x16x32_bf16 v[66:69], v[170:173], v[202:205], v[66:69]
	v_mfma_f32_16x16x32_bf16 v[114:117], v[166:169], v[182:185], v[114:117]
	v_mfma_f32_16x16x32_bf16 v[106:109], v[174:177], v[182:185], v[106:109]
	v_mfma_f32_16x16x32_bf16 v[98:101], v[166:169], v[190:193], v[98:101]
	v_mfma_f32_16x16x32_bf16 v[90:93], v[174:177], v[190:193], v[90:93]
	v_mfma_f32_16x16x32_bf16 v[82:85], v[166:169], v[198:201], v[82:85]
	v_mfma_f32_16x16x32_bf16 v[74:77], v[174:177], v[198:201], v[74:77]
	v_mfma_f32_16x16x32_bf16 v[70:73], v[166:169], v[206:209], v[70:73]
	v_mfma_f32_16x16x32_bf16 v[66:69], v[174:177], v[206:209], v[66:69]
	s_setprio 0
	s_barrier
	s_add_i32 s26, s54, s40
	v_lshl_add_u64 v[140:141], s[36:37], 0, v[0:1]
	s_mov_b32 m0, s26
	ds_read_b128 v[178:181], v145 offset:16384
	ds_read_b128 v[182:185], v145 offset:17408
	ds_read_b128 v[186:189], v145 offset:18432
	ds_read_b128 v[190:193], v145 offset:19456
	ds_read_b128 v[194:197], v145 offset:20480
	ds_read_b128 v[198:201], v145 offset:21504
	ds_read_b128 v[202:205], v145 offset:22528
	ds_read_b128 v[206:209], v145 offset:23552
	global_load_lds_dwordx4 v[140:141], off
	s_add_i32 m0, s26, 0x2000
	s_add_u32 s26, s36, 0x30000
	v_lshl_add_u64 v[210:211], s[36:37], 0, v[130:131]
	s_addc_u32 s27, s37, 0
	s_add_i32 s54, s55, s40
	global_load_lds_dwordx4 v[210:211], off
	v_lshl_add_u64 v[212:213], s[26:27], 0, v[0:1]
	s_mov_b32 m0, s54
	v_lshl_add_u64 v[214:215], s[38:39], 0, v[132:133]
	global_load_lds_dwordx4 v[212:213], off
	v_lshl_add_u64 v[212:213], s[26:27], 0, v[130:131]
	s_add_i32 m0, s54, 0x2000
	s_nop 0
	global_load_lds_dwordx4 v[212:213], off
	v_lshl_add_u64 v[212:213], s[38:39], 0, v[134:135]
	s_mov_b32 m0, s19
	s_nop 0
	global_load_lds_dwordx4 v[212:213], off
	s_mov_b32 m0, s42
	s_nop 0
	global_load_lds_dwordx4 v[214:215], off
	s_waitcnt vmcnt(8)
	s_waitcnt lgkmcnt(0)
	s_barrier
; #define PG8_STAGE(bufoff, gbase, voff) do { _Pragma("unroll") for (int _i = 0; _i < 2; ++_i) \
;         __builtin_amdgcn_global_load_lds((const unsigned*)((const char*)(gbase) + (voff)[_i]), (LAS unsigned*)(lds + (bufoff) + ldsw + _i * 8192), 16, 0, 0); } while (0)
; #define PG8_LDA(dst, b, h) do { _Pragma("unroll") for (int m = 0; m < 4; ++m) _Pragma("unroll") for (int k = 0; k < 2; ++k) dst[m][k] = *(const LAS bf16x8*)(lds + PG8_SA(b, h) + aoff + m * 2048 + k * 1024); } while (0)
; #define PG8_LDB(dst, b, h) do { _Pragma("unroll") for (int n = 0; n < 2; ++n) _Pragma("unroll") for (int k = 0; k < 2; ++k) dst[n][k] = *(const LAS bf16x8*)(lds + PG8_SB(b, h) + boff + n * 2048 + k * 1024); } while (0)
; #define PG8_MMA(ai, bj, At, Bt) do { __builtin_amdgcn_s_setprio(1); _Pragma("unroll") for (int m = 0; m < 4; ++m) _Pragma("unroll") for (int n = 0; n < 2; ++n) _Pragma("unroll") for (int k = 0; k < 2; ++k) \
;         acc[ai][bj][m][n] = __builtin_amdgcn_mfma_f32_16x16x32_bf16(Bt[n][k], At[m][k], acc[ai][bj][m][n], 0, 0, 0); __builtin_amdgcn_s_setprio(0); } while (0)
; #define PG8_WAIT_V(n) asm volatile("s_waitcnt vmcnt(" #n ")" ::: "memory")
; #define PG8_WAIT_L(n) asm volatile("s_waitcnt lgkmcnt(" #n ")" ::: "memory")
; #define PG8_BAR __builtin_amdgcn_s_barrier()
; #define PG8_SCHED __builtin_amdgcn_sched_barrier(0)
; template <class Epi, class Sched, bool ALIGN_EPI, bool LAST_FUSED = false, bool PERM = false, bool CARRY = false>
; __device__ __forceinline__ void gemm_phase(LAS unsigned char* lds, const int tid, const int K, const int lda, const int ldb, const Sched& S, const Epi& E) {
;     ...
;             PG8_WAIT_V(8); PG8_WAIT_L(0); PG8_BAR; PG8_MMA(1, 0, At, B0); PG8_MMA(1, 1, At, B1); PG8_BAR; PG8_SCHED;
;             PG8_LDB(B0, 1, 0); PG8_LDB(B1, 1, 1); PG8_SCHED; PG8_LDA(At, 1, 0); PG8_STAGE(PG8_SA(0, 1), a2 + hstepA, voffA);
;             PG8_WAIT_V(8); PG8_WAIT_L(0); PG8_BAR; PG8_MMA(0, 0, At, B0); PG8_MMA(0, 1, At, B1); PG8_BAR; PG8_SCHED;
	s_setprio 1
	v_mfma_f32_16x16x32_bf16 v[62:65], v[146:149], v[178:181], v[62:65]
	v_mfma_f32_16x16x32_bf16 v[58:61], v[154:157], v[178:181], v[58:61]
	v_mfma_f32_16x16x32_bf16 v[54:57], v[146:149], v[186:189], v[54:57]
	v_mfma_f32_16x16x32_bf16 v[46:49], v[154:157], v[186:189], v[46:49]
	v_mfma_f32_16x16x32_bf16 v[38:41], v[146:149], v[194:197], v[38:41]
	v_mfma_f32_16x16x32_bf16 v[30:33], v[154:157], v[194:197], v[30:33]
	v_mfma_f32_16x16x32_bf16 v[22:25], v[146:149], v[202:205], v[22:25]
	v_mfma_f32_16x16x32_bf16 v[14:17], v[154:157], v[202:205], v[14:17]
	v_mfma_f32_16x16x32_bf16 v[62:65], v[150:153], v[182:185], v[62:65]
	v_mfma_f32_16x16x32_bf16 v[58:61], v[158:161], v[182:185], v[58:61]
	v_mfma_f32_16x16x32_bf16 v[54:57], v[150:153], v[190:193], v[54:57]
	v_mfma_f32_16x16x32_bf16 v[46:49], v[158:161], v[190:193], v[46:49]
	v_mfma_f32_16x16x32_bf16 v[38:41], v[150:153], v[198:201], v[38:41]
	v_mfma_f32_16x16x32_bf16 v[30:33], v[158:161], v[198:201], v[30:33]
	v_mfma_f32_16x16x32_bf16 v[22:25], v[150:153], v[206:209], v[22:25]
	v_mfma_f32_16x16x32_bf16 v[14:17], v[158:161], v[206:209], v[14:17]
	s_setprio 0
	s_setprio 1
	v_mfma_f32_16x16x32_bf16 v[50:53], v[162:165], v[178:181], v[50:53]
	v_mfma_f32_16x16x32_bf16 v[42:45], v[170:173], v[178:181], v[42:45]
	v_mfma_f32_16x16x32_bf16 v[34:37], v[162:165], v[186:189], v[34:37]
	v_mfma_f32_16x16x32_bf16 v[26:29], v[170:173], v[186:189], v[26:29]
	v_mfma_f32_16x16x32_bf16 v[18:21], v[162:165], v[194:197], v[18:21]
	v_mfma_f32_16x16x32_bf16 v[10:13], v[170:173], v[194:197], v[10:13]
	v_mfma_f32_16x16x32_bf16 v[6:9], v[162:165], v[202:205], v[6:9]
	v_mfma_f32_16x16x32_bf16 v[2:5], v[170:173], v[202:205], v[2:5]
	v_mfma_f32_16x16x32_bf16 v[50:53], v[166:169], v[182:185], v[50:53]
	v_mfma_f32_16x16x32_bf16 v[42:45], v[174:177], v[182:185], v[42:45]
	v_mfma_f32_16x16x32_bf16 v[34:37], v[166:169], v[190:193], v[34:37]
	v_mfma_f32_16x16x32_bf16 v[26:29], v[174:177], v[190:193], v[26:29]
	v_mfma_f32_16x16x32_bf16 v[18:21], v[166:169], v[198:201], v[18:21]
	v_mfma_f32_16x16x32_bf16 v[10:13], v[174:177], v[198:201], v[10:13]
	v_mfma_f32_16x16x32_bf16 v[6:9], v[166:169], v[206:209], v[6:9]
	v_mfma_f32_16x16x32_bf16 v[2:5], v[174:177], v[206:209], v[2:5]
	s_setprio 0
	s_barrier
	s_add_i32 s54, 0, 0x18000
	s_add_i32 s55, 0, 0x1c000
	v_add_u32_e32 v158, s54, v144
	v_add_u32_e32 v174, s55, v144
	ds_read_b128 v[146:149], v158
	ds_read_b128 v[150:153], v158 offset:1024
	ds_read_b128 v[154:157], v158 offset:2048
	ds_read_b128 v[158:161], v158 offset:3072
	ds_read_b128 v[162:165], v174
	ds_read_b128 v[166:169], v174 offset:1024
	ds_read_b128 v[170:173], v174 offset:2048
	ds_read_b128 v[174:177], v174 offset:3072
	s_add_u32 s26, s38, 0x180000
	s_addc_u32 s27, s39, 0
	s_mov_b32 m0, s43
	v_lshl_add_u64 v[216:217], s[26:27], 0, v[134:135]
	ds_read_b128 v[178:181], v145 offset:32768
	ds_read_b128 v[182:185], v145 offset:33792
	ds_read_b128 v[186:189], v145 offset:34816
	ds_read_b128 v[190:193], v145 offset:35840
	ds_read_b128 v[194:197], v145 offset:36864
	ds_read_b128 v[198:201], v145 offset:37888
	ds_read_b128 v[202:205], v145 offset:38912
	ds_read_b128 v[206:209], v145 offset:39936
	global_load_lds_dwordx4 v[216:217], off
	v_lshl_add_u64 v[216:217], s[26:27], 0, v[132:133]
	s_mov_b32 m0, s44
	s_nop 0
	global_load_lds_dwordx4 v[216:217], off
	s_waitcnt vmcnt(8)
	s_waitcnt lgkmcnt(0)
	s_barrier
	s_setprio 1
	v_mfma_f32_16x16x32_bf16 v[126:129], v[146:149], v[178:181], v[126:129]
	v_mfma_f32_16x16x32_bf16 v[122:125], v[154:157], v[178:181], v[122:125]
	v_mfma_f32_16x16x32_bf16 v[118:121], v[146:149], v[186:189], v[118:121]
	v_mfma_f32_16x16x32_bf16 v[110:113], v[154:157], v[186:189], v[110:113]
	v_mfma_f32_16x16x32_bf16 v[102:105], v[146:149], v[194:197], v[102:105]
	v_mfma_f32_16x16x32_bf16 v[94:97], v[154:157], v[194:197], v[94:97]
	v_mfma_f32_16x16x32_bf16 v[86:89], v[146:149], v[202:205], v[86:89]
	v_mfma_f32_16x16x32_bf16 v[78:81], v[154:157], v[202:205], v[78:81]
	v_mfma_f32_16x16x32_bf16 v[126:129], v[150:153], v[182:185], v[126:129]
	v_mfma_f32_16x16x32_bf16 v[122:125], v[158:161], v[182:185], v[122:125]
	v_mfma_f32_16x16x32_bf16 v[118:121], v[150:153], v[190:193], v[118:121]
	v_mfma_f32_16x16x32_bf16 v[110:113], v[158:161], v[190:193], v[110:113]
	v_mfma_f32_16x16x32_bf16 v[102:105], v[150:153], v[198:201], v[102:105]
	v_mfma_f32_16x16x32_bf16 v[94:97], v[158:161], v[198:201], v[94:97]
	v_mfma_f32_16x16x32_bf16 v[86:89], v[150:153], v[206:209], v[86:89]
	v_mfma_f32_16x16x32_bf16 v[78:81], v[158:161], v[206:209], v[78:81]
	s_setprio 0
	s_setprio 1
	v_mfma_f32_16x16x32_bf16 v[114:117], v[162:165], v[178:181], v[114:117]
	v_mfma_f32_16x16x32_bf16 v[106:109], v[170:173], v[178:181], v[106:109]
	v_mfma_f32_16x16x32_bf16 v[98:101], v[162:165], v[186:189], v[98:101]
	v_mfma_f32_16x16x32_bf16 v[90:93], v[170:173], v[186:189], v[90:93]
	v_mfma_f32_16x16x32_bf16 v[82:85], v[162:165], v[194:197], v[82:85]
	v_mfma_f32_16x16x32_bf16 v[74:77], v[170:173], v[194:197], v[74:77]
	v_mfma_f32_16x16x32_bf16 v[70:73], v[162:165], v[202:205], v[70:73]
	v_mfma_f32_16x16x32_bf16 v[66:69], v[170:173], v[202:205], v[66:69]
	v_mfma_f32_16x16x32_bf16 v[114:117], v[166:169], v[182:185], v[114:117]
	v_mfma_f32_16x16x32_bf16 v[106:109], v[174:177], v[182:185], v[106:109]
	v_mfma_f32_16x16x32_bf16 v[98:101], v[166:169], v[190:193], v[98:101]
	v_mfma_f32_16x16x32_bf16 v[90:93], v[174:177], v[190:193], v[90:93]
	v_mfma_f32_16x16x32_bf16 v[82:85], v[166:169], v[198:201], v[82:85]
	v_mfma_f32_16x16x32_bf16 v[74:77], v[174:177], v[198:201], v[74:77]
	v_mfma_f32_16x16x32_bf16 v[70:73], v[166:169], v[206:209], v[70:73]
	v_mfma_f32_16x16x32_bf16 v[66:69], v[174:177], v[206:209], v[66:69]
	s_setprio 0
	s_barrier
; #define PG8_STAGE(bufoff, gbase, voff) do { _Pragma("unroll") for (int _i = 0; _i < 2; ++_i) \
;         __builtin_amdgcn_global_load_lds((const unsigned*)((const char*)(gbase) + (voff)[_i]), (LAS unsigned*)(lds + (bufoff) + ldsw + _i * 8192), 16, 0, 0); } while (0)
; #define PG8_LDA(dst, b, h) do { _Pragma("unroll") for (int m = 0; m < 4; ++m) _Pragma("unroll") for (int k = 0; k < 2; ++k) dst[m][k] = *(const LAS bf16x8*)(lds + PG8_SA(b, h) + aoff + m * 2048 + k * 1024); } while (0)
; #define PG8_MMA(ai, bj, At, Bt) do { __builtin_amdgcn_s_setprio(1); _Pragma("unroll") for (int m = 0; m < 4; ++m) _Pragma("unroll") for (int n = 0; n < 2; ++n) _Pragma("unroll") for (int k = 0; k < 2; ++k) \
;         acc[ai][bj][m][n] = __builtin_amdgcn_mfma_f32_16x16x32_bf16(Bt[n][k], At[m][k], acc[ai][bj][m][n], 0, 0, 0); __builtin_amdgcn_s_setprio(0); } while (0)
; #define PG8_WAIT_V(n) asm volatile("s_waitcnt vmcnt(" #n ")" ::: "memory")
; #define PG8_WAIT_L(n) asm volatile("s_waitcnt lgkmcnt(" #n ")" ::: "memory")
; #define PG8_BAR __builtin_amdgcn_s_barrier()
; #define PG8_SCHED __builtin_amdgcn_sched_barrier(0)
; template <class Epi, class Sched, bool ALIGN_EPI, bool LAST_FUSED = false, bool PERM = false, bool CARRY = false>
; __device__ __forceinline__ void gemm_phase(LAS unsigned char* lds, const int tid, const int K, const int lda, const int ldb, const Sched& S, const Epi& E) {
;     ...
;             PG8_LDA(At, 1, 1); PG8_STAGE(PG8_SB(1, 0), b3, voffB); PG8_STAGE(PG8_SB(1, 1), b3 + hstepB, voffB); PG8_STAGE(PG8_SA(1, 0), a3, voffA);
;             PG8_WAIT_V(8); PG8_WAIT_L(0); PG8_BAR; PG8_MMA(1, 0, At, B0); PG8_MMA(1, 1, At, B1); PG8_BAR; PG8_SCHED;
;         }
;         if constexpr (ALIGN_EPI) { if (wr == 0) PG8_BAR; }
	s_add_i32 s26, s54, s40
	v_lshl_add_u64 v[140:141], v[140:141], 0, s[68:69]
	s_mov_b32 m0, s26
	ds_read_b128 v[178:181], v145 offset:49152
	ds_read_b128 v[182:185], v145 offset:50176
	ds_read_b128 v[186:189], v145 offset:51200
	ds_read_b128 v[190:193], v145 offset:52224
	ds_read_b128 v[194:197], v145 offset:53248
	ds_read_b128 v[198:201], v145 offset:54272
	ds_read_b128 v[202:205], v145 offset:55296
	ds_read_b128 v[206:209], v145 offset:56320
	global_load_lds_dwordx4 v[140:141], off
	s_add_i32 m0, s26, 0x2000
	s_add_u32 s26, s36, 0x30080
	v_lshl_add_u64 v[140:141], v[210:211], 0, s[68:69]
	s_addc_u32 s27, s37, 0
	s_add_i32 s36, s55, s40
	global_load_lds_dwordx4 v[140:141], off
	v_lshl_add_u64 v[140:141], s[26:27], 0, v[0:1]
	s_mov_b32 m0, s36
	s_nop 0
	global_load_lds_dwordx4 v[140:141], off
	v_lshl_add_u64 v[140:141], s[26:27], 0, v[130:131]
	s_add_i32 m0, s36, 0x2000
	s_nop 0
	global_load_lds_dwordx4 v[140:141], off
	v_lshl_add_u64 v[140:141], v[212:213], 0, s[68:69]
	s_mov_b32 m0, s46
	s_nop 0
	global_load_lds_dwordx4 v[140:141], off
	v_lshl_add_u64 v[140:141], v[214:215], 0, s[68:69]
	s_mov_b32 m0, s47
	s_nop 0
	global_load_lds_dwordx4 v[140:141], off
	s_waitcnt vmcnt(8)
	s_waitcnt lgkmcnt(0)
	s_barrier
	s_setprio 1
	v_mfma_f32_16x16x32_bf16 v[62:65], v[146:149], v[178:181], v[62:65]
	v_mfma_f32_16x16x32_bf16 v[58:61], v[154:157], v[178:181], v[58:61]
	v_mfma_f32_16x16x32_bf16 v[54:57], v[146:149], v[186:189], v[54:57]
	v_mfma_f32_16x16x32_bf16 v[46:49], v[154:157], v[186:189], v[46:49]
	v_mfma_f32_16x16x32_bf16 v[38:41], v[146:149], v[194:197], v[38:41]
	v_mfma_f32_16x16x32_bf16 v[30:33], v[154:157], v[194:197], v[30:33]
	v_mfma_f32_16x16x32_bf16 v[22:25], v[146:149], v[202:205], v[22:25]
	v_mfma_f32_16x16x32_bf16 v[14:17], v[154:157], v[202:205], v[14:17]
	v_mfma_f32_16x16x32_bf16 v[62:65], v[150:153], v[182:185], v[62:65]
	v_mfma_f32_16x16x32_bf16 v[58:61], v[158:161], v[182:185], v[58:61]
	v_mfma_f32_16x16x32_bf16 v[54:57], v[150:153], v[190:193], v[54:57]
	v_mfma_f32_16x16x32_bf16 v[46:49], v[158:161], v[190:193], v[46:49]
	v_mfma_f32_16x16x32_bf16 v[38:41], v[150:153], v[198:201], v[38:41]
	v_mfma_f32_16x16x32_bf16 v[30:33], v[158:161], v[198:201], v[30:33]
	v_mfma_f32_16x16x32_bf16 v[22:25], v[150:153], v[206:209], v[22:25]
	v_mfma_f32_16x16x32_bf16 v[14:17], v[158:161], v[206:209], v[14:17]
	s_setprio 0
	s_setprio 1
	v_mfma_f32_16x16x32_bf16 v[50:53], v[162:165], v[178:181], v[50:53]
	v_mfma_f32_16x16x32_bf16 v[42:45], v[170:173], v[178:181], v[42:45]
	v_mfma_f32_16x16x32_bf16 v[34:37], v[162:165], v[186:189], v[34:37]
	v_mfma_f32_16x16x32_bf16 v[26:29], v[170:173], v[186:189], v[26:29]
	v_mfma_f32_16x16x32_bf16 v[18:21], v[162:165], v[194:197], v[18:21]
	v_mfma_f32_16x16x32_bf16 v[10:13], v[170:173], v[194:197], v[10:13]
	v_mfma_f32_16x16x32_bf16 v[6:9], v[162:165], v[202:205], v[6:9]
	v_mfma_f32_16x16x32_bf16 v[2:5], v[170:173], v[202:205], v[2:5]
	v_mfma_f32_16x16x32_bf16 v[50:53], v[166:169], v[182:185], v[50:53]
	v_mfma_f32_16x16x32_bf16 v[42:45], v[174:177], v[182:185], v[42:45]
	v_mfma_f32_16x16x32_bf16 v[34:37], v[166:169], v[190:193], v[34:37]
	v_mfma_f32_16x16x32_bf16 v[26:29], v[174:177], v[190:193], v[26:29]
	v_mfma_f32_16x16x32_bf16 v[18:21], v[166:169], v[198:201], v[18:21]
	v_mfma_f32_16x16x32_bf16 v[10:13], v[174:177], v[198:201], v[10:13]
	v_mfma_f32_16x16x32_bf16 v[6:9], v[166:169], v[206:209], v[6:9]
	v_mfma_f32_16x16x32_bf16 v[2:5], v[174:177], v[206:209], v[2:5]
	s_setprio 0
	s_barrier
	s_add_i32 s53, s53, 2
	s_add_u32 s13, s13, 0x100
	s_addc_u32 s52, s52, 0
	s_cmp_gt_u32 s53, 9
	s_mov_b64 s[26:27], s[30:31]
	s_cbranch_scc0 .LBB0_705
	s_and_b64 vcc, exec, s[10:11]
	s_cbranch_vccz .LBB0_708
	s_barrier

; #define PG8_STAGE(bufoff, gbase, voff) do { _Pragma("unroll") for (int _i = 0; _i < 2; ++_i) \
;         __builtin_amdgcn_global_load_lds((const unsigned*)((const char*)(gbase) + (voff)[_i]), (LAS unsigned*)(lds + (bufoff) + ldsw + _i * 8192), 16, 0, 0); } while (0)
; #define PG8_LDA(dst, b, h) do { _Pragma("unroll") for (int m = 0; m < 4; ++m) _Pragma("unroll") for (int k = 0; k < 2; ++k) dst[m][k] = *(const LAS bf16x8*)(lds + PG8_SA(b, h) + aoff + m * 2048 + k * 1024); } while (0)
; #define PG8_LDB(dst, b, h) do { _Pragma("unroll") for (int n = 0; n < 2; ++n) _Pragma("unroll") for (int k = 0; k < 2; ++k) dst[n][k] = *(const LAS bf16x8*)(lds + PG8_SB(b, h) + boff + n * 2048 + k * 1024); } while (0)
; #define PG8_MMA(ai, bj, At, Bt) do { __builtin_amdgcn_s_setprio(1); _Pragma("unroll") for (int m = 0; m < 4; ++m) _Pragma("unroll") for (int n = 0; n < 2; ++n) _Pragma("unroll") for (int k = 0; k < 2; ++k) \
;         acc[ai][bj][m][n] = __builtin_amdgcn_mfma_f32_16x16x32_bf16(Bt[n][k], At[m][k], acc[ai][bj][m][n], 0, 0, 0); __builtin_amdgcn_s_setprio(0); } while (0)
; #define PG8_WAIT_V(n) asm volatile("s_waitcnt vmcnt(" #n ")" ::: "memory")
; #define PG8_WAIT_L(n) asm volatile("s_waitcnt lgkmcnt(" #n ")" ::: "memory")
; #define PG8_BAR __builtin_amdgcn_s_barrier()
; template <class Epi, class Sched, bool ALIGN_EPI, bool LAST_FUSED = false, bool PERM = false, bool CARRY = false>
; __device__ __forceinline__ void gemm_phase(LAS unsigned char* lds, const int tid, const int K, const int lda, const int ldb, const Sched& S, const Epi& E) {
;     ...
;             const bool last = (t == nt - 2);
;             const char* a1 = cA + (size_t)(t + 1) * kstep;
;             const char* a2 = last ? nA : cA + (size_t)(t + 2) * kstep; const char* b2 = last ? nB : cB + (size_t)(t + 2) * kstep;
;             const char* a3 = a2 + kstep; const char* b3 = b2 + kstep;
;             PG8_LDB(B0, 0, 0); PG8_LDB(B1, 0, 1); PG8_SCHED; PG8_LDA(At, 0, 0); PG8_STAGE(PG8_SA(1, 1), a1 + hstepA, voffA);
;             PG8_WAIT_V(8); PG8_WAIT_L(0); PG8_BAR; PG8_MMA(0, 0, At, B0); PG8_MMA(0, 1, At, B1); PG8_BAR; PG8_SCHED;
;             PG8_LDA(At, 0, 1); PG8_STAGE(PG8_SB(0, 0), b2, voffB); PG8_STAGE(PG8_SB(0, 1), b2 + hstepB, voffB); PG8_STAGE(PG8_SA(0, 0), a2, voffA);
;             PG8_WAIT_V(8); PG8_WAIT_L(0); PG8_BAR; PG8_MMA(1, 0, At, B0); PG8_MMA(1, 1, At, B1); PG8_BAR; PG8_SCHED;
.LBB0_838:
	s_add_u32 s6, s4, 0xfff80080
	s_addc_u32 s7, s5, -1
	s_add_i32 s29, 0, 0x10000
	s_cmp_eq_u32 s28, 28
	s_cselect_b32 s37, s43, s7
	s_cselect_b32 s36, s42, s6
	v_add_u32_e32 v140, s29, v146
	s_cselect_b32 s7, s71, s23
	s_cselect_b32 s6, s70, s22
	s_add_i32 s31, 0, 0x14000
	ds_read_b128 v[136:139], v140
	ds_read_b128 v[148:151], v140 offset:1024
	ds_read_b128 v[152:155], v140 offset:2048
	ds_read_b128 v[156:159], v140 offset:3072
	v_add_u32_e32 v140, s31, v146
	ds_read_b128 v[160:163], v140
	ds_read_b128 v[164:167], v140 offset:1024
	ds_read_b128 v[168:171], v140 offset:2048
	ds_read_b128 v[172:175], v140 offset:3072
	v_lshl_add_u64 v[140:141], s[4:5], 0, v[132:133]
	s_add_i32 m0, s50, 0xc000
	ds_read_b128 v[176:179], v147
	ds_read_b128 v[180:183], v147 offset:1024
	ds_read_b128 v[184:187], v147 offset:2048
	ds_read_b128 v[188:191], v147 offset:3072
	ds_read_b128 v[192:195], v147 offset:4096
	ds_read_b128 v[196:199], v147 offset:5120
	ds_read_b128 v[200:203], v147 offset:6144
	ds_read_b128 v[204:207], v147 offset:7168
	global_load_lds_dwordx4 v[140:141], off
	v_lshl_add_u64 v[140:141], s[4:5], 0, v[134:135]
	s_add_i32 m0, s50, 0xe000
	s_nop 0
	global_load_lds_dwordx4 v[140:141], off
	s_waitcnt vmcnt(8)
	s_waitcnt lgkmcnt(0)
	s_barrier
	s_setprio 1
	v_mfma_f32_16x16x32_bf16 v[126:129], v[136:139], v[176:179], v[126:129]
	v_mfma_f32_16x16x32_bf16 v[122:125], v[152:155], v[176:179], v[122:125]
	v_mfma_f32_16x16x32_bf16 v[110:113], v[136:139], v[184:187], v[110:113]
	v_mfma_f32_16x16x32_bf16 v[106:109], v[152:155], v[184:187], v[106:109]
	v_mfma_f32_16x16x32_bf16 v[94:97], v[136:139], v[192:195], v[94:97]
	v_mfma_f32_16x16x32_bf16 v[90:93], v[152:155], v[192:195], v[90:93]
	v_mfma_f32_16x16x32_bf16 v[78:81], v[136:139], v[200:203], v[78:81]
	v_mfma_f32_16x16x32_bf16 v[74:77], v[152:155], v[200:203], v[74:77]
	v_mfma_f32_16x16x32_bf16 v[126:129], v[148:151], v[180:183], v[126:129]
	v_mfma_f32_16x16x32_bf16 v[122:125], v[156:159], v[180:183], v[122:125]
	v_mfma_f32_16x16x32_bf16 v[110:113], v[148:151], v[188:191], v[110:113]
	v_mfma_f32_16x16x32_bf16 v[106:109], v[156:159], v[188:191], v[106:109]
	v_mfma_f32_16x16x32_bf16 v[94:97], v[148:151], v[196:199], v[94:97]
	v_mfma_f32_16x16x32_bf16 v[90:93], v[156:159], v[196:199], v[90:93]
	v_mfma_f32_16x16x32_bf16 v[78:81], v[148:151], v[204:207], v[78:81]
	v_mfma_f32_16x16x32_bf16 v[74:77], v[156:159], v[204:207], v[74:77]
	s_setprio 0
	s_setprio 1
	v_mfma_f32_16x16x32_bf16 v[118:121], v[160:163], v[176:179], v[118:121]
	v_mfma_f32_16x16x32_bf16 v[114:117], v[168:171], v[176:179], v[114:117]
	v_mfma_f32_16x16x32_bf16 v[102:105], v[160:163], v[184:187], v[102:105]
	v_mfma_f32_16x16x32_bf16 v[98:101], v[168:171], v[184:187], v[98:101]
	v_mfma_f32_16x16x32_bf16 v[86:89], v[160:163], v[192:195], v[86:89]
	v_mfma_f32_16x16x32_bf16 v[82:85], v[168:171], v[192:195], v[82:85]
	v_mfma_f32_16x16x32_bf16 v[70:73], v[160:163], v[200:203], v[70:73]
	v_mfma_f32_16x16x32_bf16 v[66:69], v[168:171], v[200:203], v[66:69]
	v_mfma_f32_16x16x32_bf16 v[118:121], v[164:167], v[180:183], v[118:121]
	v_mfma_f32_16x16x32_bf16 v[114:117], v[172:175], v[180:183], v[114:117]
	v_mfma_f32_16x16x32_bf16 v[102:105], v[164:167], v[188:191], v[102:105]
	v_mfma_f32_16x16x32_bf16 v[98:101], v[172:175], v[188:191], v[98:101]
	v_mfma_f32_16x16x32_bf16 v[86:89], v[164:167], v[196:199], v[86:89]
	v_mfma_f32_16x16x32_bf16 v[82:85], v[172:175], v[196:199], v[82:85]
	v_mfma_f32_16x16x32_bf16 v[70:73], v[164:167], v[204:207], v[70:73]
	v_mfma_f32_16x16x32_bf16 v[66:69], v[172:175], v[204:207], v[66:69]
	s_setprio 0
	s_barrier
	s_add_i32 s29, s29, s49
	v_lshl_add_u64 v[140:141], s[6:7], 0, v[0:1]
	s_mov_b32 m0, s29
	ds_read_b128 v[176:179], v147 offset:16384
	ds_read_b128 v[180:183], v147 offset:17408
	ds_read_b128 v[184:187], v147 offset:18432
	ds_read_b128 v[188:191], v147 offset:19456
	ds_read_b128 v[192:195], v147 offset:20480
	ds_read_b128 v[196:199], v147 offset:21504
	ds_read_b128 v[200:203], v147 offset:22528
	ds_read_b128 v[204:207], v147 offset:23552
	global_load_lds_dwordx4 v[140:141], off
	s_add_i32 m0, s29, 0x2000
	s_add_u32 s44, s6, 0x80000
	v_lshl_add_u64 v[208:209], s[6:7], 0, v[130:131]
	s_addc_u32 s45, s7, 0
	s_add_i32 s29, s31, s49
	global_load_lds_dwordx4 v[208:209], off
	v_lshl_add_u64 v[210:211], s[44:45], 0, v[0:1]
	s_mov_b32 m0, s29
	v_lshl_add_u64 v[212:213], s[36:37], 0, v[130:131]
	global_load_lds_dwordx4 v[210:211], off
	v_lshl_add_u64 v[210:211], s[44:45], 0, v[130:131]
	s_add_i32 m0, s29, 0x2000
	s_nop 0
	global_load_lds_dwordx4 v[210:211], off
	v_lshl_add_u64 v[210:211], s[36:37], 0, v[0:1]
	s_mov_b32 m0, s50
	s_nop 0
	global_load_lds_dwordx4 v[210:211], off
	s_mov_b32 m0, s51
	s_nop 0
	global_load_lds_dwordx4 v[212:213], off
	s_waitcnt vmcnt(8)
	s_waitcnt lgkmcnt(0)
	s_barrier
; #define PG8_STAGE(bufoff, gbase, voff) do { _Pragma("unroll") for (int _i = 0; _i < 2; ++_i) \
;         __builtin_amdgcn_global_load_lds((const unsigned*)((const char*)(gbase) + (voff)[_i]), (LAS unsigned*)(lds + (bufoff) + ldsw + _i * 8192), 16, 0, 0); } while (0)
; #define PG8_LDA(dst, b, h) do { _Pragma("unroll") for (int m = 0; m < 4; ++m) _Pragma("unroll") for (int k = 0; k < 2; ++k) dst[m][k] = *(const LAS bf16x8*)(lds + PG8_SA(b, h) + aoff + m * 2048 + k * 1024); } while (0)
; #define PG8_LDB(dst, b, h) do { _Pragma("unroll") for (int n = 0; n < 2; ++n) _Pragma("unroll") for (int k = 0; k < 2; ++k) dst[n][k] = *(const LAS bf16x8*)(lds + PG8_SB(b, h) + boff + n * 2048 + k * 1024); } while (0)
; #define PG8_MMA(ai, bj, At, Bt) do { __builtin_amdgcn_s_setprio(1); _Pragma("unroll") for (int m = 0; m < 4; ++m) _Pragma("unroll") for (int n = 0; n < 2; ++n) _Pragma("unroll") for (int k = 0; k < 2; ++k) \
;         acc[ai][bj][m][n] = __builtin_amdgcn_mfma_f32_16x16x32_bf16(Bt[n][k], At[m][k], acc[ai][bj][m][n], 0, 0, 0); __builtin_amdgcn_s_setprio(0); } while (0)
; #define PG8_WAIT_V(n) asm volatile("s_waitcnt vmcnt(" #n ")" ::: "memory")
; #define PG8_WAIT_L(n) asm volatile("s_waitcnt lgkmcnt(" #n ")" ::: "memory")
; #define PG8_BAR __builtin_amdgcn_s_barrier()
; #define PG8_SCHED __builtin_amdgcn_sched_barrier(0)
; template <class Epi, class Sched, bool ALIGN_EPI, bool LAST_FUSED = false, bool PERM = false, bool CARRY = false>
; __device__ __forceinline__ void gemm_phase(LAS unsigned char* lds, const int tid, const int K, const int lda, const int ldb, const Sched& S, const Epi& E) {
;     ...
;             PG8_WAIT_V(8); PG8_WAIT_L(0); PG8_BAR; PG8_MMA(1, 0, At, B0); PG8_MMA(1, 1, At, B1); PG8_BAR; PG8_SCHED;
;             PG8_LDB(B0, 1, 0); PG8_LDB(B1, 1, 1); PG8_SCHED; PG8_LDA(At, 1, 0); PG8_STAGE(PG8_SA(0, 1), a2 + hstepA, voffA);
;             PG8_WAIT_V(8); PG8_WAIT_L(0); PG8_BAR; PG8_MMA(0, 0, At, B0); PG8_MMA(0, 1, At, B1); PG8_BAR; PG8_SCHED;
	s_setprio 1
	v_mfma_f32_16x16x32_bf16 v[62:65], v[136:139], v[176:179], v[62:65]
	v_mfma_f32_16x16x32_bf16 v[58:61], v[152:155], v[176:179], v[58:61]
	v_mfma_f32_16x16x32_bf16 v[46:49], v[136:139], v[184:187], v[46:49]
	v_mfma_f32_16x16x32_bf16 v[42:45], v[152:155], v[184:187], v[42:45]
	v_mfma_f32_16x16x32_bf16 v[30:33], v[136:139], v[192:195], v[30:33]
	v_mfma_f32_16x16x32_bf16 v[26:29], v[152:155], v[192:195], v[26:29]
	v_mfma_f32_16x16x32_bf16 v[14:17], v[136:139], v[200:203], v[14:17]
	v_mfma_f32_16x16x32_bf16 v[10:13], v[152:155], v[200:203], v[10:13]
	v_mfma_f32_16x16x32_bf16 v[62:65], v[148:151], v[180:183], v[62:65]
	v_mfma_f32_16x16x32_bf16 v[58:61], v[156:159], v[180:183], v[58:61]
	v_mfma_f32_16x16x32_bf16 v[46:49], v[148:151], v[188:191], v[46:49]
	v_mfma_f32_16x16x32_bf16 v[42:45], v[156:159], v[188:191], v[42:45]
	v_mfma_f32_16x16x32_bf16 v[30:33], v[148:151], v[196:199], v[30:33]
	v_mfma_f32_16x16x32_bf16 v[26:29], v[156:159], v[196:199], v[26:29]
	v_mfma_f32_16x16x32_bf16 v[14:17], v[148:151], v[204:207], v[14:17]
	v_mfma_f32_16x16x32_bf16 v[10:13], v[156:159], v[204:207], v[10:13]
	s_setprio 0
	s_setprio 1
	v_mfma_f32_16x16x32_bf16 v[54:57], v[160:163], v[176:179], v[54:57]
	v_mfma_f32_16x16x32_bf16 v[50:53], v[168:171], v[176:179], v[50:53]
	v_mfma_f32_16x16x32_bf16 v[38:41], v[160:163], v[184:187], v[38:41]
	v_mfma_f32_16x16x32_bf16 v[34:37], v[168:171], v[184:187], v[34:37]
	v_mfma_f32_16x16x32_bf16 v[22:25], v[160:163], v[192:195], v[22:25]
	v_mfma_f32_16x16x32_bf16 v[18:21], v[168:171], v[192:195], v[18:21]
	v_mfma_f32_16x16x32_bf16 v[6:9], v[160:163], v[200:203], v[6:9]
	v_mfma_f32_16x16x32_bf16 v[2:5], v[168:171], v[200:203], v[2:5]
	v_mfma_f32_16x16x32_bf16 v[54:57], v[164:167], v[180:183], v[54:57]
	v_mfma_f32_16x16x32_bf16 v[50:53], v[172:175], v[180:183], v[50:53]
	v_mfma_f32_16x16x32_bf16 v[38:41], v[164:167], v[188:191], v[38:41]
	v_mfma_f32_16x16x32_bf16 v[34:37], v[172:175], v[188:191], v[34:37]
	v_mfma_f32_16x16x32_bf16 v[22:25], v[164:167], v[196:199], v[22:25]
	v_mfma_f32_16x16x32_bf16 v[18:21], v[172:175], v[196:199], v[18:21]
	v_mfma_f32_16x16x32_bf16 v[6:9], v[164:167], v[204:207], v[6:9]
	v_mfma_f32_16x16x32_bf16 v[2:5], v[172:175], v[204:207], v[2:5]
	s_setprio 0
	s_barrier
	s_add_i32 s29, 0, 0x18000
	s_add_i32 s31, 0, 0x1c000
	v_add_u32_e32 v156, s29, v146
	v_add_u32_e32 v172, s31, v146
	ds_read_b128 v[136:139], v156
	ds_read_b128 v[148:151], v156 offset:1024
	ds_read_b128 v[152:155], v156 offset:2048
	ds_read_b128 v[156:159], v156 offset:3072
	ds_read_b128 v[160:163], v172
	ds_read_b128 v[164:167], v172 offset:1024
	ds_read_b128 v[168:171], v172 offset:2048
	ds_read_b128 v[172:175], v172 offset:3072
	s_add_u32 s36, s36, 0x80000
	s_addc_u32 s37, s37, 0
	s_mov_b32 m0, s52
	v_lshl_add_u64 v[214:215], s[36:37], 0, v[0:1]
	ds_read_b128 v[176:179], v147 offset:32768
	ds_read_b128 v[180:183], v147 offset:33792
	ds_read_b128 v[184:187], v147 offset:34816
	ds_read_b128 v[188:191], v147 offset:35840
	ds_read_b128 v[192:195], v147 offset:36864
	ds_read_b128 v[196:199], v147 offset:37888
	ds_read_b128 v[200:203], v147 offset:38912
	ds_read_b128 v[204:207], v147 offset:39936
	global_load_lds_dwordx4 v[214:215], off
	v_lshl_add_u64 v[214:215], s[36:37], 0, v[130:131]
	s_mov_b32 m0, s53
	s_nop 0
	global_load_lds_dwordx4 v[214:215], off
	s_waitcnt vmcnt(8)
	s_waitcnt lgkmcnt(0)
	s_barrier
	s_setprio 1
	v_mfma_f32_16x16x32_bf16 v[126:129], v[136:139], v[176:179], v[126:129]
	v_mfma_f32_16x16x32_bf16 v[122:125], v[152:155], v[176:179], v[122:125]
	v_mfma_f32_16x16x32_bf16 v[110:113], v[136:139], v[184:187], v[110:113]
	v_mfma_f32_16x16x32_bf16 v[106:109], v[152:155], v[184:187], v[106:109]
	v_mfma_f32_16x16x32_bf16 v[94:97], v[136:139], v[192:195], v[94:97]
	v_mfma_f32_16x16x32_bf16 v[90:93], v[152:155], v[192:195], v[90:93]
	v_mfma_f32_16x16x32_bf16 v[78:81], v[136:139], v[200:203], v[78:81]
	v_mfma_f32_16x16x32_bf16 v[74:77], v[152:155], v[200:203], v[74:77]
	v_mfma_f32_16x16x32_bf16 v[126:129], v[148:151], v[180:183], v[126:129]
	v_mfma_f32_16x16x32_bf16 v[122:125], v[156:159], v[180:183], v[122:125]
	v_mfma_f32_16x16x32_bf16 v[110:113], v[148:151], v[188:191], v[110:113]
	v_mfma_f32_16x16x32_bf16 v[106:109], v[156:159], v[188:191], v[106:109]
	v_mfma_f32_16x16x32_bf16 v[94:97], v[148:151], v[196:199], v[94:97]
	v_mfma_f32_16x16x32_bf16 v[90:93], v[156:159], v[196:199], v[90:93]
	v_mfma_f32_16x16x32_bf16 v[78:81], v[148:151], v[204:207], v[78:81]
	v_mfma_f32_16x16x32_bf16 v[74:77], v[156:159], v[204:207], v[74:77]
	s_setprio 0
	s_setprio 1
	v_mfma_f32_16x16x32_bf16 v[118:121], v[160:163], v[176:179], v[118:121]
	v_mfma_f32_16x16x32_bf16 v[114:117], v[168:171], v[176:179], v[114:117]
	v_mfma_f32_16x16x32_bf16 v[102:105], v[160:163], v[184:187], v[102:105]
	v_mfma_f32_16x16x32_bf16 v[98:101], v[168:171], v[184:187], v[98:101]
	v_mfma_f32_16x16x32_bf16 v[86:89], v[160:163], v[192:195], v[86:89]
	v_mfma_f32_16x16x32_bf16 v[82:85], v[168:171], v[192:195], v[82:85]
	v_mfma_f32_16x16x32_bf16 v[70:73], v[160:163], v[200:203], v[70:73]
	v_mfma_f32_16x16x32_bf16 v[66:69], v[168:171], v[200:203], v[66:69]
	v_mfma_f32_16x16x32_bf16 v[118:121], v[164:167], v[180:183], v[118:121]
	v_mfma_f32_16x16x32_bf16 v[114:117], v[172:175], v[180:183], v[114:117]
	v_mfma_f32_16x16x32_bf16 v[102:105], v[164:167], v[188:191], v[102:105]
	v_mfma_f32_16x16x32_bf16 v[98:101], v[172:175], v[188:191], v[98:101]
	v_mfma_f32_16x16x32_bf16 v[86:89], v[164:167], v[196:199], v[86:89]
	v_mfma_f32_16x16x32_bf16 v[82:85], v[172:175], v[196:199], v[82:85]
	v_mfma_f32_16x16x32_bf16 v[70:73], v[164:167], v[204:207], v[70:73]
	v_mfma_f32_16x16x32_bf16 v[66:69], v[172:175], v[204:207], v[66:69]
	s_setprio 0
	s_barrier
; #define PG8_STAGE(bufoff, gbase, voff) do { _Pragma("unroll") for (int _i = 0; _i < 2; ++_i) \
;         __builtin_amdgcn_global_load_lds((const unsigned*)((const char*)(gbase) + (voff)[_i]), (LAS unsigned*)(lds + (bufoff) + ldsw + _i * 8192), 16, 0, 0); } while (0)
; #define PG8_LDA(dst, b, h) do { _Pragma("unroll") for (int m = 0; m < 4; ++m) _Pragma("unroll") for (int k = 0; k < 2; ++k) dst[m][k] = *(const LAS bf16x8*)(lds + PG8_SA(b, h) + aoff + m * 2048 + k * 1024); } while (0)
; #define PG8_MMA(ai, bj, At, Bt) do { __builtin_amdgcn_s_setprio(1); _Pragma("unroll") for (int m = 0; m < 4; ++m) _Pragma("unroll") for (int n = 0; n < 2; ++n) _Pragma("unroll") for (int k = 0; k < 2; ++k) \
;         acc[ai][bj][m][n] = __builtin_amdgcn_mfma_f32_16x16x32_bf16(Bt[n][k], At[m][k], acc[ai][bj][m][n], 0, 0, 0); __builtin_amdgcn_s_setprio(0); } while (0)
; #define PG8_WAIT_V(n) asm volatile("s_waitcnt vmcnt(" #n ")" ::: "memory")
; #define PG8_WAIT_L(n) asm volatile("s_waitcnt lgkmcnt(" #n ")" ::: "memory")
; #define PG8_BAR __builtin_amdgcn_s_barrier()
; #define PG8_SCHED __builtin_amdgcn_sched_barrier(0)
; template <class Epi, class Sched, bool ALIGN_EPI, bool LAST_FUSED = false, bool PERM = false, bool CARRY = false>
; __device__ __forceinline__ void gemm_phase(LAS unsigned char* lds, const int tid, const int K, const int lda, const int ldb, const Sched& S, const Epi& E) {
;     ...
;             PG8_LDA(At, 1, 1); PG8_STAGE(PG8_SB(1, 0), b3, voffB); PG8_STAGE(PG8_SB(1, 1), b3 + hstepB, voffB); PG8_STAGE(PG8_SA(1, 0), a3, voffA);
;             PG8_WAIT_V(8); PG8_WAIT_L(0); PG8_BAR; PG8_MMA(1, 0, At, B0); PG8_MMA(1, 1, At, B1); PG8_BAR; PG8_SCHED;
;         }
;         if constexpr (ALIGN_EPI) { if (wr == 0) PG8_BAR; }
	s_add_i32 s29, s29, s49
	v_lshl_add_u64 v[140:141], v[140:141], 0, s[68:69]
	s_mov_b32 m0, s29
	ds_read_b128 v[176:179], v147 offset:49152
	ds_read_b128 v[180:183], v147 offset:50176
	ds_read_b128 v[184:187], v147 offset:51200
	ds_read_b128 v[188:191], v147 offset:52224
	ds_read_b128 v[192:195], v147 offset:53248
	ds_read_b128 v[196:199], v147 offset:54272
	ds_read_b128 v[200:203], v147 offset:55296
	ds_read_b128 v[204:207], v147 offset:56320
	global_load_lds_dwordx4 v[140:141], off
	s_add_i32 m0, s29, 0x2000
	s_add_u32 s6, s6, 0x80080
	v_lshl_add_u64 v[140:141], v[208:209], 0, s[68:69]
	s_addc_u32 s7, s7, 0
	s_add_i32 s29, s31, s49
	global_load_lds_dwordx4 v[140:141], off
	v_lshl_add_u64 v[140:141], s[6:7], 0, v[0:1]
	s_mov_b32 m0, s29
	s_nop 0
	global_load_lds_dwordx4 v[140:141], off
	v_lshl_add_u64 v[140:141], s[6:7], 0, v[130:131]
	s_add_i32 m0, s29, 0x2000
	s_nop 0
	global_load_lds_dwordx4 v[140:141], off
	v_lshl_add_u64 v[140:141], v[210:211], 0, s[68:69]
	s_mov_b32 m0, s55
	s_nop 0
	global_load_lds_dwordx4 v[140:141], off
	v_lshl_add_u64 v[140:141], v[212:213], 0, s[68:69]
	s_mov_b32 m0, s56
	s_nop 0
	global_load_lds_dwordx4 v[140:141], off
	s_waitcnt vmcnt(8)
	s_waitcnt lgkmcnt(0)
	s_barrier
	s_setprio 1
	v_mfma_f32_16x16x32_bf16 v[62:65], v[136:139], v[176:179], v[62:65]
	v_mfma_f32_16x16x32_bf16 v[58:61], v[152:155], v[176:179], v[58:61]
	v_mfma_f32_16x16x32_bf16 v[46:49], v[136:139], v[184:187], v[46:49]
	v_mfma_f32_16x16x32_bf16 v[42:45], v[152:155], v[184:187], v[42:45]
	v_mfma_f32_16x16x32_bf16 v[30:33], v[136:139], v[192:195], v[30:33]
	v_mfma_f32_16x16x32_bf16 v[26:29], v[152:155], v[192:195], v[26:29]
	v_mfma_f32_16x16x32_bf16 v[14:17], v[136:139], v[200:203], v[14:17]
	v_mfma_f32_16x16x32_bf16 v[10:13], v[152:155], v[200:203], v[10:13]
	v_mfma_f32_16x16x32_bf16 v[62:65], v[148:151], v[180:183], v[62:65]
	v_mfma_f32_16x16x32_bf16 v[58:61], v[156:159], v[180:183], v[58:61]
	v_mfma_f32_16x16x32_bf16 v[46:49], v[148:151], v[188:191], v[46:49]
	v_mfma_f32_16x16x32_bf16 v[42:45], v[156:159], v[188:191], v[42:45]
	v_mfma_f32_16x16x32_bf16 v[30:33], v[148:151], v[196:199], v[30:33]
	v_mfma_f32_16x16x32_bf16 v[26:29], v[156:159], v[196:199], v[26:29]
	v_mfma_f32_16x16x32_bf16 v[14:17], v[148:151], v[204:207], v[14:17]
	v_mfma_f32_16x16x32_bf16 v[10:13], v[156:159], v[204:207], v[10:13]
	s_setprio 0
	s_setprio 1
	v_mfma_f32_16x16x32_bf16 v[54:57], v[160:163], v[176:179], v[54:57]
	v_mfma_f32_16x16x32_bf16 v[50:53], v[168:171], v[176:179], v[50:53]
	v_mfma_f32_16x16x32_bf16 v[38:41], v[160:163], v[184:187], v[38:41]
	v_mfma_f32_16x16x32_bf16 v[34:37], v[168:171], v[184:187], v[34:37]
	v_mfma_f32_16x16x32_bf16 v[22:25], v[160:163], v[192:195], v[22:25]
	v_mfma_f32_16x16x32_bf16 v[18:21], v[168:171], v[192:195], v[18:21]
	v_mfma_f32_16x16x32_bf16 v[6:9], v[160:163], v[200:203], v[6:9]
	v_mfma_f32_16x16x32_bf16 v[2:5], v[168:171], v[200:203], v[2:5]
	v_mfma_f32_16x16x32_bf16 v[54:57], v[164:167], v[180:183], v[54:57]
	v_mfma_f32_16x16x32_bf16 v[50:53], v[172:175], v[180:183], v[50:53]
	v_mfma_f32_16x16x32_bf16 v[38:41], v[164:167], v[188:191], v[38:41]
	v_mfma_f32_16x16x32_bf16 v[34:37], v[172:175], v[188:191], v[34:37]
	v_mfma_f32_16x16x32_bf16 v[22:25], v[164:167], v[196:199], v[22:25]
	v_mfma_f32_16x16x32_bf16 v[18:21], v[172:175], v[196:199], v[18:21]
	v_mfma_f32_16x16x32_bf16 v[6:9], v[164:167], v[204:207], v[6:9]
	v_mfma_f32_16x16x32_bf16 v[2:5], v[172:175], v[204:207], v[2:5]
	s_setprio 0
	s_barrier
	s_add_i32 s28, s28, 2
	s_add_u32 s4, s4, 0x100
	s_addc_u32 s5, s5, 0
	s_add_u32 s22, s22, 0x100
	s_addc_u32 s23, s23, 0
	s_cmp_gt_u32 s28, 29
	s_cbranch_scc0 .LBB0_838
	s_and_b64 vcc, exec, s[26:27]
	s_cbranch_vccz .LBB0_841
	s_barrier

; #define PG8_STAGE(bufoff, gbase, voff) do { _Pragma("unroll") for (int _i = 0; _i < 2; ++_i) \
;         __builtin_amdgcn_global_load_lds((const unsigned*)((const char*)(gbase) + (voff)[_i]), (LAS unsigned*)(lds + (bufoff) + ldsw + _i * 8192), 16, 0, 0); } while (0)
; #define PG8_LDA(dst, b, h) do { _Pragma("unroll") for (int m = 0; m < 4; ++m) _Pragma("unroll") for (int k = 0; k < 2; ++k) dst[m][k] = *(const LAS bf16x8*)(lds + PG8_SA(b, h) + aoff + m * 2048 + k * 1024); } while (0)
; #define PG8_LDB(dst, b, h) do { _Pragma("unroll") for (int n = 0; n < 2; ++n) _Pragma("unroll") for (int k = 0; k < 2; ++k) dst[n][k] = *(const LAS bf16x8*)(lds + PG8_SB(b, h) + boff + n * 2048 + k * 1024); } while (0)
; #define PG8_MMA(ai, bj, At, Bt) do { __builtin_amdgcn_s_setprio(1); _Pragma("unroll") for (int m = 0; m < 4; ++m) _Pragma("unroll") for (int n = 0; n < 2; ++n) _Pragma("unroll") for (int k = 0; k < 2; ++k) \
;         acc[ai][bj][m][n] = __builtin_amdgcn_mfma_f32_16x16x32_bf16(Bt[n][k], At[m][k], acc[ai][bj][m][n], 0, 0, 0); __builtin_amdgcn_s_setprio(0); } while (0)
; #define PG8_WAIT_V(n) asm volatile("s_waitcnt vmcnt(" #n ")" ::: "memory")
; #define PG8_WAIT_L(n) asm volatile("s_waitcnt lgkmcnt(" #n ")" ::: "memory")
; #define PG8_BAR __builtin_amdgcn_s_barrier()
; template <class Epi, class Sched, bool ALIGN_EPI, bool LAST_FUSED = false, bool PERM = false, bool CARRY = false>
; __device__ __forceinline__ void gemm_phase(LAS unsigned char* lds, const int tid, const int K, const int lda, const int ldb, const Sched& S, const Epi& E) {
;     ...
;             const bool last = (t == nt - 2);
;             const char* a1 = cA + (size_t)(t + 1) * kstep;
;             const char* a2 = last ? nA : cA + (size_t)(t + 2) * kstep; const char* b2 = last ? nB : cB + (size_t)(t + 2) * kstep;
;             const char* a3 = a2 + kstep; const char* b3 = b2 + kstep;
;             PG8_LDB(B0, 0, 0); PG8_LDB(B1, 0, 1); PG8_SCHED; PG8_LDA(At, 0, 0); PG8_STAGE(PG8_SA(1, 1), a1 + hstepA, voffA);
;             PG8_WAIT_V(8); PG8_WAIT_L(0); PG8_BAR; PG8_MMA(0, 0, At, B0); PG8_MMA(0, 1, At, B1); PG8_BAR; PG8_SCHED;
;             PG8_LDA(At, 0, 1); PG8_STAGE(PG8_SB(0, 0), b2, voffB); PG8_STAGE(PG8_SB(0, 1), b2 + hstepB, voffB); PG8_STAGE(PG8_SA(0, 0), a2, voffA);
;             PG8_WAIT_V(8); PG8_WAIT_L(0); PG8_BAR; PG8_MMA(1, 0, At, B0); PG8_MMA(1, 1, At, B1); PG8_BAR; PG8_SCHED;
.LBB0_1077:
	s_add_u32 s23, s26, 0xfff80080
	s_addc_u32 s28, s27, -1
	s_add_i32 s29, 0, 0x10000
	s_cmp_eq_u32 s15, 28
	s_cselect_b32 s37, s17, s28
	s_cselect_b32 s36, s16, s23
	s_cselect_b32 s31, s19, s13
	s_cselect_b32 s30, s18, s5
	s_add_i32 s23, 0, 0x14000
	v_add_u32_e32 v152, s29, v142
	v_add_u32_e32 v168, s23, v142
	ds_read_b128 v[136:139], v152
	ds_read_b128 v[144:147], v152 offset:1024
	ds_read_b128 v[148:151], v152 offset:2048
	ds_read_b128 v[152:155], v152 offset:3072
	ds_read_b128 v[156:159], v168
	ds_read_b128 v[160:163], v168 offset:1024
	ds_read_b128 v[164:167], v168 offset:2048
	ds_read_b128 v[168:171], v168 offset:3072
	v_lshl_add_u64 v[204:205], s[26:27], 0, v[132:133]
	s_add_i32 m0, s46, 0xc000
	ds_read_b128 v[172:175], v143
	ds_read_b128 v[176:179], v143 offset:1024
	ds_read_b128 v[180:183], v143 offset:2048
	ds_read_b128 v[184:187], v143 offset:3072
	ds_read_b128 v[188:191], v143 offset:4096
	ds_read_b128 v[192:195], v143 offset:5120
	ds_read_b128 v[196:199], v143 offset:6144
	ds_read_b128 v[200:203], v143 offset:7168
	global_load_lds_dwordx4 v[204:205], off
	v_lshl_add_u64 v[204:205], s[26:27], 0, v[134:135]
	s_add_i32 m0, s46, 0xe000
	s_nop 0
	global_load_lds_dwordx4 v[204:205], off
	s_waitcnt vmcnt(8)
	s_waitcnt lgkmcnt(0)
	s_barrier
	s_setprio 1
	v_mfma_f32_16x16x32_bf16 v[126:129], v[136:139], v[172:175], v[126:129]
	v_mfma_f32_16x16x32_bf16 v[122:125], v[148:151], v[172:175], v[122:125]
	v_mfma_f32_16x16x32_bf16 v[110:113], v[136:139], v[180:183], v[110:113]
	v_mfma_f32_16x16x32_bf16 v[106:109], v[148:151], v[180:183], v[106:109]
	v_mfma_f32_16x16x32_bf16 v[94:97], v[136:139], v[188:191], v[94:97]
	v_mfma_f32_16x16x32_bf16 v[90:93], v[148:151], v[188:191], v[90:93]
	v_mfma_f32_16x16x32_bf16 v[78:81], v[136:139], v[196:199], v[78:81]
	v_mfma_f32_16x16x32_bf16 v[74:77], v[148:151], v[196:199], v[74:77]
	v_mfma_f32_16x16x32_bf16 v[126:129], v[144:147], v[176:179], v[126:129]
	v_mfma_f32_16x16x32_bf16 v[122:125], v[152:155], v[176:179], v[122:125]
	v_mfma_f32_16x16x32_bf16 v[110:113], v[144:147], v[184:187], v[110:113]
	v_mfma_f32_16x16x32_bf16 v[106:109], v[152:155], v[184:187], v[106:109]
	v_mfma_f32_16x16x32_bf16 v[94:97], v[144:147], v[192:195], v[94:97]
	v_mfma_f32_16x16x32_bf16 v[90:93], v[152:155], v[192:195], v[90:93]
	v_mfma_f32_16x16x32_bf16 v[78:81], v[144:147], v[200:203], v[78:81]
	v_mfma_f32_16x16x32_bf16 v[74:77], v[152:155], v[200:203], v[74:77]
	s_setprio 0
	s_setprio 1
	v_mfma_f32_16x16x32_bf16 v[118:121], v[156:159], v[172:175], v[118:121]
	v_mfma_f32_16x16x32_bf16 v[114:117], v[164:167], v[172:175], v[114:117]
	v_mfma_f32_16x16x32_bf16 v[102:105], v[156:159], v[180:183], v[102:105]
	v_mfma_f32_16x16x32_bf16 v[98:101], v[164:167], v[180:183], v[98:101]
	v_mfma_f32_16x16x32_bf16 v[86:89], v[156:159], v[188:191], v[86:89]
	v_mfma_f32_16x16x32_bf16 v[82:85], v[164:167], v[188:191], v[82:85]
	v_mfma_f32_16x16x32_bf16 v[70:73], v[156:159], v[196:199], v[70:73]
	v_mfma_f32_16x16x32_bf16 v[66:69], v[164:167], v[196:199], v[66:69]
	v_mfma_f32_16x16x32_bf16 v[118:121], v[160:163], v[176:179], v[118:121]
	v_mfma_f32_16x16x32_bf16 v[114:117], v[168:171], v[176:179], v[114:117]
	v_mfma_f32_16x16x32_bf16 v[102:105], v[160:163], v[184:187], v[102:105]
	v_mfma_f32_16x16x32_bf16 v[98:101], v[168:171], v[184:187], v[98:101]
	v_mfma_f32_16x16x32_bf16 v[86:89], v[160:163], v[192:195], v[86:89]
	v_mfma_f32_16x16x32_bf16 v[82:85], v[168:171], v[192:195], v[82:85]
	v_mfma_f32_16x16x32_bf16 v[70:73], v[160:163], v[200:203], v[70:73]
	v_mfma_f32_16x16x32_bf16 v[66:69], v[168:171], v[200:203], v[66:69]
	s_setprio 0
	s_barrier
	s_add_i32 s28, s29, s43
	v_lshl_add_u64 v[204:205], s[30:31], 0, v[0:1]
	s_mov_b32 m0, s28
	ds_read_b128 v[172:175], v143 offset:16384
	ds_read_b128 v[176:179], v143 offset:17408
	ds_read_b128 v[180:183], v143 offset:18432
	ds_read_b128 v[184:187], v143 offset:19456
	ds_read_b128 v[188:191], v143 offset:20480
	ds_read_b128 v[192:195], v143 offset:21504
	ds_read_b128 v[196:199], v143 offset:22528
	ds_read_b128 v[200:203], v143 offset:23552
	global_load_lds_dwordx4 v[204:205], off
	s_add_i32 m0, s28, 0x2000
	s_add_u32 s28, s30, 0x80000
	v_lshl_add_u64 v[206:207], s[30:31], 0, v[130:131]
	s_addc_u32 s29, s31, 0
	s_add_i32 s23, s23, s43
	global_load_lds_dwordx4 v[206:207], off
	v_lshl_add_u64 v[208:209], s[28:29], 0, v[0:1]
	s_mov_b32 m0, s23
	v_lshl_add_u64 v[210:211], s[36:37], 0, v[130:131]
	global_load_lds_dwordx4 v[208:209], off
	v_lshl_add_u64 v[208:209], s[28:29], 0, v[130:131]
	s_add_i32 m0, s23, 0x2000
	s_nop 0
	global_load_lds_dwordx4 v[208:209], off
	v_lshl_add_u64 v[208:209], s[36:37], 0, v[0:1]
	s_mov_b32 m0, s46
	s_nop 0
	global_load_lds_dwordx4 v[208:209], off
	s_mov_b32 m0, s47
	s_nop 0
	global_load_lds_dwordx4 v[210:211], off
	s_waitcnt vmcnt(8)
	s_waitcnt lgkmcnt(0)
	s_barrier
; #define PG8_STAGE(bufoff, gbase, voff) do { _Pragma("unroll") for (int _i = 0; _i < 2; ++_i) \
;         __builtin_amdgcn_global_load_lds((const unsigned*)((const char*)(gbase) + (voff)[_i]), (LAS unsigned*)(lds + (bufoff) + ldsw + _i * 8192), 16, 0, 0); } while (0)
; #define PG8_LDA(dst, b, h) do { _Pragma("unroll") for (int m = 0; m < 4; ++m) _Pragma("unroll") for (int k = 0; k < 2; ++k) dst[m][k] = *(const LAS bf16x8*)(lds + PG8_SA(b, h) + aoff + m * 2048 + k * 1024); } while (0)
; #define PG8_LDB(dst, b, h) do { _Pragma("unroll") for (int n = 0; n < 2; ++n) _Pragma("unroll") for (int k = 0; k < 2; ++k) dst[n][k] = *(const LAS bf16x8*)(lds + PG8_SB(b, h) + boff + n * 2048 + k * 1024); } while (0)
; #define PG8_MMA(ai, bj, At, Bt) do { __builtin_amdgcn_s_setprio(1); _Pragma("unroll") for (int m = 0; m < 4; ++m) _Pragma("unroll") for (int n = 0; n < 2; ++n) _Pragma("unroll") for (int k = 0; k < 2; ++k) \
;         acc[ai][bj][m][n] = __builtin_amdgcn_mfma_f32_16x16x32_bf16(Bt[n][k], At[m][k], acc[ai][bj][m][n], 0, 0, 0); __builtin_amdgcn_s_setprio(0); } while (0)
; #define PG8_WAIT_V(n) asm volatile("s_waitcnt vmcnt(" #n ")" ::: "memory")
; #define PG8_WAIT_L(n) asm volatile("s_waitcnt lgkmcnt(" #n ")" ::: "memory")
; #define PG8_BAR __builtin_amdgcn_s_barrier()
; #define PG8_SCHED __builtin_amdgcn_sched_barrier(0)
; template <class Epi, class Sched, bool ALIGN_EPI, bool LAST_FUSED = false, bool PERM = false, bool CARRY = false>
; __device__ __forceinline__ void gemm_phase(LAS unsigned char* lds, const int tid, const int K, const int lda, const int ldb, const Sched& S, const Epi& E) {
;     ...
;             PG8_WAIT_V(8); PG8_WAIT_L(0); PG8_BAR; PG8_MMA(1, 0, At, B0); PG8_MMA(1, 1, At, B1); PG8_BAR; PG8_SCHED;
;             PG8_LDB(B0, 1, 0); PG8_LDB(B1, 1, 1); PG8_SCHED; PG8_LDA(At, 1, 0); PG8_STAGE(PG8_SA(0, 1), a2 + hstepA, voffA);
;             PG8_WAIT_V(8); PG8_WAIT_L(0); PG8_BAR; PG8_MMA(0, 0, At, B0); PG8_MMA(0, 1, At, B1); PG8_BAR; PG8_SCHED;
	s_setprio 1
	v_mfma_f32_16x16x32_bf16 v[62:65], v[136:139], v[172:175], v[62:65]
	v_mfma_f32_16x16x32_bf16 v[58:61], v[148:151], v[172:175], v[58:61]
	v_mfma_f32_16x16x32_bf16 v[46:49], v[136:139], v[180:183], v[46:49]
	v_mfma_f32_16x16x32_bf16 v[42:45], v[148:151], v[180:183], v[42:45]
	v_mfma_f32_16x16x32_bf16 v[30:33], v[136:139], v[188:191], v[30:33]
	v_mfma_f32_16x16x32_bf16 v[26:29], v[148:151], v[188:191], v[26:29]
	v_mfma_f32_16x16x32_bf16 v[14:17], v[136:139], v[196:199], v[14:17]
	v_mfma_f32_16x16x32_bf16 v[10:13], v[148:151], v[196:199], v[10:13]
	v_mfma_f32_16x16x32_bf16 v[62:65], v[144:147], v[176:179], v[62:65]
	v_mfma_f32_16x16x32_bf16 v[58:61], v[152:155], v[176:179], v[58:61]
	v_mfma_f32_16x16x32_bf16 v[46:49], v[144:147], v[184:187], v[46:49]
	v_mfma_f32_16x16x32_bf16 v[42:45], v[152:155], v[184:187], v[42:45]
	v_mfma_f32_16x16x32_bf16 v[30:33], v[144:147], v[192:195], v[30:33]
	v_mfma_f32_16x16x32_bf16 v[26:29], v[152:155], v[192:195], v[26:29]
	v_mfma_f32_16x16x32_bf16 v[14:17], v[144:147], v[200:203], v[14:17]
	v_mfma_f32_16x16x32_bf16 v[10:13], v[152:155], v[200:203], v[10:13]
	s_setprio 0
	s_setprio 1
	v_mfma_f32_16x16x32_bf16 v[54:57], v[156:159], v[172:175], v[54:57]
	v_mfma_f32_16x16x32_bf16 v[50:53], v[164:167], v[172:175], v[50:53]
	v_mfma_f32_16x16x32_bf16 v[38:41], v[156:159], v[180:183], v[38:41]
	v_mfma_f32_16x16x32_bf16 v[34:37], v[164:167], v[180:183], v[34:37]
	v_mfma_f32_16x16x32_bf16 v[22:25], v[156:159], v[188:191], v[22:25]
	v_mfma_f32_16x16x32_bf16 v[18:21], v[164:167], v[188:191], v[18:21]
	v_mfma_f32_16x16x32_bf16 v[6:9], v[156:159], v[196:199], v[6:9]
	v_mfma_f32_16x16x32_bf16 v[2:5], v[164:167], v[196:199], v[2:5]
	v_mfma_f32_16x16x32_bf16 v[54:57], v[160:163], v[176:179], v[54:57]
	v_mfma_f32_16x16x32_bf16 v[50:53], v[168:171], v[176:179], v[50:53]
	v_mfma_f32_16x16x32_bf16 v[38:41], v[160:163], v[184:187], v[38:41]
	v_mfma_f32_16x16x32_bf16 v[34:37], v[168:171], v[184:187], v[34:37]
	v_mfma_f32_16x16x32_bf16 v[22:25], v[160:163], v[192:195], v[22:25]
	v_mfma_f32_16x16x32_bf16 v[18:21], v[168:171], v[192:195], v[18:21]
	v_mfma_f32_16x16x32_bf16 v[6:9], v[160:163], v[200:203], v[6:9]
	v_mfma_f32_16x16x32_bf16 v[2:5], v[168:171], v[200:203], v[2:5]
	s_setprio 0
	s_barrier
	s_add_i32 s23, 0, 0x18000
	s_add_i32 s35, 0, 0x1c000
	v_add_u32_e32 v152, s23, v142
	v_add_u32_e32 v168, s35, v142
	ds_read_b128 v[136:139], v152
	ds_read_b128 v[144:147], v152 offset:1024
	ds_read_b128 v[148:151], v152 offset:2048
	ds_read_b128 v[152:155], v152 offset:3072
	ds_read_b128 v[156:159], v168
	ds_read_b128 v[160:163], v168 offset:1024
	ds_read_b128 v[164:167], v168 offset:2048
	ds_read_b128 v[168:171], v168 offset:3072
	s_add_u32 s28, s36, 0x80000
	s_addc_u32 s29, s37, 0
	s_mov_b32 m0, s48
	v_lshl_add_u64 v[212:213], s[28:29], 0, v[0:1]
	ds_read_b128 v[172:175], v143 offset:32768
	ds_read_b128 v[176:179], v143 offset:33792
	ds_read_b128 v[180:183], v143 offset:34816
	ds_read_b128 v[184:187], v143 offset:35840
	ds_read_b128 v[188:191], v143 offset:36864
	ds_read_b128 v[192:195], v143 offset:37888
	ds_read_b128 v[196:199], v143 offset:38912
	ds_read_b128 v[200:203], v143 offset:39936
	global_load_lds_dwordx4 v[212:213], off
	v_lshl_add_u64 v[212:213], s[28:29], 0, v[130:131]
	s_mov_b32 m0, s49
	s_nop 0
	global_load_lds_dwordx4 v[212:213], off
	s_waitcnt vmcnt(8)
	s_waitcnt lgkmcnt(0)
	s_barrier
	s_setprio 1
	v_mfma_f32_16x16x32_bf16 v[126:129], v[136:139], v[172:175], v[126:129]
	v_mfma_f32_16x16x32_bf16 v[122:125], v[148:151], v[172:175], v[122:125]
	v_mfma_f32_16x16x32_bf16 v[110:113], v[136:139], v[180:183], v[110:113]
	v_mfma_f32_16x16x32_bf16 v[106:109], v[148:151], v[180:183], v[106:109]
	v_mfma_f32_16x16x32_bf16 v[94:97], v[136:139], v[188:191], v[94:97]
	v_mfma_f32_16x16x32_bf16 v[90:93], v[148:151], v[188:191], v[90:93]
	v_mfma_f32_16x16x32_bf16 v[78:81], v[136:139], v[196:199], v[78:81]
	v_mfma_f32_16x16x32_bf16 v[74:77], v[148:151], v[196:199], v[74:77]
	v_mfma_f32_16x16x32_bf16 v[126:129], v[144:147], v[176:179], v[126:129]
	v_mfma_f32_16x16x32_bf16 v[122:125], v[152:155], v[176:179], v[122:125]
	v_mfma_f32_16x16x32_bf16 v[110:113], v[144:147], v[184:187], v[110:113]
	v_mfma_f32_16x16x32_bf16 v[106:109], v[152:155], v[184:187], v[106:109]
	v_mfma_f32_16x16x32_bf16 v[94:97], v[144:147], v[192:195], v[94:97]
	v_mfma_f32_16x16x32_bf16 v[90:93], v[152:155], v[192:195], v[90:93]
	v_mfma_f32_16x16x32_bf16 v[78:81], v[144:147], v[200:203], v[78:81]
	v_mfma_f32_16x16x32_bf16 v[74:77], v[152:155], v[200:203], v[74:77]
	s_setprio 0
	s_setprio 1
	v_mfma_f32_16x16x32_bf16 v[118:121], v[156:159], v[172:175], v[118:121]
	v_mfma_f32_16x16x32_bf16 v[114:117], v[164:167], v[172:175], v[114:117]
	v_mfma_f32_16x16x32_bf16 v[102:105], v[156:159], v[180:183], v[102:105]
	v_mfma_f32_16x16x32_bf16 v[98:101], v[164:167], v[180:183], v[98:101]
	v_mfma_f32_16x16x32_bf16 v[86:89], v[156:159], v[188:191], v[86:89]
	v_mfma_f32_16x16x32_bf16 v[82:85], v[164:167], v[188:191], v[82:85]
	v_mfma_f32_16x16x32_bf16 v[70:73], v[156:159], v[196:199], v[70:73]
	v_mfma_f32_16x16x32_bf16 v[66:69], v[164:167], v[196:199], v[66:69]
	v_mfma_f32_16x16x32_bf16 v[118:121], v[160:163], v[176:179], v[118:121]
	v_mfma_f32_16x16x32_bf16 v[114:117], v[168:171], v[176:179], v[114:117]
	v_mfma_f32_16x16x32_bf16 v[102:105], v[160:163], v[184:187], v[102:105]
	v_mfma_f32_16x16x32_bf16 v[98:101], v[168:171], v[184:187], v[98:101]
	v_mfma_f32_16x16x32_bf16 v[86:89], v[160:163], v[192:195], v[86:89]
	v_mfma_f32_16x16x32_bf16 v[82:85], v[168:171], v[192:195], v[82:85]
	v_mfma_f32_16x16x32_bf16 v[70:73], v[160:163], v[200:203], v[70:73]
	v_mfma_f32_16x16x32_bf16 v[66:69], v[168:171], v[200:203], v[66:69]
	s_setprio 0
	s_barrier
; #define PG8_STAGE(bufoff, gbase, voff) do { _Pragma("unroll") for (int _i = 0; _i < 2; ++_i) \
;         __builtin_amdgcn_global_load_lds((const unsigned*)((const char*)(gbase) + (voff)[_i]), (LAS unsigned*)(lds + (bufoff) + ldsw + _i * 8192), 16, 0, 0); } while (0)
; #define PG8_LDA(dst, b, h) do { _Pragma("unroll") for (int m = 0; m < 4; ++m) _Pragma("unroll") for (int k = 0; k < 2; ++k) dst[m][k] = *(const LAS bf16x8*)(lds + PG8_SA(b, h) + aoff + m * 2048 + k * 1024); } while (0)
; #define PG8_MMA(ai, bj, At, Bt) do { __builtin_amdgcn_s_setprio(1); _Pragma("unroll") for (int m = 0; m < 4; ++m) _Pragma("unroll") for (int n = 0; n < 2; ++n) _Pragma("unroll") for (int k = 0; k < 2; ++k) \
;         acc[ai][bj][m][n] = __builtin_amdgcn_mfma_f32_16x16x32_bf16(Bt[n][k], At[m][k], acc[ai][bj][m][n], 0, 0, 0); __builtin_amdgcn_s_setprio(0); } while (0)
; #define PG8_WAIT_V(n) asm volatile("s_waitcnt vmcnt(" #n ")" ::: "memory")
; #define PG8_WAIT_L(n) asm volatile("s_waitcnt lgkmcnt(" #n ")" ::: "memory")
; #define PG8_BAR __builtin_amdgcn_s_barrier()
; #define PG8_SCHED __builtin_amdgcn_sched_barrier(0)
; template <class Epi, class Sched, bool ALIGN_EPI, bool LAST_FUSED = false, bool PERM = false, bool CARRY = false>
; __device__ __forceinline__ void gemm_phase(LAS unsigned char* lds, const int tid, const int K, const int lda, const int ldb, const Sched& S, const Epi& E) {
;     ...
;             PG8_LDA(At, 1, 1); PG8_STAGE(PG8_SB(1, 0), b3, voffB); PG8_STAGE(PG8_SB(1, 1), b3 + hstepB, voffB); PG8_STAGE(PG8_SA(1, 0), a3, voffA);
;             PG8_WAIT_V(8); PG8_WAIT_L(0); PG8_BAR; PG8_MMA(1, 0, At, B0); PG8_MMA(1, 1, At, B1); PG8_BAR; PG8_SCHED;
;         }
;         if constexpr (ALIGN_EPI) { if (wr == 0) PG8_BAR; }
	s_add_i32 s23, s23, s43
	v_lshl_add_u64 v[204:205], v[204:205], 0, s[68:69]
	s_mov_b32 m0, s23
	ds_read_b128 v[172:175], v143 offset:49152
	ds_read_b128 v[176:179], v143 offset:50176
	ds_read_b128 v[180:183], v143 offset:51200
	ds_read_b128 v[184:187], v143 offset:52224
	ds_read_b128 v[188:191], v143 offset:53248
	ds_read_b128 v[192:195], v143 offset:54272
	ds_read_b128 v[196:199], v143 offset:55296
	ds_read_b128 v[200:203], v143 offset:56320
	global_load_lds_dwordx4 v[204:205], off
	s_add_i32 m0, s23, 0x2000
	s_add_u32 s28, s30, 0x80080
	v_lshl_add_u64 v[204:205], v[206:207], 0, s[68:69]
	s_addc_u32 s29, s31, 0
	s_add_i32 s23, s35, s43
	global_load_lds_dwordx4 v[204:205], off
	v_lshl_add_u64 v[204:205], s[28:29], 0, v[0:1]
	s_mov_b32 m0, s23
	s_nop 0
	global_load_lds_dwordx4 v[204:205], off
	v_lshl_add_u64 v[204:205], s[28:29], 0, v[130:131]
	s_add_i32 m0, s23, 0x2000
	s_nop 0
	global_load_lds_dwordx4 v[204:205], off
	v_lshl_add_u64 v[204:205], v[208:209], 0, s[68:69]
	s_mov_b32 m0, s51
	s_nop 0
	global_load_lds_dwordx4 v[204:205], off
	v_lshl_add_u64 v[204:205], v[210:211], 0, s[68:69]
	s_mov_b32 m0, s52
	s_nop 0
	global_load_lds_dwordx4 v[204:205], off
	s_waitcnt vmcnt(8)
	s_waitcnt lgkmcnt(0)
	s_barrier
	s_setprio 1
	v_mfma_f32_16x16x32_bf16 v[62:65], v[136:139], v[172:175], v[62:65]
	v_mfma_f32_16x16x32_bf16 v[58:61], v[148:151], v[172:175], v[58:61]
	v_mfma_f32_16x16x32_bf16 v[46:49], v[136:139], v[180:183], v[46:49]
	v_mfma_f32_16x16x32_bf16 v[42:45], v[148:151], v[180:183], v[42:45]
	v_mfma_f32_16x16x32_bf16 v[30:33], v[136:139], v[188:191], v[30:33]
	v_mfma_f32_16x16x32_bf16 v[26:29], v[148:151], v[188:191], v[26:29]
	v_mfma_f32_16x16x32_bf16 v[14:17], v[136:139], v[196:199], v[14:17]
	v_mfma_f32_16x16x32_bf16 v[10:13], v[148:151], v[196:199], v[10:13]
	v_mfma_f32_16x16x32_bf16 v[62:65], v[144:147], v[176:179], v[62:65]
	v_mfma_f32_16x16x32_bf16 v[58:61], v[152:155], v[176:179], v[58:61]
	v_mfma_f32_16x16x32_bf16 v[46:49], v[144:147], v[184:187], v[46:49]
	v_mfma_f32_16x16x32_bf16 v[42:45], v[152:155], v[184:187], v[42:45]
	v_mfma_f32_16x16x32_bf16 v[30:33], v[144:147], v[192:195], v[30:33]
	v_mfma_f32_16x16x32_bf16 v[26:29], v[152:155], v[192:195], v[26:29]
	v_mfma_f32_16x16x32_bf16 v[14:17], v[144:147], v[200:203], v[14:17]
	v_mfma_f32_16x16x32_bf16 v[10:13], v[152:155], v[200:203], v[10:13]
	s_setprio 0
	s_setprio 1
	v_mfma_f32_16x16x32_bf16 v[54:57], v[156:159], v[172:175], v[54:57]
	v_mfma_f32_16x16x32_bf16 v[50:53], v[164:167], v[172:175], v[50:53]
	v_mfma_f32_16x16x32_bf16 v[38:41], v[156:159], v[180:183], v[38:41]
	v_mfma_f32_16x16x32_bf16 v[34:37], v[164:167], v[180:183], v[34:37]
	v_mfma_f32_16x16x32_bf16 v[22:25], v[156:159], v[188:191], v[22:25]
	v_mfma_f32_16x16x32_bf16 v[18:21], v[164:167], v[188:191], v[18:21]
	v_mfma_f32_16x16x32_bf16 v[6:9], v[156:159], v[196:199], v[6:9]
	v_mfma_f32_16x16x32_bf16 v[2:5], v[164:167], v[196:199], v[2:5]
	v_mfma_f32_16x16x32_bf16 v[54:57], v[160:163], v[176:179], v[54:57]
	v_mfma_f32_16x16x32_bf16 v[50:53], v[168:171], v[176:179], v[50:53]
	v_mfma_f32_16x16x32_bf16 v[38:41], v[160:163], v[184:187], v[38:41]
	v_mfma_f32_16x16x32_bf16 v[34:37], v[168:171], v[184:187], v[34:37]
	v_mfma_f32_16x16x32_bf16 v[22:25], v[160:163], v[192:195], v[22:25]
	v_mfma_f32_16x16x32_bf16 v[18:21], v[168:171], v[192:195], v[18:21]
	v_mfma_f32_16x16x32_bf16 v[6:9], v[160:163], v[200:203], v[6:9]
	v_mfma_f32_16x16x32_bf16 v[2:5], v[168:171], v[200:203], v[2:5]
	s_setprio 0
	s_barrier
	s_add_i32 s15, s15, 2
	s_add_u32 s26, s26, 0x100
	s_addc_u32 s27, s27, 0
	s_add_u32 s5, s5, 0x100
	s_addc_u32 s13, s13, 0
	s_cmp_gt_u32 s15, 29
	s_cbranch_scc0 .LBB0_1077
	s_and_b64 vcc, exec, s[10:11]
	s_cbranch_vccz .LBB0_1080
	s_barrier

; #define PG8_STAGE(bufoff, gbase, voff) do { _Pragma("unroll") for (int _i = 0; _i < 2; ++_i) \
;         __builtin_amdgcn_global_load_lds((const unsigned*)((const char*)(gbase) + (voff)[_i]), (LAS unsigned*)(lds + (bufoff) + ldsw + _i * 8192), 16, 0, 0); } while (0)
; #define PG8_LDA(dst, b, h) do { _Pragma("unroll") for (int m = 0; m < 4; ++m) _Pragma("unroll") for (int k = 0; k < 2; ++k) dst[m][k] = *(const LAS bf16x8*)(lds + PG8_SA(b, h) + aoff + m * 2048 + k * 1024); } while (0)
; #define PG8_LDB(dst, b, h) do { _Pragma("unroll") for (int n = 0; n < 2; ++n) _Pragma("unroll") for (int k = 0; k < 2; ++k) dst[n][k] = *(const LAS bf16x8*)(lds + PG8_SB(b, h) + boff + n * 2048 + k * 1024); } while (0)
; #define PG8_MMA(ai, bj, At, Bt) do { __builtin_amdgcn_s_setprio(1); _Pragma("unroll") for (int m = 0; m < 4; ++m) _Pragma("unroll") for (int n = 0; n < 2; ++n) _Pragma("unroll") for (int k = 0; k < 2; ++k) \
;         acc[ai][bj][m][n] = __builtin_amdgcn_mfma_f32_16x16x32_bf16(Bt[n][k], At[m][k], acc[ai][bj][m][n], 0, 0, 0); __builtin_amdgcn_s_setprio(0); } while (0)
; #define PG8_WAIT_V(n) asm volatile("s_waitcnt vmcnt(" #n ")" ::: "memory")
; #define PG8_WAIT_L(n) asm volatile("s_waitcnt lgkmcnt(" #n ")" ::: "memory")
; #define PG8_BAR __builtin_amdgcn_s_barrier()
; template <class Epi, class Sched, bool ALIGN_EPI, bool LAST_FUSED = false, bool PERM = false, bool CARRY = false>
; __device__ __forceinline__ void gemm_phase(LAS unsigned char* lds, const int tid, const int K, const int lda, const int ldb, const Sched& S, const Epi& E) {
;     ...
;             const bool last = (t == nt - 2);
;             const char* a1 = cA + (size_t)(t + 1) * kstep;
;             const char* a2 = last ? nA : cA + (size_t)(t + 2) * kstep; const char* b2 = last ? nB : cB + (size_t)(t + 2) * kstep;
;             const char* a3 = a2 + kstep; const char* b3 = b2 + kstep;
;             PG8_LDB(B0, 0, 0); PG8_LDB(B1, 0, 1); PG8_SCHED; PG8_LDA(At, 0, 0); PG8_STAGE(PG8_SA(1, 1), a1 + hstepA, voffA);
;             PG8_WAIT_V(8); PG8_WAIT_L(0); PG8_BAR; PG8_MMA(0, 0, At, B0); PG8_MMA(0, 1, At, B1); PG8_BAR; PG8_SCHED;
;             PG8_LDA(At, 0, 1); PG8_STAGE(PG8_SB(0, 0), b2, voffB); PG8_STAGE(PG8_SB(0, 1), b2 + hstepB, voffB); PG8_STAGE(PG8_SA(0, 0), a2, voffA);
;             PG8_WAIT_V(8); PG8_WAIT_L(0); PG8_BAR; PG8_MMA(1, 0, At, B0); PG8_MMA(1, 1, At, B1); PG8_BAR; PG8_SCHED;
.LBB0_1367:
	s_add_u32 s19, s38, s17
	s_addc_u32 s23, s39, 0
	s_add_u32 s35, s19, 0x100
	s_addc_u32 s37, s23, 0
	s_and_b64 s[28:29], s[46:47], exec
	s_cselect_b32 s51, s27, s37
	s_cselect_b32 s50, s26, s35
	s_add_u32 s17, s40, s17
	s_addc_u32 s28, s41, 0
	s_add_u32 s17, s17, 0x100
	s_addc_u32 s35, s28, 0
	s_add_i32 s45, 0, 0x10000
	s_and_b64 s[28:29], s[46:47], exec
	s_cselect_b32 s55, s31, s35
	s_cselect_b32 s54, s30, s17
	s_add_i32 s47, 0, 0x14000
	s_add_u32 s52, s19, 0x80080
	s_addc_u32 s53, s23, 0
	s_add_i32 s44, s45, s61
	s_add_i32 m0, s63, 0xc000
	s_add_i32 s79, s63, 0xe000
	s_add_i32 s29, s44, 0x2000
	s_add_u32 s58, s54, 0x10000
	v_add_u32_e32 v46, s45, v216
	v_add_u32_e32 v164, s47, v216
	s_addc_u32 s59, s55, 0
	s_add_i32 s37, s47, s61
	ds_read_b128 v[26:29], v46
	ds_read_b128 v[34:37], v46 offset:1024
	ds_read_b128 v[38:41], v46 offset:2048
	ds_read_b128 v[46:49], v46 offset:3072
	ds_read_b128 v[54:57], v164
	ds_read_b128 v[58:61], v164 offset:1024
	ds_read_b128 v[160:163], v164 offset:2048
	ds_read_b128 v[164:167], v164 offset:3072
	s_add_i32 s35, s37, 0x2000
	s_add_i32 s28, 0, 0x18000
	s_add_i32 s23, 0, 0x1c000
	s_add_u32 s48, s50, 0x80000
	s_addc_u32 s49, s51, 0
	s_add_i32 s19, s28, s61
	s_add_i32 s17, s19, 0x2000
	s_add_u32 s46, s54, 0x10080
	s_addc_u32 s47, s55, 0
	s_add_i32 s78, s23, s61
	s_add_i32 s45, s78, 0x2000
	v_lshl_add_u64 v[200:201], s[52:53], 0, v[158:159]
	ds_read_b128 v[168:171], v217
	ds_read_b128 v[172:175], v217 offset:1024
	ds_read_b128 v[176:179], v217 offset:2048
	ds_read_b128 v[180:183], v217 offset:3072
	ds_read_b128 v[184:187], v217 offset:4096
	ds_read_b128 v[188:191], v217 offset:5120
	ds_read_b128 v[192:195], v217 offset:6144
	ds_read_b128 v[196:199], v217 offset:7168
	global_load_lds_dwordx4 v[200:201], off
	v_lshl_add_u64 v[200:201], s[52:53], 0, v[156:157]
	s_mov_b32 m0, s79
	s_nop 0
	global_load_lds_dwordx4 v[200:201], off
	s_waitcnt vmcnt(8)
	s_waitcnt lgkmcnt(0)
	s_barrier
	s_setprio 1
	v_mfma_f32_16x16x32_bf16 v[150:153], v[26:29], v[168:171], v[150:153]
	v_mfma_f32_16x16x32_bf16 v[142:145], v[38:41], v[168:171], v[142:145]
	v_mfma_f32_16x16x32_bf16 v[134:137], v[26:29], v[176:179], v[134:137]
	v_mfma_f32_16x16x32_bf16 v[126:129], v[38:41], v[176:179], v[126:129]
	v_mfma_f32_16x16x32_bf16 v[118:121], v[26:29], v[184:187], v[118:121]
	v_mfma_f32_16x16x32_bf16 v[110:113], v[38:41], v[184:187], v[110:113]
	v_mfma_f32_16x16x32_bf16 v[102:105], v[26:29], v[192:195], v[102:105]
	v_mfma_f32_16x16x32_bf16 v[94:97], v[38:41], v[192:195], v[94:97]
	v_mfma_f32_16x16x32_bf16 v[150:153], v[34:37], v[172:175], v[150:153]
	v_mfma_f32_16x16x32_bf16 v[142:145], v[46:49], v[172:175], v[142:145]
	v_mfma_f32_16x16x32_bf16 v[134:137], v[34:37], v[180:183], v[134:137]
	v_mfma_f32_16x16x32_bf16 v[126:129], v[46:49], v[180:183], v[126:129]
	v_mfma_f32_16x16x32_bf16 v[118:121], v[34:37], v[188:191], v[118:121]
	v_mfma_f32_16x16x32_bf16 v[110:113], v[46:49], v[188:191], v[110:113]
	v_mfma_f32_16x16x32_bf16 v[102:105], v[34:37], v[196:199], v[102:105]
	v_mfma_f32_16x16x32_bf16 v[94:97], v[46:49], v[196:199], v[94:97]
	s_setprio 0
	s_setprio 1
	v_mfma_f32_16x16x32_bf16 v[146:149], v[54:57], v[168:171], v[146:149]
	v_mfma_f32_16x16x32_bf16 v[138:141], v[160:163], v[168:171], v[138:141]
	v_mfma_f32_16x16x32_bf16 v[130:133], v[54:57], v[176:179], v[130:133]
	v_mfma_f32_16x16x32_bf16 v[122:125], v[160:163], v[176:179], v[122:125]
	v_mfma_f32_16x16x32_bf16 v[114:117], v[54:57], v[184:187], v[114:117]
	v_mfma_f32_16x16x32_bf16 v[106:109], v[160:163], v[184:187], v[106:109]
	v_mfma_f32_16x16x32_bf16 v[98:101], v[54:57], v[192:195], v[98:101]
	v_mfma_f32_16x16x32_bf16 v[90:93], v[160:163], v[192:195], v[90:93]
	v_mfma_f32_16x16x32_bf16 v[146:149], v[58:61], v[172:175], v[146:149]
	v_mfma_f32_16x16x32_bf16 v[138:141], v[164:167], v[172:175], v[138:141]
	v_mfma_f32_16x16x32_bf16 v[130:133], v[58:61], v[180:183], v[130:133]
	v_mfma_f32_16x16x32_bf16 v[122:125], v[164:167], v[180:183], v[122:125]
	v_mfma_f32_16x16x32_bf16 v[114:117], v[58:61], v[188:191], v[114:117]
	v_mfma_f32_16x16x32_bf16 v[106:109], v[164:167], v[188:191], v[106:109]
	v_mfma_f32_16x16x32_bf16 v[98:101], v[58:61], v[196:199], v[98:101]
	v_mfma_f32_16x16x32_bf16 v[90:93], v[164:167], v[196:199], v[90:93]
	s_setprio 0
	s_barrier
	s_mov_b32 m0, s44
	v_lshl_add_u64 v[204:205], s[54:55], 0, v[0:1]
	ds_read_b128 v[168:171], v217 offset:16384
	ds_read_b128 v[172:175], v217 offset:17408
	ds_read_b128 v[176:179], v217 offset:18432
	ds_read_b128 v[180:183], v217 offset:19456
	ds_read_b128 v[184:187], v217 offset:20480
	ds_read_b128 v[188:191], v217 offset:21504
	ds_read_b128 v[192:195], v217 offset:22528
	ds_read_b128 v[196:199], v217 offset:23552
	global_load_lds_dwordx4 v[204:205], off
	v_lshl_add_u64 v[206:207], s[54:55], 0, v[154:155]
	s_mov_b32 m0, s29
	v_lshl_add_u64 v[200:201], s[58:59], 0, v[0:1]
	global_load_lds_dwordx4 v[206:207], off
	s_mov_b32 m0, s37
	v_lshl_add_u64 v[208:209], s[50:51], 0, v[158:159]
	global_load_lds_dwordx4 v[200:201], off
	v_lshl_add_u64 v[200:201], s[58:59], 0, v[154:155]
	s_mov_b32 m0, s35
	v_lshl_add_u64 v[210:211], s[50:51], 0, v[156:157]
	global_load_lds_dwordx4 v[200:201], off
	s_mov_b32 m0, s63
	s_nop 0
	global_load_lds_dwordx4 v[208:209], off
	s_mov_b32 m0, s64
	s_nop 0
	global_load_lds_dwordx4 v[210:211], off
	s_waitcnt vmcnt(8)
	s_waitcnt lgkmcnt(0)
	s_barrier
; #define PG8_STAGE(bufoff, gbase, voff) do { _Pragma("unroll") for (int _i = 0; _i < 2; ++_i) \
;         __builtin_amdgcn_global_load_lds((const unsigned*)((const char*)(gbase) + (voff)[_i]), (LAS unsigned*)(lds + (bufoff) + ldsw + _i * 8192), 16, 0, 0); } while (0)
; #define PG8_LDA(dst, b, h) do { _Pragma("unroll") for (int m = 0; m < 4; ++m) _Pragma("unroll") for (int k = 0; k < 2; ++k) dst[m][k] = *(const LAS bf16x8*)(lds + PG8_SA(b, h) + aoff + m * 2048 + k * 1024); } while (0)
; #define PG8_LDB(dst, b, h) do { _Pragma("unroll") for (int n = 0; n < 2; ++n) _Pragma("unroll") for (int k = 0; k < 2; ++k) dst[n][k] = *(const LAS bf16x8*)(lds + PG8_SB(b, h) + boff + n * 2048 + k * 1024); } while (0)
; #define PG8_MMA(ai, bj, At, Bt) do { __builtin_amdgcn_s_setprio(1); _Pragma("unroll") for (int m = 0; m < 4; ++m) _Pragma("unroll") for (int n = 0; n < 2; ++n) _Pragma("unroll") for (int k = 0; k < 2; ++k) \
;         acc[ai][bj][m][n] = __builtin_amdgcn_mfma_f32_16x16x32_bf16(Bt[n][k], At[m][k], acc[ai][bj][m][n], 0, 0, 0); __builtin_amdgcn_s_setprio(0); } while (0)
; #define PG8_WAIT_V(n) asm volatile("s_waitcnt vmcnt(" #n ")" ::: "memory")
; #define PG8_WAIT_L(n) asm volatile("s_waitcnt lgkmcnt(" #n ")" ::: "memory")
; #define PG8_BAR __builtin_amdgcn_s_barrier()
; #define PG8_SCHED __builtin_amdgcn_sched_barrier(0)
; template <class Epi, class Sched, bool ALIGN_EPI, bool LAST_FUSED = false, bool PERM = false, bool CARRY = false>
; __device__ __forceinline__ void gemm_phase(LAS unsigned char* lds, const int tid, const int K, const int lda, const int ldb, const Sched& S, const Epi& E) {
;     ...
;             PG8_WAIT_V(8); PG8_WAIT_L(0); PG8_BAR; PG8_MMA(1, 0, At, B0); PG8_MMA(1, 1, At, B1); PG8_BAR; PG8_SCHED;
;             PG8_LDB(B0, 1, 0); PG8_LDB(B1, 1, 1); PG8_SCHED; PG8_LDA(At, 1, 0); PG8_STAGE(PG8_SA(0, 1), a2 + hstepA, voffA);
;             PG8_WAIT_V(8); PG8_WAIT_L(0); PG8_BAR; PG8_MMA(0, 0, At, B0); PG8_MMA(0, 1, At, B1); PG8_BAR; PG8_SCHED;
	s_setprio 1
	v_mfma_f32_16x16x32_bf16 v[86:89], v[26:29], v[168:171], v[86:89]
	v_mfma_f32_16x16x32_bf16 v[78:81], v[38:41], v[168:171], v[78:81]
	v_mfma_f32_16x16x32_bf16 v[70:73], v[26:29], v[176:179], v[70:73]
	v_mfma_f32_16x16x32_bf16 v[62:65], v[38:41], v[176:179], v[62:65]
	v_mfma_f32_16x16x32_bf16 v[42:45], v[26:29], v[184:187], v[42:45]
	v_mfma_f32_16x16x32_bf16 v[22:25], v[38:41], v[184:187], v[22:25]
	v_mfma_f32_16x16x32_bf16 v[14:17], v[26:29], v[192:195], v[14:17]
	v_mfma_f32_16x16x32_bf16 v[6:9], v[38:41], v[192:195], v[6:9]
	v_mfma_f32_16x16x32_bf16 v[86:89], v[34:37], v[172:175], v[86:89]
	v_mfma_f32_16x16x32_bf16 v[78:81], v[46:49], v[172:175], v[78:81]
	v_mfma_f32_16x16x32_bf16 v[70:73], v[34:37], v[180:183], v[70:73]
	v_mfma_f32_16x16x32_bf16 v[62:65], v[46:49], v[180:183], v[62:65]
	v_mfma_f32_16x16x32_bf16 v[42:45], v[34:37], v[188:191], v[42:45]
	v_mfma_f32_16x16x32_bf16 v[22:25], v[46:49], v[188:191], v[22:25]
	v_mfma_f32_16x16x32_bf16 v[14:17], v[34:37], v[196:199], v[14:17]
	v_mfma_f32_16x16x32_bf16 v[6:9], v[46:49], v[196:199], v[6:9]
	s_setprio 0
	s_setprio 1
	v_mfma_f32_16x16x32_bf16 v[30:33], v[54:57], v[184:187], v[30:33]
	v_mfma_f32_16x16x32_bf16 v[18:21], v[160:163], v[184:187], v[18:21]
	v_mfma_f32_16x16x32_bf16 v[10:13], v[54:57], v[192:195], v[10:13]
	v_mfma_f32_16x16x32_bf16 v[2:5], v[160:163], v[192:195], v[2:5]
	v_mfma_f32_16x16x32_bf16 v[26:29], v[54:57], v[168:171], v[82:85]
	v_mfma_f32_16x16x32_bf16 v[34:37], v[160:163], v[168:171], v[74:77]
	v_mfma_f32_16x16x32_bf16 v[38:41], v[54:57], v[176:179], v[66:69]
	v_mfma_f32_16x16x32_bf16 v[46:49], v[160:163], v[176:179], v[50:53]
	v_mfma_f32_16x16x32_bf16 v[30:33], v[58:61], v[188:191], v[30:33]
	v_mfma_f32_16x16x32_bf16 v[18:21], v[164:167], v[188:191], v[18:21]
	v_mfma_f32_16x16x32_bf16 v[10:13], v[58:61], v[196:199], v[10:13]
	v_mfma_f32_16x16x32_bf16 v[2:5], v[164:167], v[196:199], v[2:5]
	v_mfma_f32_16x16x32_bf16 v[26:29], v[58:61], v[172:175], v[26:29]
	v_mfma_f32_16x16x32_bf16 v[34:37], v[164:167], v[172:175], v[34:37]
	v_mfma_f32_16x16x32_bf16 v[38:41], v[58:61], v[180:183], v[38:41]
	v_mfma_f32_16x16x32_bf16 v[46:49], v[164:167], v[180:183], v[46:49]
	s_setprio 0
	s_barrier
	v_add_u32_e32 v66, s28, v216
	v_add_u32_e32 v74, s23, v216
	ds_read_b128 v[50:53], v66
	ds_read_b128 v[54:57], v66 offset:1024
	ds_read_b128 v[58:61], v66 offset:2048
	ds_read_b128 v[66:69], v66 offset:3072
	ds_read_b128 v[160:163], v74
	ds_read_b128 v[164:167], v74 offset:1024
	ds_read_b128 v[168:171], v74 offset:2048
	ds_read_b128 v[172:175], v74 offset:3072
	s_mov_b32 m0, s65
	v_lshl_add_u64 v[200:201], s[48:49], 0, v[158:159]
	ds_read_b128 v[74:77], v217 offset:32768
	ds_read_b128 v[82:85], v217 offset:33792
	ds_read_b128 v[176:179], v217 offset:34816
	ds_read_b128 v[180:183], v217 offset:35840
	ds_read_b128 v[184:187], v217 offset:36864
	ds_read_b128 v[188:191], v217 offset:37888
	ds_read_b128 v[192:195], v217 offset:38912
	ds_read_b128 v[196:199], v217 offset:39936
	global_load_lds_dwordx4 v[200:201], off
	v_lshl_add_u64 v[200:201], s[48:49], 0, v[156:157]
	s_mov_b32 m0, s66
	s_nop 0
	global_load_lds_dwordx4 v[200:201], off
	s_waitcnt vmcnt(8)
	s_waitcnt lgkmcnt(0)
	s_barrier
	s_setprio 1
	v_mfma_f32_16x16x32_bf16 v[150:153], v[50:53], v[74:77], v[150:153]
	v_mfma_f32_16x16x32_bf16 v[142:145], v[58:61], v[74:77], v[142:145]
	v_mfma_f32_16x16x32_bf16 v[134:137], v[50:53], v[176:179], v[134:137]
	v_mfma_f32_16x16x32_bf16 v[126:129], v[58:61], v[176:179], v[126:129]
	v_mfma_f32_16x16x32_bf16 v[118:121], v[50:53], v[184:187], v[118:121]
	v_mfma_f32_16x16x32_bf16 v[110:113], v[58:61], v[184:187], v[110:113]
	v_mfma_f32_16x16x32_bf16 v[102:105], v[50:53], v[192:195], v[102:105]
	v_mfma_f32_16x16x32_bf16 v[94:97], v[58:61], v[192:195], v[94:97]
	v_mfma_f32_16x16x32_bf16 v[150:153], v[54:57], v[82:85], v[150:153]
	v_mfma_f32_16x16x32_bf16 v[142:145], v[66:69], v[82:85], v[142:145]
	v_mfma_f32_16x16x32_bf16 v[134:137], v[54:57], v[180:183], v[134:137]
	v_mfma_f32_16x16x32_bf16 v[126:129], v[66:69], v[180:183], v[126:129]
	v_mfma_f32_16x16x32_bf16 v[118:121], v[54:57], v[188:191], v[118:121]
	v_mfma_f32_16x16x32_bf16 v[110:113], v[66:69], v[188:191], v[110:113]
	v_mfma_f32_16x16x32_bf16 v[102:105], v[54:57], v[196:199], v[102:105]
	v_mfma_f32_16x16x32_bf16 v[94:97], v[66:69], v[196:199], v[94:97]
	s_setprio 0
	s_setprio 1
	v_mfma_f32_16x16x32_bf16 v[146:149], v[160:163], v[74:77], v[146:149]
	v_mfma_f32_16x16x32_bf16 v[74:77], v[168:171], v[74:77], v[138:141]
	v_mfma_f32_16x16x32_bf16 v[138:141], v[172:175], v[82:85], v[74:77]
	v_mfma_f32_16x16x32_bf16 v[74:77], v[160:163], v[176:179], v[130:133]
	v_mfma_f32_16x16x32_bf16 v[130:133], v[164:167], v[180:183], v[74:77]
	v_mfma_f32_16x16x32_bf16 v[74:77], v[168:171], v[176:179], v[122:125]
	v_mfma_f32_16x16x32_bf16 v[122:125], v[172:175], v[180:183], v[74:77]
	v_mfma_f32_16x16x32_bf16 v[74:77], v[160:163], v[184:187], v[114:117]
	v_mfma_f32_16x16x32_bf16 v[114:117], v[164:167], v[188:191], v[74:77]
	v_mfma_f32_16x16x32_bf16 v[74:77], v[168:171], v[184:187], v[106:109]
	v_mfma_f32_16x16x32_bf16 v[106:109], v[172:175], v[188:191], v[74:77]
	v_mfma_f32_16x16x32_bf16 v[74:77], v[160:163], v[192:195], v[98:101]
	v_mfma_f32_16x16x32_bf16 v[98:101], v[164:167], v[196:199], v[74:77]
	v_mfma_f32_16x16x32_bf16 v[74:77], v[168:171], v[192:195], v[90:93]
	v_mfma_f32_16x16x32_bf16 v[146:149], v[164:167], v[82:85], v[146:149]
	v_mfma_f32_16x16x32_bf16 v[90:93], v[172:175], v[196:199], v[74:77]
	s_setprio 0
	s_barrier
; #define PG8_STAGE(bufoff, gbase, voff) do { _Pragma("unroll") for (int _i = 0; _i < 2; ++_i) \
;         __builtin_amdgcn_global_load_lds((const unsigned*)((const char*)(gbase) + (voff)[_i]), (LAS unsigned*)(lds + (bufoff) + ldsw + _i * 8192), 16, 0, 0); } while (0)
; #define PG8_LDA(dst, b, h) do { _Pragma("unroll") for (int m = 0; m < 4; ++m) _Pragma("unroll") for (int k = 0; k < 2; ++k) dst[m][k] = *(const LAS bf16x8*)(lds + PG8_SA(b, h) + aoff + m * 2048 + k * 1024); } while (0)
; #define PG8_MMA(ai, bj, At, Bt) do { __builtin_amdgcn_s_setprio(1); _Pragma("unroll") for (int m = 0; m < 4; ++m) _Pragma("unroll") for (int n = 0; n < 2; ++n) _Pragma("unroll") for (int k = 0; k < 2; ++k) \
;         acc[ai][bj][m][n] = __builtin_amdgcn_mfma_f32_16x16x32_bf16(Bt[n][k], At[m][k], acc[ai][bj][m][n], 0, 0, 0); __builtin_amdgcn_s_setprio(0); } while (0)
; #define PG8_WAIT_V(n) asm volatile("s_waitcnt vmcnt(" #n ")" ::: "memory")
; #define PG8_WAIT_L(n) asm volatile("s_waitcnt lgkmcnt(" #n ")" ::: "memory")
; #define PG8_BAR __builtin_amdgcn_s_barrier()
; #define PG8_SCHED __builtin_amdgcn_sched_barrier(0)
; template <class Epi, class Sched, bool ALIGN_EPI, bool LAST_FUSED = false, bool PERM = false, bool CARRY = false>
; __device__ __forceinline__ void gemm_phase(LAS unsigned char* lds, const int tid, const int K, const int lda, const int ldb, const Sched& S, const Epi& E) {
;     ...
;             PG8_LDA(At, 1, 1); PG8_STAGE(PG8_SB(1, 0), b3, voffB); PG8_STAGE(PG8_SB(1, 1), b3 + hstepB, voffB); PG8_STAGE(PG8_SA(1, 0), a3, voffA);
;             PG8_WAIT_V(8); PG8_WAIT_L(0); PG8_BAR; PG8_MMA(1, 0, At, B0); PG8_MMA(1, 1, At, B1); PG8_BAR; PG8_SCHED;
;         }
;         if constexpr (ALIGN_EPI) { if (wr == 0) PG8_BAR; }
	s_mov_b32 m0, s19
	v_lshl_add_u64 v[82:83], v[204:205], 0, s[68:69]
	s_nop 1
	ds_read_b128 v[74:77], v217 offset:49152
	ds_read_b128 v[176:179], v217 offset:50176
	ds_read_b128 v[180:183], v217 offset:51200
	ds_read_b128 v[184:187], v217 offset:52224
	ds_read_b128 v[188:191], v217 offset:53248
	ds_read_b128 v[192:195], v217 offset:54272
	ds_read_b128 v[196:199], v217 offset:55296
	ds_read_b128 v[200:203], v217 offset:56320
	global_load_lds_dwordx4 v[82:83], off
	v_lshl_add_u64 v[82:83], v[206:207], 0, s[68:69]
	s_mov_b32 m0, s17
	s_nop 0
	global_load_lds_dwordx4 v[82:83], off
	v_lshl_add_u64 v[82:83], s[46:47], 0, v[0:1]
	s_mov_b32 m0, s78
	s_nop 0
	global_load_lds_dwordx4 v[82:83], off
	v_lshl_add_u64 v[82:83], s[46:47], 0, v[154:155]
	s_mov_b32 m0, s45
	s_nop 0
	global_load_lds_dwordx4 v[82:83], off
	v_lshl_add_u64 v[82:83], v[208:209], 0, s[68:69]
	s_mov_b32 m0, s74
	s_nop 0
	global_load_lds_dwordx4 v[82:83], off
	v_lshl_add_u64 v[82:83], v[210:211], 0, s[68:69]
	s_mov_b32 m0, s75
	s_nop 0
	global_load_lds_dwordx4 v[82:83], off
	s_waitcnt vmcnt(8)
	s_waitcnt lgkmcnt(0)
	s_barrier
	s_setprio 1
	v_mfma_f32_16x16x32_bf16 v[82:85], v[50:53], v[74:77], v[86:89]
	v_mfma_f32_16x16x32_bf16 v[78:81], v[58:61], v[74:77], v[78:81]
	v_mfma_f32_16x16x32_bf16 v[70:73], v[50:53], v[180:183], v[70:73]
	v_mfma_f32_16x16x32_bf16 v[62:65], v[58:61], v[180:183], v[62:65]
	v_mfma_f32_16x16x32_bf16 v[42:45], v[50:53], v[188:191], v[42:45]
	v_mfma_f32_16x16x32_bf16 v[22:25], v[58:61], v[188:191], v[22:25]
	v_mfma_f32_16x16x32_bf16 v[14:17], v[50:53], v[196:199], v[14:17]
	v_mfma_f32_16x16x32_bf16 v[6:9], v[58:61], v[196:199], v[6:9]
	v_mfma_f32_16x16x32_bf16 v[86:89], v[54:57], v[176:179], v[82:85]
	v_mfma_f32_16x16x32_bf16 v[78:81], v[66:69], v[176:179], v[78:81]
	v_mfma_f32_16x16x32_bf16 v[70:73], v[54:57], v[184:187], v[70:73]
	v_mfma_f32_16x16x32_bf16 v[62:65], v[66:69], v[184:187], v[62:65]
	v_mfma_f32_16x16x32_bf16 v[42:45], v[54:57], v[192:195], v[42:45]
	v_mfma_f32_16x16x32_bf16 v[22:25], v[66:69], v[192:195], v[22:25]
	v_mfma_f32_16x16x32_bf16 v[14:17], v[54:57], v[200:203], v[14:17]
	v_mfma_f32_16x16x32_bf16 v[6:9], v[66:69], v[200:203], v[6:9]
	s_setprio 0
	s_setprio 1
	v_mfma_f32_16x16x32_bf16 v[26:29], v[160:163], v[74:77], v[26:29]
	v_mfma_f32_16x16x32_bf16 v[82:85], v[164:167], v[176:179], v[26:29]
	v_mfma_f32_16x16x32_bf16 v[26:29], v[168:171], v[74:77], v[34:37]
	v_mfma_f32_16x16x32_bf16 v[74:77], v[172:175], v[176:179], v[26:29]
	v_mfma_f32_16x16x32_bf16 v[26:29], v[160:163], v[180:183], v[38:41]
	v_mfma_f32_16x16x32_bf16 v[66:69], v[164:167], v[184:187], v[26:29]
	v_mfma_f32_16x16x32_bf16 v[26:29], v[168:171], v[180:183], v[46:49]
	v_mfma_f32_16x16x32_bf16 v[50:53], v[172:175], v[184:187], v[26:29]
	v_mfma_f32_16x16x32_bf16 v[26:29], v[160:163], v[188:191], v[30:33]
	v_mfma_f32_16x16x32_bf16 v[18:21], v[168:171], v[188:191], v[18:21]
	v_mfma_f32_16x16x32_bf16 v[10:13], v[160:163], v[196:199], v[10:13]
	v_mfma_f32_16x16x32_bf16 v[2:5], v[168:171], v[196:199], v[2:5]
	v_mfma_f32_16x16x32_bf16 v[30:33], v[164:167], v[192:195], v[26:29]
	v_mfma_f32_16x16x32_bf16 v[18:21], v[172:175], v[192:195], v[18:21]
	v_mfma_f32_16x16x32_bf16 v[10:13], v[164:167], v[200:203], v[10:13]
	v_mfma_f32_16x16x32_bf16 v[2:5], v[172:175], v[200:203], v[2:5]
	s_setprio 0
	s_barrier
	s_movk_i32 s17, 0x100
	s_andn2_b64 vcc, exec, s[42:43]
	s_mov_b64 s[46:47], -1
	s_mov_b64 s[42:43], 0
	s_cbranch_vccz .LBB0_1367
	s_and_b64 vcc, exec, s[14:15]
	s_cbranch_vccz .LBB0_1370
	s_barrier

; #define PG8_STAGE(bufoff, gbase, voff) do { _Pragma("unroll") for (int _i = 0; _i < 2; ++_i) \
;         __builtin_amdgcn_global_load_lds((const unsigned*)((const char*)(gbase) + (voff)[_i]), (LAS unsigned*)(lds + (bufoff) + ldsw + _i * 8192), 16, 0, 0); } while (0)
; #define PG8_LDA(dst, b, h) do { _Pragma("unroll") for (int m = 0; m < 4; ++m) _Pragma("unroll") for (int k = 0; k < 2; ++k) dst[m][k] = *(const LAS bf16x8*)(lds + PG8_SA(b, h) + aoff + m * 2048 + k * 1024); } while (0)
; #define PG8_LDB(dst, b, h) do { _Pragma("unroll") for (int n = 0; n < 2; ++n) _Pragma("unroll") for (int k = 0; k < 2; ++k) dst[n][k] = *(const LAS bf16x8*)(lds + PG8_SB(b, h) + boff + n * 2048 + k * 1024); } while (0)
; #define PG8_MMA(ai, bj, At, Bt) do { __builtin_amdgcn_s_setprio(1); _Pragma("unroll") for (int m = 0; m < 4; ++m) _Pragma("unroll") for (int n = 0; n < 2; ++n) _Pragma("unroll") for (int k = 0; k < 2; ++k) \
;         acc[ai][bj][m][n] = __builtin_amdgcn_mfma_f32_16x16x32_bf16(Bt[n][k], At[m][k], acc[ai][bj][m][n], 0, 0, 0); __builtin_amdgcn_s_setprio(0); } while (0)
; #define PG8_WAIT_V(n) asm volatile("s_waitcnt vmcnt(" #n ")" ::: "memory")
; #define PG8_WAIT_L(n) asm volatile("s_waitcnt lgkmcnt(" #n ")" ::: "memory")
; #define PG8_BAR __builtin_amdgcn_s_barrier()
; template <class Epi, class Sched, bool ALIGN_EPI, bool LAST_FUSED = false, bool PERM = false, bool CARRY = false>
; __device__ __forceinline__ void gemm_phase(LAS unsigned char* lds, const int tid, const int K, const int lda, const int ldb, const Sched& S, const Epi& E) {
;     ...
;             const bool last = (t == nt - 2);
;             const char* a1 = cA + (size_t)(t + 1) * kstep;
;             const char* a2 = last ? nA : cA + (size_t)(t + 2) * kstep; const char* b2 = last ? nB : cB + (size_t)(t + 2) * kstep;
;             const char* a3 = a2 + kstep; const char* b3 = b2 + kstep;
;             PG8_LDB(B0, 0, 0); PG8_LDB(B1, 0, 1); PG8_SCHED; PG8_LDA(At, 0, 0); PG8_STAGE(PG8_SA(1, 1), a1 + hstepA, voffA);
;             PG8_WAIT_V(8); PG8_WAIT_L(0); PG8_BAR; PG8_MMA(0, 0, At, B0); PG8_MMA(0, 1, At, B1); PG8_BAR; PG8_SCHED;
;             PG8_LDA(At, 0, 1); PG8_STAGE(PG8_SB(0, 0), b2, voffB); PG8_STAGE(PG8_SB(0, 1), b2 + hstepB, voffB); PG8_STAGE(PG8_SA(0, 0), a2, voffA);
;             PG8_WAIT_V(8); PG8_WAIT_L(0); PG8_BAR; PG8_MMA(1, 0, At, B0); PG8_MMA(1, 1, At, B1); PG8_BAR; PG8_SCHED;
.LBB0_1585:
	s_add_u32 s52, s42, s48
	s_addc_u32 s53, s43, s49
	s_add_u32 s76, s40, s48
	s_addc_u32 s77, s41, s49
	s_add_i32 s96, 0, 0x10000
	s_cmp_eq_u32 s3, s95
	s_cselect_b32 s53, s24, s53
	s_cselect_b32 s52, s55, s52
	s_cselect_b32 s77, s93, s77
	s_cselect_b32 s76, s94, s76
	s_add_i32 vcc_lo, 0, 0x14000
	v_add_u32_e32 v156, s96, v140
	v_add_u32_e32 v172, vcc_lo, v140
	ds_read_b128 v[142:145], v156
	ds_read_b128 v[146:149], v156 offset:1024
	ds_read_b128 v[150:153], v156 offset:2048
	ds_read_b128 v[156:159], v156 offset:3072
	ds_read_b128 v[160:163], v172
	ds_read_b128 v[164:167], v172 offset:1024
	ds_read_b128 v[168:171], v172 offset:2048
	ds_read_b128 v[172:175], v172 offset:3072
	v_lshl_add_u64 v[208:209], s[42:43], 0, v[138:139]
	s_add_i32 m0, s35, 0xc000
	ds_read_b128 v[176:179], v141
	ds_read_b128 v[180:183], v141 offset:1024
	ds_read_b128 v[184:187], v141 offset:2048
	ds_read_b128 v[188:191], v141 offset:3072
	ds_read_b128 v[192:195], v141 offset:4096
	ds_read_b128 v[196:199], v141 offset:5120
	ds_read_b128 v[200:203], v141 offset:6144
	ds_read_b128 v[204:207], v141 offset:7168
	global_load_lds_dwordx4 v[208:209], off
	v_lshl_add_u64 v[208:209], s[42:43], 0, v[128:129]
	s_add_i32 m0, s35, 0xe000
	s_nop 0
	global_load_lds_dwordx4 v[208:209], off
	s_waitcnt vmcnt(8)
	s_waitcnt lgkmcnt(0)
	s_barrier
	s_setprio 1
	v_mfma_f32_16x16x32_bf16 v[62:65], v[142:145], v[176:179], v[62:65]
	v_mfma_f32_16x16x32_bf16 v[42:45], v[150:153], v[176:179], v[42:45]
	v_mfma_f32_16x16x32_bf16 v[18:21], v[142:145], v[184:187], v[18:21]
	v_mfma_f32_16x16x32_bf16 v[14:17], v[150:153], v[184:187], v[14:17]
	v_mfma_f32_16x16x32_bf16 v[38:41], v[142:145], v[192:195], v[38:41]
	v_mfma_f32_16x16x32_bf16 v[30:33], v[150:153], v[192:195], v[30:33]
	v_mfma_f32_16x16x32_bf16 v[58:61], v[142:145], v[200:203], v[58:61]
	v_mfma_f32_16x16x32_bf16 v[54:57], v[150:153], v[200:203], v[54:57]
	v_mfma_f32_16x16x32_bf16 v[62:65], v[146:149], v[180:183], v[62:65]
	v_mfma_f32_16x16x32_bf16 v[42:45], v[156:159], v[180:183], v[42:45]
	v_mfma_f32_16x16x32_bf16 v[18:21], v[146:149], v[188:191], v[18:21]
	v_mfma_f32_16x16x32_bf16 v[14:17], v[156:159], v[188:191], v[14:17]
	v_mfma_f32_16x16x32_bf16 v[38:41], v[146:149], v[196:199], v[38:41]
	v_mfma_f32_16x16x32_bf16 v[30:33], v[156:159], v[196:199], v[30:33]
	v_mfma_f32_16x16x32_bf16 v[58:61], v[146:149], v[204:207], v[58:61]
	v_mfma_f32_16x16x32_bf16 v[54:57], v[156:159], v[204:207], v[54:57]
	s_setprio 0
	s_setprio 1
	v_mfma_f32_16x16x32_bf16 v[34:37], v[160:163], v[176:179], v[34:37]
	v_mfma_f32_16x16x32_bf16 v[2:5], v[168:171], v[176:179], v[2:5]
	v_mfma_f32_16x16x32_bf16 v[10:13], v[160:163], v[184:187], v[10:13]
	v_mfma_f32_16x16x32_bf16 v[6:9], v[168:171], v[184:187], v[6:9]
	v_mfma_f32_16x16x32_bf16 v[26:29], v[160:163], v[192:195], v[26:29]
	v_mfma_f32_16x16x32_bf16 v[22:25], v[168:171], v[192:195], v[22:25]
	v_mfma_f32_16x16x32_bf16 v[50:53], v[160:163], v[200:203], v[50:53]
	v_mfma_f32_16x16x32_bf16 v[46:49], v[168:171], v[200:203], v[46:49]
	v_mfma_f32_16x16x32_bf16 v[34:37], v[164:167], v[180:183], v[34:37]
	v_mfma_f32_16x16x32_bf16 v[2:5], v[172:175], v[180:183], v[2:5]
	v_mfma_f32_16x16x32_bf16 v[10:13], v[164:167], v[188:191], v[10:13]
	v_mfma_f32_16x16x32_bf16 v[6:9], v[172:175], v[188:191], v[6:9]
	v_mfma_f32_16x16x32_bf16 v[26:29], v[164:167], v[196:199], v[26:29]
	v_mfma_f32_16x16x32_bf16 v[22:25], v[172:175], v[196:199], v[22:25]
	v_mfma_f32_16x16x32_bf16 v[50:53], v[164:167], v[204:207], v[50:53]
	v_mfma_f32_16x16x32_bf16 v[46:49], v[172:175], v[204:207], v[46:49]
	s_setprio 0
	s_barrier
	s_add_i32 s96, s96, s87
	v_lshl_add_u64 v[208:209], s[76:77], 0, v[0:1]
	s_mov_b32 m0, s96
	ds_read_b128 v[176:179], v141 offset:16384
	ds_read_b128 v[180:183], v141 offset:17408
	ds_read_b128 v[184:187], v141 offset:18432
	ds_read_b128 v[188:191], v141 offset:19456
	ds_read_b128 v[192:195], v141 offset:20480
	ds_read_b128 v[196:199], v141 offset:21504
	ds_read_b128 v[200:203], v141 offset:22528
	ds_read_b128 v[204:207], v141 offset:23552
	global_load_lds_dwordx4 v[208:209], off
	s_add_i32 m0, s96, 0x2000
	s_add_u32 s96, s76, 0x80000
	v_lshl_add_u64 v[210:211], s[76:77], 0, v[122:123]
	s_addc_u32 s97, s77, 0
	s_add_i32 vcc_lo, vcc_lo, s87
	global_load_lds_dwordx4 v[210:211], off
	v_lshl_add_u64 v[212:213], s[96:97], 0, v[0:1]
	s_mov_b32 m0, vcc_lo
	v_lshl_add_u64 v[214:215], s[52:53], 0, v[122:123]
	global_load_lds_dwordx4 v[212:213], off
	v_lshl_add_u64 v[212:213], s[96:97], 0, v[122:123]
	s_add_i32 m0, vcc_lo, 0x2000
	s_nop 0
	global_load_lds_dwordx4 v[212:213], off
	v_lshl_add_u64 v[212:213], s[52:53], 0, v[0:1]
	s_mov_b32 m0, s35
	s_nop 0
	global_load_lds_dwordx4 v[212:213], off
	s_mov_b32 m0, s28
	s_nop 0
	global_load_lds_dwordx4 v[214:215], off
	s_waitcnt vmcnt(8)
	s_waitcnt lgkmcnt(0)
	s_barrier
; #define PG8_STAGE(bufoff, gbase, voff) do { _Pragma("unroll") for (int _i = 0; _i < 2; ++_i) \
;         __builtin_amdgcn_global_load_lds((const unsigned*)((const char*)(gbase) + (voff)[_i]), (LAS unsigned*)(lds + (bufoff) + ldsw + _i * 8192), 16, 0, 0); } while (0)
; #define PG8_LDA(dst, b, h) do { _Pragma("unroll") for (int m = 0; m < 4; ++m) _Pragma("unroll") for (int k = 0; k < 2; ++k) dst[m][k] = *(const LAS bf16x8*)(lds + PG8_SA(b, h) + aoff + m * 2048 + k * 1024); } while (0)
; #define PG8_LDB(dst, b, h) do { _Pragma("unroll") for (int n = 0; n < 2; ++n) _Pragma("unroll") for (int k = 0; k < 2; ++k) dst[n][k] = *(const LAS bf16x8*)(lds + PG8_SB(b, h) + boff + n * 2048 + k * 1024); } while (0)
; #define PG8_MMA(ai, bj, At, Bt) do { __builtin_amdgcn_s_setprio(1); _Pragma("unroll") for (int m = 0; m < 4; ++m) _Pragma("unroll") for (int n = 0; n < 2; ++n) _Pragma("unroll") for (int k = 0; k < 2; ++k) \
;         acc[ai][bj][m][n] = __builtin_amdgcn_mfma_f32_16x16x32_bf16(Bt[n][k], At[m][k], acc[ai][bj][m][n], 0, 0, 0); __builtin_amdgcn_s_setprio(0); } while (0)
; #define PG8_WAIT_V(n) asm volatile("s_waitcnt vmcnt(" #n ")" ::: "memory")
; #define PG8_WAIT_L(n) asm volatile("s_waitcnt lgkmcnt(" #n ")" ::: "memory")
; #define PG8_BAR __builtin_amdgcn_s_barrier()
; #define PG8_SCHED __builtin_amdgcn_sched_barrier(0)
; template <class Epi, class Sched, bool ALIGN_EPI, bool LAST_FUSED = false, bool PERM = false, bool CARRY = false>
; __device__ __forceinline__ void gemm_phase(LAS unsigned char* lds, const int tid, const int K, const int lda, const int ldb, const Sched& S, const Epi& E) {
;     ...
;             PG8_WAIT_V(8); PG8_WAIT_L(0); PG8_BAR; PG8_MMA(1, 0, At, B0); PG8_MMA(1, 1, At, B1); PG8_BAR; PG8_SCHED;
;             PG8_LDB(B0, 1, 0); PG8_LDB(B1, 1, 1); PG8_SCHED; PG8_LDA(At, 1, 0); PG8_STAGE(PG8_SA(0, 1), a2 + hstepA, voffA);
;             PG8_WAIT_V(8); PG8_WAIT_L(0); PG8_BAR; PG8_MMA(0, 0, At, B0); PG8_MMA(0, 1, At, B1); PG8_BAR; PG8_SCHED;
	s_setprio 1
	v_mfma_f32_16x16x32_bf16 v[78:81], v[142:145], v[176:179], v[78:81]
	v_mfma_f32_16x16x32_bf16 v[74:77], v[150:153], v[176:179], v[74:77]
	v_mfma_f32_16x16x32_bf16 v[98:101], v[142:145], v[184:187], v[98:101]
	v_mfma_f32_16x16x32_bf16 v[94:97], v[150:153], v[184:187], v[94:97]
	v_mfma_f32_16x16x32_bf16 v[118:121], v[142:145], v[192:195], v[118:121]
	v_mfma_f32_16x16x32_bf16 v[114:117], v[150:153], v[192:195], v[114:117]
	v_mfma_f32_16x16x32_bf16 v[134:137], v[142:145], v[200:203], v[134:137]
	v_mfma_f32_16x16x32_bf16 v[130:133], v[150:153], v[200:203], v[130:133]
	v_mfma_f32_16x16x32_bf16 v[78:81], v[146:149], v[180:183], v[78:81]
	v_mfma_f32_16x16x32_bf16 v[74:77], v[156:159], v[180:183], v[74:77]
	v_mfma_f32_16x16x32_bf16 v[98:101], v[146:149], v[188:191], v[98:101]
	v_mfma_f32_16x16x32_bf16 v[94:97], v[156:159], v[188:191], v[94:97]
	v_mfma_f32_16x16x32_bf16 v[118:121], v[146:149], v[196:199], v[118:121]
	v_mfma_f32_16x16x32_bf16 v[114:117], v[156:159], v[196:199], v[114:117]
	v_mfma_f32_16x16x32_bf16 v[134:137], v[146:149], v[204:207], v[134:137]
	v_mfma_f32_16x16x32_bf16 v[130:133], v[156:159], v[204:207], v[130:133]
	s_setprio 0
	s_setprio 1
	v_mfma_f32_16x16x32_bf16 v[70:73], v[160:163], v[176:179], v[70:73]
	v_mfma_f32_16x16x32_bf16 v[66:69], v[168:171], v[176:179], v[66:69]
	v_mfma_f32_16x16x32_bf16 v[90:93], v[160:163], v[184:187], v[90:93]
	v_mfma_f32_16x16x32_bf16 v[86:89], v[168:171], v[184:187], v[86:89]
	v_mfma_f32_16x16x32_bf16 v[110:113], v[160:163], v[192:195], v[110:113]
	v_mfma_f32_16x16x32_bf16 v[106:109], v[168:171], v[192:195], v[106:109]
	v_mfma_f32_16x16x32_bf16 v[102:105], v[160:163], v[200:203], v[102:105]
	v_mfma_f32_16x16x32_bf16 v[82:85], v[168:171], v[200:203], v[82:85]
	v_mfma_f32_16x16x32_bf16 v[70:73], v[164:167], v[180:183], v[70:73]
	v_mfma_f32_16x16x32_bf16 v[66:69], v[172:175], v[180:183], v[66:69]
	v_mfma_f32_16x16x32_bf16 v[90:93], v[164:167], v[188:191], v[90:93]
	v_mfma_f32_16x16x32_bf16 v[86:89], v[172:175], v[188:191], v[86:89]
	v_mfma_f32_16x16x32_bf16 v[110:113], v[164:167], v[196:199], v[110:113]
	v_mfma_f32_16x16x32_bf16 v[106:109], v[172:175], v[196:199], v[106:109]
	v_mfma_f32_16x16x32_bf16 v[102:105], v[164:167], v[204:207], v[102:105]
	v_mfma_f32_16x16x32_bf16 v[82:85], v[172:175], v[204:207], v[82:85]
	s_setprio 0
	s_barrier
	s_add_i32 s96, 0, 0x18000
	s_add_i32 s97, 0, 0x1c000
	v_add_u32_e32 v156, s96, v140
	v_add_u32_e32 v172, s97, v140
	ds_read_b128 v[142:145], v156
	ds_read_b128 v[146:149], v156 offset:1024
	ds_read_b128 v[150:153], v156 offset:2048
	ds_read_b128 v[156:159], v156 offset:3072
	ds_read_b128 v[160:163], v172
	ds_read_b128 v[164:167], v172 offset:1024
	ds_read_b128 v[168:171], v172 offset:2048
	ds_read_b128 v[172:175], v172 offset:3072
	s_add_u32 s52, s52, 0x80000
	s_addc_u32 s53, s53, 0
	s_mov_b32 m0, s29
	v_lshl_add_u64 v[216:217], s[52:53], 0, v[0:1]
	ds_read_b128 v[176:179], v141 offset:32768
	ds_read_b128 v[180:183], v141 offset:33792
	ds_read_b128 v[184:187], v141 offset:34816
	ds_read_b128 v[188:191], v141 offset:35840
	ds_read_b128 v[192:195], v141 offset:36864
	ds_read_b128 v[196:199], v141 offset:37888
	ds_read_b128 v[200:203], v141 offset:38912
	ds_read_b128 v[204:207], v141 offset:39936
	global_load_lds_dwordx4 v[216:217], off
	v_lshl_add_u64 v[216:217], s[52:53], 0, v[122:123]
	s_mov_b32 m0, s14
	s_nop 0
	global_load_lds_dwordx4 v[216:217], off
	s_waitcnt vmcnt(8)
	s_waitcnt lgkmcnt(0)
	s_barrier
	s_setprio 1
	v_mfma_f32_16x16x32_bf16 v[62:65], v[142:145], v[176:179], v[62:65]
	v_mfma_f32_16x16x32_bf16 v[42:45], v[150:153], v[176:179], v[42:45]
	v_mfma_f32_16x16x32_bf16 v[18:21], v[142:145], v[184:187], v[18:21]
	v_mfma_f32_16x16x32_bf16 v[14:17], v[150:153], v[184:187], v[14:17]
	v_mfma_f32_16x16x32_bf16 v[38:41], v[142:145], v[192:195], v[38:41]
	v_mfma_f32_16x16x32_bf16 v[30:33], v[150:153], v[192:195], v[30:33]
	v_mfma_f32_16x16x32_bf16 v[58:61], v[142:145], v[200:203], v[58:61]
	v_mfma_f32_16x16x32_bf16 v[54:57], v[150:153], v[200:203], v[54:57]
	v_mfma_f32_16x16x32_bf16 v[62:65], v[146:149], v[180:183], v[62:65]
	v_mfma_f32_16x16x32_bf16 v[42:45], v[156:159], v[180:183], v[42:45]
	v_mfma_f32_16x16x32_bf16 v[18:21], v[146:149], v[188:191], v[18:21]
	v_mfma_f32_16x16x32_bf16 v[14:17], v[156:159], v[188:191], v[14:17]
	v_mfma_f32_16x16x32_bf16 v[38:41], v[146:149], v[196:199], v[38:41]
	v_mfma_f32_16x16x32_bf16 v[30:33], v[156:159], v[196:199], v[30:33]
	v_mfma_f32_16x16x32_bf16 v[58:61], v[146:149], v[204:207], v[58:61]
	v_mfma_f32_16x16x32_bf16 v[54:57], v[156:159], v[204:207], v[54:57]
	s_setprio 0
	s_setprio 1
	v_mfma_f32_16x16x32_bf16 v[34:37], v[160:163], v[176:179], v[34:37]
	v_mfma_f32_16x16x32_bf16 v[2:5], v[168:171], v[176:179], v[2:5]
	v_mfma_f32_16x16x32_bf16 v[10:13], v[160:163], v[184:187], v[10:13]
	v_mfma_f32_16x16x32_bf16 v[6:9], v[168:171], v[184:187], v[6:9]
	v_mfma_f32_16x16x32_bf16 v[26:29], v[160:163], v[192:195], v[26:29]
	v_mfma_f32_16x16x32_bf16 v[22:25], v[168:171], v[192:195], v[22:25]
	v_mfma_f32_16x16x32_bf16 v[50:53], v[160:163], v[200:203], v[50:53]
	v_mfma_f32_16x16x32_bf16 v[46:49], v[168:171], v[200:203], v[46:49]
	v_mfma_f32_16x16x32_bf16 v[34:37], v[164:167], v[180:183], v[34:37]
	v_mfma_f32_16x16x32_bf16 v[2:5], v[172:175], v[180:183], v[2:5]
	v_mfma_f32_16x16x32_bf16 v[10:13], v[164:167], v[188:191], v[10:13]
	v_mfma_f32_16x16x32_bf16 v[6:9], v[172:175], v[188:191], v[6:9]
	v_mfma_f32_16x16x32_bf16 v[26:29], v[164:167], v[196:199], v[26:29]
	v_mfma_f32_16x16x32_bf16 v[22:25], v[172:175], v[196:199], v[22:25]
	v_mfma_f32_16x16x32_bf16 v[50:53], v[164:167], v[204:207], v[50:53]
	v_mfma_f32_16x16x32_bf16 v[46:49], v[172:175], v[204:207], v[46:49]
	s_setprio 0
	s_barrier
; #define PG8_STAGE(bufoff, gbase, voff) do { _Pragma("unroll") for (int _i = 0; _i < 2; ++_i) \
;         __builtin_amdgcn_global_load_lds((const unsigned*)((const char*)(gbase) + (voff)[_i]), (LAS unsigned*)(lds + (bufoff) + ldsw + _i * 8192), 16, 0, 0); } while (0)
; #define PG8_LDA(dst, b, h) do { _Pragma("unroll") for (int m = 0; m < 4; ++m) _Pragma("unroll") for (int k = 0; k < 2; ++k) dst[m][k] = *(const LAS bf16x8*)(lds + PG8_SA(b, h) + aoff + m * 2048 + k * 1024); } while (0)
; #define PG8_MMA(ai, bj, At, Bt) do { __builtin_amdgcn_s_setprio(1); _Pragma("unroll") for (int m = 0; m < 4; ++m) _Pragma("unroll") for (int n = 0; n < 2; ++n) _Pragma("unroll") for (int k = 0; k < 2; ++k) \
;         acc[ai][bj][m][n] = __builtin_amdgcn_mfma_f32_16x16x32_bf16(Bt[n][k], At[m][k], acc[ai][bj][m][n], 0, 0, 0); __builtin_amdgcn_s_setprio(0); } while (0)
; #define PG8_WAIT_V(n) asm volatile("s_waitcnt vmcnt(" #n ")" ::: "memory")
; #define PG8_WAIT_L(n) asm volatile("s_waitcnt lgkmcnt(" #n ")" ::: "memory")
; #define PG8_BAR __builtin_amdgcn_s_barrier()
; #define PG8_SCHED __builtin_amdgcn_sched_barrier(0)
; template <class Epi, class Sched, bool ALIGN_EPI, bool LAST_FUSED = false, bool PERM = false, bool CARRY = false>
; __device__ __forceinline__ void gemm_phase(LAS unsigned char* lds, const int tid, const int K, const int lda, const int ldb, const Sched& S, const Epi& E) {
;     ...
;             PG8_LDA(At, 1, 1); PG8_STAGE(PG8_SB(1, 0), b3, voffB); PG8_STAGE(PG8_SB(1, 1), b3 + hstepB, voffB); PG8_STAGE(PG8_SA(1, 0), a3, voffA);
;             PG8_WAIT_V(8); PG8_WAIT_L(0); PG8_BAR; PG8_MMA(1, 0, At, B0); PG8_MMA(1, 1, At, B1); PG8_BAR; PG8_SCHED;
;         }
;         if constexpr (ALIGN_EPI) { if (wr == 0) PG8_BAR; }
	s_add_i32 s52, s96, s87
	v_lshl_add_u64 v[208:209], v[208:209], 0, s[68:69]
	s_mov_b32 m0, s52
	ds_read_b128 v[176:179], v141 offset:49152
	ds_read_b128 v[180:183], v141 offset:50176
	ds_read_b128 v[184:187], v141 offset:51200
	ds_read_b128 v[188:191], v141 offset:52224
	ds_read_b128 v[192:195], v141 offset:53248
	ds_read_b128 v[196:199], v141 offset:54272
	ds_read_b128 v[200:203], v141 offset:55296
	ds_read_b128 v[204:207], v141 offset:56320
	global_load_lds_dwordx4 v[208:209], off
	s_add_i32 m0, s52, 0x2000
	s_add_u32 s52, s76, 0x80080
	v_lshl_add_u64 v[208:209], v[210:211], 0, s[68:69]
	s_addc_u32 s53, s77, 0
	s_add_i32 s76, s97, s87
	global_load_lds_dwordx4 v[208:209], off
	v_lshl_add_u64 v[208:209], s[52:53], 0, v[0:1]
	s_mov_b32 m0, s76
	s_nop 0
	global_load_lds_dwordx4 v[208:209], off
	v_lshl_add_u64 v[208:209], s[52:53], 0, v[122:123]
	s_add_i32 m0, s76, 0x2000
	s_nop 0
	global_load_lds_dwordx4 v[208:209], off
	v_lshl_add_u64 v[208:209], v[212:213], 0, s[68:69]
	s_mov_b32 m0, s85
	s_nop 0
	global_load_lds_dwordx4 v[208:209], off
	v_lshl_add_u64 v[208:209], v[214:215], 0, s[68:69]
	s_mov_b32 m0, s89
	s_nop 0
	global_load_lds_dwordx4 v[208:209], off
	s_waitcnt vmcnt(8)
	s_waitcnt lgkmcnt(0)
	s_barrier
	s_setprio 1
	v_mfma_f32_16x16x32_bf16 v[78:81], v[142:145], v[176:179], v[78:81]
	v_mfma_f32_16x16x32_bf16 v[74:77], v[150:153], v[176:179], v[74:77]
	v_mfma_f32_16x16x32_bf16 v[98:101], v[142:145], v[184:187], v[98:101]
	v_mfma_f32_16x16x32_bf16 v[94:97], v[150:153], v[184:187], v[94:97]
	v_mfma_f32_16x16x32_bf16 v[118:121], v[142:145], v[192:195], v[118:121]
	v_mfma_f32_16x16x32_bf16 v[114:117], v[150:153], v[192:195], v[114:117]
	v_mfma_f32_16x16x32_bf16 v[134:137], v[142:145], v[200:203], v[134:137]
	v_mfma_f32_16x16x32_bf16 v[130:133], v[150:153], v[200:203], v[130:133]
	v_mfma_f32_16x16x32_bf16 v[78:81], v[146:149], v[180:183], v[78:81]
	v_mfma_f32_16x16x32_bf16 v[74:77], v[156:159], v[180:183], v[74:77]
	v_mfma_f32_16x16x32_bf16 v[98:101], v[146:149], v[188:191], v[98:101]
	v_mfma_f32_16x16x32_bf16 v[94:97], v[156:159], v[188:191], v[94:97]
	v_mfma_f32_16x16x32_bf16 v[118:121], v[146:149], v[196:199], v[118:121]
	v_mfma_f32_16x16x32_bf16 v[114:117], v[156:159], v[196:199], v[114:117]
	v_mfma_f32_16x16x32_bf16 v[134:137], v[146:149], v[204:207], v[134:137]
	v_mfma_f32_16x16x32_bf16 v[130:133], v[156:159], v[204:207], v[130:133]
	s_setprio 0
	s_setprio 1
	v_mfma_f32_16x16x32_bf16 v[70:73], v[160:163], v[176:179], v[70:73]
	v_mfma_f32_16x16x32_bf16 v[66:69], v[168:171], v[176:179], v[66:69]
	v_mfma_f32_16x16x32_bf16 v[90:93], v[160:163], v[184:187], v[90:93]
	v_mfma_f32_16x16x32_bf16 v[86:89], v[168:171], v[184:187], v[86:89]
	v_mfma_f32_16x16x32_bf16 v[110:113], v[160:163], v[192:195], v[110:113]
	v_mfma_f32_16x16x32_bf16 v[106:109], v[168:171], v[192:195], v[106:109]
	v_mfma_f32_16x16x32_bf16 v[102:105], v[160:163], v[200:203], v[102:105]
	v_mfma_f32_16x16x32_bf16 v[82:85], v[168:171], v[200:203], v[82:85]
	v_mfma_f32_16x16x32_bf16 v[70:73], v[164:167], v[180:183], v[70:73]
	v_mfma_f32_16x16x32_bf16 v[66:69], v[172:175], v[180:183], v[66:69]
	v_mfma_f32_16x16x32_bf16 v[90:93], v[164:167], v[188:191], v[90:93]
	v_mfma_f32_16x16x32_bf16 v[86:89], v[172:175], v[188:191], v[86:89]
	v_mfma_f32_16x16x32_bf16 v[110:113], v[164:167], v[196:199], v[110:113]
	v_mfma_f32_16x16x32_bf16 v[106:109], v[172:175], v[196:199], v[106:109]
	v_mfma_f32_16x16x32_bf16 v[102:105], v[164:167], v[204:207], v[102:105]
	v_mfma_f32_16x16x32_bf16 v[82:85], v[172:175], v[204:207], v[82:85]
	s_setprio 0
	s_barrier
	s_add_i32 s52, s95, 2
	s_add_u32 s48, s48, 0x100
	s_addc_u32 s49, s49, 0
	v_lshl_add_u64 v[138:139], v[138:139], 0, s[72:73]
	v_lshl_add_u64 v[128:129], v[128:129], 0, s[72:73]
	s_cmp_ge_i32 s95, s3
	s_mov_b32 s95, s52
	s_cbranch_scc0 .LBB0_1585
	s_and_b64 vcc, exec, s[36:37]
	s_cbranch_vccz .LBB0_1588
	s_barrier

; #define PG8_STAGE(bufoff, gbase, voff) do { _Pragma("unroll") for (int _i = 0; _i < 2; ++_i) \
;         __builtin_amdgcn_global_load_lds((const unsigned*)((const char*)(gbase) + (voff)[_i]), (LAS unsigned*)(lds + (bufoff) + ldsw + _i * 8192), 16, 0, 0); } while (0)
; #define PG8_LDA(dst, b, h) do { _Pragma("unroll") for (int m = 0; m < 4; ++m) _Pragma("unroll") for (int k = 0; k < 2; ++k) dst[m][k] = *(const LAS bf16x8*)(lds + PG8_SA(b, h) + aoff + m * 2048 + k * 1024); } while (0)
; #define PG8_LDB(dst, b, h) do { _Pragma("unroll") for (int n = 0; n < 2; ++n) _Pragma("unroll") for (int k = 0; k < 2; ++k) dst[n][k] = *(const LAS bf16x8*)(lds + PG8_SB(b, h) + boff + n * 2048 + k * 1024); } while (0)
; #define PG8_MMA(ai, bj, At, Bt) do { __builtin_amdgcn_s_setprio(1); _Pragma("unroll") for (int m = 0; m < 4; ++m) _Pragma("unroll") for (int n = 0; n < 2; ++n) _Pragma("unroll") for (int k = 0; k < 2; ++k) \
;         acc[ai][bj][m][n] = __builtin_amdgcn_mfma_f32_16x16x32_bf16(Bt[n][k], At[m][k], acc[ai][bj][m][n], 0, 0, 0); __builtin_amdgcn_s_setprio(0); } while (0)
; #define PG8_WAIT_V(n) asm volatile("s_waitcnt vmcnt(" #n ")" ::: "memory")
; #define PG8_WAIT_L(n) asm volatile("s_waitcnt lgkmcnt(" #n ")" ::: "memory")
; #define PG8_BAR __builtin_amdgcn_s_barrier()
; template <class Epi, class Sched, bool ALIGN_EPI, bool LAST_FUSED = false, bool PERM = false, bool CARRY = false>
; __device__ __forceinline__ void gemm_phase(LAS unsigned char* lds, const int tid, const int K, const int lda, const int ldb, const Sched& S, const Epi& E) {
;     ...
;             const bool last = (t == nt - 2);
;             const char* a1 = cA + (size_t)(t + 1) * kstep;
;             const char* a2 = last ? nA : cA + (size_t)(t + 2) * kstep; const char* b2 = last ? nB : cB + (size_t)(t + 2) * kstep;
;             const char* a3 = a2 + kstep; const char* b3 = b2 + kstep;
;             PG8_LDB(B0, 0, 0); PG8_LDB(B1, 0, 1); PG8_SCHED; PG8_LDA(At, 0, 0); PG8_STAGE(PG8_SA(1, 1), a1 + hstepA, voffA);
;             PG8_WAIT_V(8); PG8_WAIT_L(0); PG8_BAR; PG8_MMA(0, 0, At, B0); PG8_MMA(0, 1, At, B1); PG8_BAR; PG8_SCHED;
;             PG8_LDA(At, 0, 1); PG8_STAGE(PG8_SB(0, 0), b2, voffB); PG8_STAGE(PG8_SB(0, 1), b2 + hstepB, voffB); PG8_STAGE(PG8_SA(0, 0), a2, voffA);
;             PG8_WAIT_V(8); PG8_WAIT_L(0); PG8_BAR; PG8_MMA(1, 0, At, B0); PG8_MMA(1, 1, At, B1); PG8_BAR; PG8_SCHED;
.LBB0_1662:
	s_add_u32 s52, s38, s48
	s_addc_u32 s53, s39, s49
	s_add_u32 s66, s40, s48
	s_addc_u32 s67, s41, s49
	s_waitcnt lgkmcnt(0)
	s_add_i32 s90, 0, 0x10000
	s_cmp_eq_u32 s3, s89
	s_cselect_b32 s53, s24, s53
	s_cselect_b32 s52, s85, s52
	s_cselect_b32 s67, s86, s67
	s_cselect_b32 s66, s87, s66
	s_add_i32 s92, 0, 0x14000
	v_add_u32_e32 v156, s90, v140
	v_add_u32_e32 v172, s92, v140
	ds_read_b128 v[142:145], v156
	ds_read_b128 v[146:149], v156 offset:1024
	ds_read_b128 v[150:153], v156 offset:2048
	ds_read_b128 v[156:159], v156 offset:3072
	ds_read_b128 v[160:163], v172
	ds_read_b128 v[164:167], v172 offset:1024
	ds_read_b128 v[168:171], v172 offset:2048
	ds_read_b128 v[172:175], v172 offset:3072
	v_lshl_add_u64 v[208:209], s[38:39], 0, v[138:139]
	s_add_i32 m0, s35, 0xc000
	ds_read_b128 v[176:179], v141
	ds_read_b128 v[180:183], v141 offset:1024
	ds_read_b128 v[184:187], v141 offset:2048
	ds_read_b128 v[188:191], v141 offset:3072
	ds_read_b128 v[192:195], v141 offset:4096
	ds_read_b128 v[196:199], v141 offset:5120
	ds_read_b128 v[200:203], v141 offset:6144
	ds_read_b128 v[204:207], v141 offset:7168
	global_load_lds_dwordx4 v[208:209], off
	v_lshl_add_u64 v[208:209], s[38:39], 0, v[128:129]
	s_add_i32 m0, s35, 0xe000
	s_nop 0
	global_load_lds_dwordx4 v[208:209], off
	s_waitcnt vmcnt(8)
	s_waitcnt lgkmcnt(0)
	s_barrier
	s_setprio 1
	v_mfma_f32_16x16x32_bf16 v[62:65], v[142:145], v[176:179], v[62:65]
	v_mfma_f32_16x16x32_bf16 v[42:45], v[150:153], v[176:179], v[42:45]
	v_mfma_f32_16x16x32_bf16 v[18:21], v[142:145], v[184:187], v[18:21]
	v_mfma_f32_16x16x32_bf16 v[14:17], v[150:153], v[184:187], v[14:17]
	v_mfma_f32_16x16x32_bf16 v[38:41], v[142:145], v[192:195], v[38:41]
	v_mfma_f32_16x16x32_bf16 v[30:33], v[150:153], v[192:195], v[30:33]
	v_mfma_f32_16x16x32_bf16 v[58:61], v[142:145], v[200:203], v[58:61]
	v_mfma_f32_16x16x32_bf16 v[54:57], v[150:153], v[200:203], v[54:57]
	v_mfma_f32_16x16x32_bf16 v[62:65], v[146:149], v[180:183], v[62:65]
	v_mfma_f32_16x16x32_bf16 v[42:45], v[156:159], v[180:183], v[42:45]
	v_mfma_f32_16x16x32_bf16 v[18:21], v[146:149], v[188:191], v[18:21]
	v_mfma_f32_16x16x32_bf16 v[14:17], v[156:159], v[188:191], v[14:17]
	v_mfma_f32_16x16x32_bf16 v[38:41], v[146:149], v[196:199], v[38:41]
	v_mfma_f32_16x16x32_bf16 v[30:33], v[156:159], v[196:199], v[30:33]
	v_mfma_f32_16x16x32_bf16 v[58:61], v[146:149], v[204:207], v[58:61]
	v_mfma_f32_16x16x32_bf16 v[54:57], v[156:159], v[204:207], v[54:57]
	s_setprio 0
	s_setprio 1
	v_mfma_f32_16x16x32_bf16 v[34:37], v[160:163], v[176:179], v[34:37]
	v_mfma_f32_16x16x32_bf16 v[2:5], v[168:171], v[176:179], v[2:5]
	v_mfma_f32_16x16x32_bf16 v[10:13], v[160:163], v[184:187], v[10:13]
	v_mfma_f32_16x16x32_bf16 v[6:9], v[168:171], v[184:187], v[6:9]
	v_mfma_f32_16x16x32_bf16 v[26:29], v[160:163], v[192:195], v[26:29]
	v_mfma_f32_16x16x32_bf16 v[22:25], v[168:171], v[192:195], v[22:25]
	v_mfma_f32_16x16x32_bf16 v[50:53], v[160:163], v[200:203], v[50:53]
	v_mfma_f32_16x16x32_bf16 v[46:49], v[168:171], v[200:203], v[46:49]
	v_mfma_f32_16x16x32_bf16 v[34:37], v[164:167], v[180:183], v[34:37]
	v_mfma_f32_16x16x32_bf16 v[2:5], v[172:175], v[180:183], v[2:5]
	v_mfma_f32_16x16x32_bf16 v[10:13], v[164:167], v[188:191], v[10:13]
	v_mfma_f32_16x16x32_bf16 v[6:9], v[172:175], v[188:191], v[6:9]
	v_mfma_f32_16x16x32_bf16 v[26:29], v[164:167], v[196:199], v[26:29]
	v_mfma_f32_16x16x32_bf16 v[22:25], v[172:175], v[196:199], v[22:25]
	v_mfma_f32_16x16x32_bf16 v[50:53], v[164:167], v[204:207], v[50:53]
	v_mfma_f32_16x16x32_bf16 v[46:49], v[172:175], v[204:207], v[46:49]
	s_setprio 0
	s_barrier
	s_add_i32 s90, s90, s76
	v_lshl_add_u64 v[208:209], s[66:67], 0, v[0:1]
	s_mov_b32 m0, s90
	ds_read_b128 v[176:179], v141 offset:16384
	ds_read_b128 v[180:183], v141 offset:17408
	ds_read_b128 v[184:187], v141 offset:18432
	ds_read_b128 v[188:191], v141 offset:19456
	ds_read_b128 v[192:195], v141 offset:20480
	ds_read_b128 v[196:199], v141 offset:21504
	ds_read_b128 v[200:203], v141 offset:22528
	ds_read_b128 v[204:207], v141 offset:23552
	global_load_lds_dwordx4 v[208:209], off
	s_add_i32 m0, s90, 0x2000
	s_add_u32 s90, s66, 0x100000
	v_lshl_add_u64 v[210:211], s[66:67], 0, v[122:123]
	s_addc_u32 s91, s67, 0
	s_add_i32 s92, s92, s76
	global_load_lds_dwordx4 v[210:211], off
	v_lshl_add_u64 v[212:213], s[90:91], 0, v[0:1]
	s_mov_b32 m0, s92
	v_lshl_add_u64 v[214:215], s[52:53], 0, v[122:123]
	global_load_lds_dwordx4 v[212:213], off
	v_lshl_add_u64 v[212:213], s[90:91], 0, v[122:123]
	s_add_i32 m0, s92, 0x2000
	s_nop 0
	global_load_lds_dwordx4 v[212:213], off
	v_lshl_add_u64 v[212:213], s[52:53], 0, v[0:1]
	s_mov_b32 m0, s35
	s_nop 0
	global_load_lds_dwordx4 v[212:213], off
	s_mov_b32 m0, s28
	s_nop 0
	global_load_lds_dwordx4 v[214:215], off
	s_waitcnt vmcnt(8)
	s_waitcnt lgkmcnt(0)
	s_barrier
; #define PG8_STAGE(bufoff, gbase, voff) do { _Pragma("unroll") for (int _i = 0; _i < 2; ++_i) \
;         __builtin_amdgcn_global_load_lds((const unsigned*)((const char*)(gbase) + (voff)[_i]), (LAS unsigned*)(lds + (bufoff) + ldsw + _i * 8192), 16, 0, 0); } while (0)
; #define PG8_LDA(dst, b, h) do { _Pragma("unroll") for (int m = 0; m < 4; ++m) _Pragma("unroll") for (int k = 0; k < 2; ++k) dst[m][k] = *(const LAS bf16x8*)(lds + PG8_SA(b, h) + aoff + m * 2048 + k * 1024); } while (0)
; #define PG8_LDB(dst, b, h) do { _Pragma("unroll") for (int n = 0; n < 2; ++n) _Pragma("unroll") for (int k = 0; k < 2; ++k) dst[n][k] = *(const LAS bf16x8*)(lds + PG8_SB(b, h) + boff + n * 2048 + k * 1024); } while (0)
; #define PG8_MMA(ai, bj, At, Bt) do { __builtin_amdgcn_s_setprio(1); _Pragma("unroll") for (int m = 0; m < 4; ++m) _Pragma("unroll") for (int n = 0; n < 2; ++n) _Pragma("unroll") for (int k = 0; k < 2; ++k) \
;         acc[ai][bj][m][n] = __builtin_amdgcn_mfma_f32_16x16x32_bf16(Bt[n][k], At[m][k], acc[ai][bj][m][n], 0, 0, 0); __builtin_amdgcn_s_setprio(0); } while (0)
; #define PG8_WAIT_V(n) asm volatile("s_waitcnt vmcnt(" #n ")" ::: "memory")
; #define PG8_WAIT_L(n) asm volatile("s_waitcnt lgkmcnt(" #n ")" ::: "memory")
; #define PG8_BAR __builtin_amdgcn_s_barrier()
; #define PG8_SCHED __builtin_amdgcn_sched_barrier(0)
; template <class Epi, class Sched, bool ALIGN_EPI, bool LAST_FUSED = false, bool PERM = false, bool CARRY = false>
; __device__ __forceinline__ void gemm_phase(LAS unsigned char* lds, const int tid, const int K, const int lda, const int ldb, const Sched& S, const Epi& E) {
;     ...
;             PG8_WAIT_V(8); PG8_WAIT_L(0); PG8_BAR; PG8_MMA(1, 0, At, B0); PG8_MMA(1, 1, At, B1); PG8_BAR; PG8_SCHED;
;             PG8_LDB(B0, 1, 0); PG8_LDB(B1, 1, 1); PG8_SCHED; PG8_LDA(At, 1, 0); PG8_STAGE(PG8_SA(0, 1), a2 + hstepA, voffA);
;             PG8_WAIT_V(8); PG8_WAIT_L(0); PG8_BAR; PG8_MMA(0, 0, At, B0); PG8_MMA(0, 1, At, B1); PG8_BAR; PG8_SCHED;
	s_setprio 1
	v_mfma_f32_16x16x32_bf16 v[78:81], v[142:145], v[176:179], v[78:81]
	v_mfma_f32_16x16x32_bf16 v[74:77], v[150:153], v[176:179], v[74:77]
	v_mfma_f32_16x16x32_bf16 v[98:101], v[142:145], v[184:187], v[98:101]
	v_mfma_f32_16x16x32_bf16 v[94:97], v[150:153], v[184:187], v[94:97]
	v_mfma_f32_16x16x32_bf16 v[118:121], v[142:145], v[192:195], v[118:121]
	v_mfma_f32_16x16x32_bf16 v[114:117], v[150:153], v[192:195], v[114:117]
	v_mfma_f32_16x16x32_bf16 v[134:137], v[142:145], v[200:203], v[134:137]
	v_mfma_f32_16x16x32_bf16 v[130:133], v[150:153], v[200:203], v[130:133]
	v_mfma_f32_16x16x32_bf16 v[78:81], v[146:149], v[180:183], v[78:81]
	v_mfma_f32_16x16x32_bf16 v[74:77], v[156:159], v[180:183], v[74:77]
	v_mfma_f32_16x16x32_bf16 v[98:101], v[146:149], v[188:191], v[98:101]
	v_mfma_f32_16x16x32_bf16 v[94:97], v[156:159], v[188:191], v[94:97]
	v_mfma_f32_16x16x32_bf16 v[118:121], v[146:149], v[196:199], v[118:121]
	v_mfma_f32_16x16x32_bf16 v[114:117], v[156:159], v[196:199], v[114:117]
	v_mfma_f32_16x16x32_bf16 v[134:137], v[146:149], v[204:207], v[134:137]
	v_mfma_f32_16x16x32_bf16 v[130:133], v[156:159], v[204:207], v[130:133]
	s_setprio 0
	s_setprio 1
	v_mfma_f32_16x16x32_bf16 v[70:73], v[160:163], v[176:179], v[70:73]
	v_mfma_f32_16x16x32_bf16 v[66:69], v[168:171], v[176:179], v[66:69]
	v_mfma_f32_16x16x32_bf16 v[90:93], v[160:163], v[184:187], v[90:93]
	v_mfma_f32_16x16x32_bf16 v[86:89], v[168:171], v[184:187], v[86:89]
	v_mfma_f32_16x16x32_bf16 v[110:113], v[160:163], v[192:195], v[110:113]
	v_mfma_f32_16x16x32_bf16 v[106:109], v[168:171], v[192:195], v[106:109]
	v_mfma_f32_16x16x32_bf16 v[102:105], v[160:163], v[200:203], v[102:105]
	v_mfma_f32_16x16x32_bf16 v[82:85], v[168:171], v[200:203], v[82:85]
	v_mfma_f32_16x16x32_bf16 v[70:73], v[164:167], v[180:183], v[70:73]
	v_mfma_f32_16x16x32_bf16 v[66:69], v[172:175], v[180:183], v[66:69]
	v_mfma_f32_16x16x32_bf16 v[90:93], v[164:167], v[188:191], v[90:93]
	v_mfma_f32_16x16x32_bf16 v[86:89], v[172:175], v[188:191], v[86:89]
	v_mfma_f32_16x16x32_bf16 v[110:113], v[164:167], v[196:199], v[110:113]
	v_mfma_f32_16x16x32_bf16 v[106:109], v[172:175], v[196:199], v[106:109]
	v_mfma_f32_16x16x32_bf16 v[102:105], v[164:167], v[204:207], v[102:105]
	v_mfma_f32_16x16x32_bf16 v[82:85], v[172:175], v[204:207], v[82:85]
	s_setprio 0
	s_barrier
	s_add_i32 s90, 0, 0x18000
	s_add_i32 s91, 0, 0x1c000
	v_add_u32_e32 v156, s90, v140
	v_add_u32_e32 v172, s91, v140
	ds_read_b128 v[142:145], v156
	ds_read_b128 v[146:149], v156 offset:1024
	ds_read_b128 v[150:153], v156 offset:2048
	ds_read_b128 v[156:159], v156 offset:3072
	ds_read_b128 v[160:163], v172
	ds_read_b128 v[164:167], v172 offset:1024
	ds_read_b128 v[168:171], v172 offset:2048
	ds_read_b128 v[172:175], v172 offset:3072
	s_add_u32 s52, s52, 0x100000
	s_addc_u32 s53, s53, 0
	s_mov_b32 m0, s29
	v_lshl_add_u64 v[216:217], s[52:53], 0, v[0:1]
	ds_read_b128 v[176:179], v141 offset:32768
	ds_read_b128 v[180:183], v141 offset:33792
	ds_read_b128 v[184:187], v141 offset:34816
	ds_read_b128 v[188:191], v141 offset:35840
	ds_read_b128 v[192:195], v141 offset:36864
	ds_read_b128 v[196:199], v141 offset:37888
	ds_read_b128 v[200:203], v141 offset:38912
	ds_read_b128 v[204:207], v141 offset:39936
	global_load_lds_dwordx4 v[216:217], off
	v_lshl_add_u64 v[216:217], s[52:53], 0, v[122:123]
	s_mov_b32 m0, s14
	s_nop 0
	global_load_lds_dwordx4 v[216:217], off
	s_waitcnt vmcnt(8)
	s_waitcnt lgkmcnt(0)
	s_barrier
	s_setprio 1
	v_mfma_f32_16x16x32_bf16 v[62:65], v[142:145], v[176:179], v[62:65]
	v_mfma_f32_16x16x32_bf16 v[42:45], v[150:153], v[176:179], v[42:45]
	v_mfma_f32_16x16x32_bf16 v[18:21], v[142:145], v[184:187], v[18:21]
	v_mfma_f32_16x16x32_bf16 v[14:17], v[150:153], v[184:187], v[14:17]
	v_mfma_f32_16x16x32_bf16 v[38:41], v[142:145], v[192:195], v[38:41]
	v_mfma_f32_16x16x32_bf16 v[30:33], v[150:153], v[192:195], v[30:33]
	v_mfma_f32_16x16x32_bf16 v[58:61], v[142:145], v[200:203], v[58:61]
	v_mfma_f32_16x16x32_bf16 v[54:57], v[150:153], v[200:203], v[54:57]
	v_mfma_f32_16x16x32_bf16 v[62:65], v[146:149], v[180:183], v[62:65]
	v_mfma_f32_16x16x32_bf16 v[42:45], v[156:159], v[180:183], v[42:45]
	v_mfma_f32_16x16x32_bf16 v[18:21], v[146:149], v[188:191], v[18:21]
	v_mfma_f32_16x16x32_bf16 v[14:17], v[156:159], v[188:191], v[14:17]
	v_mfma_f32_16x16x32_bf16 v[38:41], v[146:149], v[196:199], v[38:41]
	v_mfma_f32_16x16x32_bf16 v[30:33], v[156:159], v[196:199], v[30:33]
	v_mfma_f32_16x16x32_bf16 v[58:61], v[146:149], v[204:207], v[58:61]
	v_mfma_f32_16x16x32_bf16 v[54:57], v[156:159], v[204:207], v[54:57]
	s_setprio 0
	s_setprio 1
	v_mfma_f32_16x16x32_bf16 v[34:37], v[160:163], v[176:179], v[34:37]
	v_mfma_f32_16x16x32_bf16 v[2:5], v[168:171], v[176:179], v[2:5]
	v_mfma_f32_16x16x32_bf16 v[10:13], v[160:163], v[184:187], v[10:13]
	v_mfma_f32_16x16x32_bf16 v[6:9], v[168:171], v[184:187], v[6:9]
	v_mfma_f32_16x16x32_bf16 v[26:29], v[160:163], v[192:195], v[26:29]
	v_mfma_f32_16x16x32_bf16 v[22:25], v[168:171], v[192:195], v[22:25]
	v_mfma_f32_16x16x32_bf16 v[50:53], v[160:163], v[200:203], v[50:53]
	v_mfma_f32_16x16x32_bf16 v[46:49], v[168:171], v[200:203], v[46:49]
	v_mfma_f32_16x16x32_bf16 v[34:37], v[164:167], v[180:183], v[34:37]
	v_mfma_f32_16x16x32_bf16 v[2:5], v[172:175], v[180:183], v[2:5]
	v_mfma_f32_16x16x32_bf16 v[10:13], v[164:167], v[188:191], v[10:13]
	v_mfma_f32_16x16x32_bf16 v[6:9], v[172:175], v[188:191], v[6:9]
	v_mfma_f32_16x16x32_bf16 v[26:29], v[164:167], v[196:199], v[26:29]
	v_mfma_f32_16x16x32_bf16 v[22:25], v[172:175], v[196:199], v[22:25]
	v_mfma_f32_16x16x32_bf16 v[50:53], v[164:167], v[204:207], v[50:53]
	v_mfma_f32_16x16x32_bf16 v[46:49], v[172:175], v[204:207], v[46:49]
	s_setprio 0
	s_barrier
; #define PG8_STAGE(bufoff, gbase, voff) do { _Pragma("unroll") for (int _i = 0; _i < 2; ++_i) \
;         __builtin_amdgcn_global_load_lds((const unsigned*)((const char*)(gbase) + (voff)[_i]), (LAS unsigned*)(lds + (bufoff) + ldsw + _i * 8192), 16, 0, 0); } while (0)
; #define PG8_LDA(dst, b, h) do { _Pragma("unroll") for (int m = 0; m < 4; ++m) _Pragma("unroll") for (int k = 0; k < 2; ++k) dst[m][k] = *(const LAS bf16x8*)(lds + PG8_SA(b, h) + aoff + m * 2048 + k * 1024); } while (0)
; #define PG8_MMA(ai, bj, At, Bt) do { __builtin_amdgcn_s_setprio(1); _Pragma("unroll") for (int m = 0; m < 4; ++m) _Pragma("unroll") for (int n = 0; n < 2; ++n) _Pragma("unroll") for (int k = 0; k < 2; ++k) \
;         acc[ai][bj][m][n] = __builtin_amdgcn_mfma_f32_16x16x32_bf16(Bt[n][k], At[m][k], acc[ai][bj][m][n], 0, 0, 0); __builtin_amdgcn_s_setprio(0); } while (0)
; #define PG8_WAIT_V(n) asm volatile("s_waitcnt vmcnt(" #n ")" ::: "memory")
; #define PG8_WAIT_L(n) asm volatile("s_waitcnt lgkmcnt(" #n ")" ::: "memory")
; #define PG8_BAR __builtin_amdgcn_s_barrier()
; #define PG8_SCHED __builtin_amdgcn_sched_barrier(0)
; template <class Epi, class Sched, bool ALIGN_EPI, bool LAST_FUSED = false, bool PERM = false, bool CARRY = false>
; __device__ __forceinline__ void gemm_phase(LAS unsigned char* lds, const int tid, const int K, const int lda, const int ldb, const Sched& S, const Epi& E) {
;     ...
;             PG8_LDA(At, 1, 1); PG8_STAGE(PG8_SB(1, 0), b3, voffB); PG8_STAGE(PG8_SB(1, 1), b3 + hstepB, voffB); PG8_STAGE(PG8_SA(1, 0), a3, voffA);
;             PG8_WAIT_V(8); PG8_WAIT_L(0); PG8_BAR; PG8_MMA(1, 0, At, B0); PG8_MMA(1, 1, At, B1); PG8_BAR; PG8_SCHED;
;         }
;         if constexpr (ALIGN_EPI) { if (wr == 0) PG8_BAR; }
	s_add_i32 s52, s90, s76
	v_lshl_add_u64 v[208:209], v[208:209], 0, s[68:69]
	s_mov_b32 m0, s52
	ds_read_b128 v[176:179], v141 offset:49152
	ds_read_b128 v[180:183], v141 offset:50176
	ds_read_b128 v[184:187], v141 offset:51200
	ds_read_b128 v[188:191], v141 offset:52224
	ds_read_b128 v[192:195], v141 offset:53248
	ds_read_b128 v[196:199], v141 offset:54272
	ds_read_b128 v[200:203], v141 offset:55296
	ds_read_b128 v[204:207], v141 offset:56320
	global_load_lds_dwordx4 v[208:209], off
	s_add_i32 m0, s52, 0x2000
	s_add_u32 s52, s66, 0x100080
	v_lshl_add_u64 v[208:209], v[210:211], 0, s[68:69]
	s_addc_u32 s53, s67, 0
	s_add_i32 s66, s91, s76
	global_load_lds_dwordx4 v[208:209], off
	v_lshl_add_u64 v[208:209], s[52:53], 0, v[0:1]
	s_mov_b32 m0, s66
	s_nop 0
	global_load_lds_dwordx4 v[208:209], off
	v_lshl_add_u64 v[208:209], s[52:53], 0, v[122:123]
	s_add_i32 m0, s66, 0x2000
	s_nop 0
	global_load_lds_dwordx4 v[208:209], off
	v_lshl_add_u64 v[208:209], v[212:213], 0, s[68:69]
	s_mov_b32 m0, s77
	s_nop 0
	global_load_lds_dwordx4 v[208:209], off
	v_lshl_add_u64 v[208:209], v[214:215], 0, s[68:69]
	s_mov_b32 m0, s79
	s_nop 0
	global_load_lds_dwordx4 v[208:209], off
	s_waitcnt vmcnt(8)
	s_waitcnt lgkmcnt(0)
	s_barrier
	s_setprio 1
	v_mfma_f32_16x16x32_bf16 v[78:81], v[142:145], v[176:179], v[78:81]
	v_mfma_f32_16x16x32_bf16 v[74:77], v[150:153], v[176:179], v[74:77]
	v_mfma_f32_16x16x32_bf16 v[98:101], v[142:145], v[184:187], v[98:101]
	v_mfma_f32_16x16x32_bf16 v[94:97], v[150:153], v[184:187], v[94:97]
	v_mfma_f32_16x16x32_bf16 v[118:121], v[142:145], v[192:195], v[118:121]
	v_mfma_f32_16x16x32_bf16 v[114:117], v[150:153], v[192:195], v[114:117]
	v_mfma_f32_16x16x32_bf16 v[134:137], v[142:145], v[200:203], v[134:137]
	v_mfma_f32_16x16x32_bf16 v[130:133], v[150:153], v[200:203], v[130:133]
	v_mfma_f32_16x16x32_bf16 v[78:81], v[146:149], v[180:183], v[78:81]
	v_mfma_f32_16x16x32_bf16 v[74:77], v[156:159], v[180:183], v[74:77]
	v_mfma_f32_16x16x32_bf16 v[98:101], v[146:149], v[188:191], v[98:101]
	v_mfma_f32_16x16x32_bf16 v[94:97], v[156:159], v[188:191], v[94:97]
	v_mfma_f32_16x16x32_bf16 v[118:121], v[146:149], v[196:199], v[118:121]
	v_mfma_f32_16x16x32_bf16 v[114:117], v[156:159], v[196:199], v[114:117]
	v_mfma_f32_16x16x32_bf16 v[134:137], v[146:149], v[204:207], v[134:137]
	v_mfma_f32_16x16x32_bf16 v[130:133], v[156:159], v[204:207], v[130:133]
	s_setprio 0
	s_setprio 1
	v_mfma_f32_16x16x32_bf16 v[70:73], v[160:163], v[176:179], v[70:73]
	v_mfma_f32_16x16x32_bf16 v[66:69], v[168:171], v[176:179], v[66:69]
	v_mfma_f32_16x16x32_bf16 v[90:93], v[160:163], v[184:187], v[90:93]
	v_mfma_f32_16x16x32_bf16 v[86:89], v[168:171], v[184:187], v[86:89]
	v_mfma_f32_16x16x32_bf16 v[110:113], v[160:163], v[192:195], v[110:113]
	v_mfma_f32_16x16x32_bf16 v[106:109], v[168:171], v[192:195], v[106:109]
	v_mfma_f32_16x16x32_bf16 v[102:105], v[160:163], v[200:203], v[102:105]
	v_mfma_f32_16x16x32_bf16 v[82:85], v[168:171], v[200:203], v[82:85]
	v_mfma_f32_16x16x32_bf16 v[70:73], v[164:167], v[180:183], v[70:73]
	v_mfma_f32_16x16x32_bf16 v[66:69], v[172:175], v[180:183], v[66:69]
	v_mfma_f32_16x16x32_bf16 v[90:93], v[164:167], v[188:191], v[90:93]
	v_mfma_f32_16x16x32_bf16 v[86:89], v[172:175], v[188:191], v[86:89]
	v_mfma_f32_16x16x32_bf16 v[110:113], v[164:167], v[196:199], v[110:113]
	v_mfma_f32_16x16x32_bf16 v[106:109], v[172:175], v[196:199], v[106:109]
	v_mfma_f32_16x16x32_bf16 v[102:105], v[164:167], v[204:207], v[102:105]
	v_mfma_f32_16x16x32_bf16 v[82:85], v[172:175], v[204:207], v[82:85]
	s_setprio 0
	s_barrier
	s_add_i32 s52, s89, 2
	s_add_u32 s48, s48, 0x100
	s_addc_u32 s49, s49, 0
	v_lshl_add_u64 v[138:139], v[138:139], 0, s[72:73]
	v_lshl_add_u64 v[128:129], v[128:129], 0, s[72:73]
	s_cmp_ge_i32 s89, s3
	s_mov_b32 s89, s52
	s_cbranch_scc0 .LBB0_1662
	s_and_b64 vcc, exec, s[36:37]
	s_cbranch_vccz .LBB0_1665
	s_barrier

; #define PG8_STAGE(bufoff, gbase, voff) do { _Pragma("unroll") for (int _i = 0; _i < 2; ++_i) \
;         __builtin_amdgcn_global_load_lds((const unsigned*)((const char*)(gbase) + (voff)[_i]), (LAS unsigned*)(lds + (bufoff) + ldsw + _i * 8192), 16, 0, 0); } while (0)
; #define PG8_LDA(dst, b, h) do { _Pragma("unroll") for (int m = 0; m < 4; ++m) _Pragma("unroll") for (int k = 0; k < 2; ++k) dst[m][k] = *(const LAS bf16x8*)(lds + PG8_SA(b, h) + aoff + m * 2048 + k * 1024); } while (0)
; #define PG8_LDB(dst, b, h) do { _Pragma("unroll") for (int n = 0; n < 2; ++n) _Pragma("unroll") for (int k = 0; k < 2; ++k) dst[n][k] = *(const LAS bf16x8*)(lds + PG8_SB(b, h) + boff + n * 2048 + k * 1024); } while (0)
; #define PG8_MMA(ai, bj, At, Bt) do { __builtin_amdgcn_s_setprio(1); _Pragma("unroll") for (int m = 0; m < 4; ++m) _Pragma("unroll") for (int n = 0; n < 2; ++n) _Pragma("unroll") for (int k = 0; k < 2; ++k) \
;         acc[ai][bj][m][n] = __builtin_amdgcn_mfma_f32_16x16x32_bf16(Bt[n][k], At[m][k], acc[ai][bj][m][n], 0, 0, 0); __builtin_amdgcn_s_setprio(0); } while (0)
; #define PG8_WAIT_V(n) asm volatile("s_waitcnt vmcnt(" #n ")" ::: "memory")
; #define PG8_WAIT_L(n) asm volatile("s_waitcnt lgkmcnt(" #n ")" ::: "memory")
; #define PG8_BAR __builtin_amdgcn_s_barrier()
; template <class Epi, class Sched, bool ALIGN_EPI, bool LAST_FUSED = false, bool PERM = false, bool CARRY = false>
; __device__ __forceinline__ void gemm_phase(LAS unsigned char* lds, const int tid, const int K, const int lda, const int ldb, const Sched& S, const Epi& E) {
;     ...
;             const bool last = (t == nt - 2);
;             const char* a1 = cA + (size_t)(t + 1) * kstep;
;             const char* a2 = last ? nA : cA + (size_t)(t + 2) * kstep; const char* b2 = last ? nB : cB + (size_t)(t + 2) * kstep;
;             const char* a3 = a2 + kstep; const char* b3 = b2 + kstep;
;             PG8_LDB(B0, 0, 0); PG8_LDB(B1, 0, 1); PG8_SCHED; PG8_LDA(At, 0, 0); PG8_STAGE(PG8_SA(1, 1), a1 + hstepA, voffA);
;             PG8_WAIT_V(8); PG8_WAIT_L(0); PG8_BAR; PG8_MMA(0, 0, At, B0); PG8_MMA(0, 1, At, B1); PG8_BAR; PG8_SCHED;
;             PG8_LDA(At, 0, 1); PG8_STAGE(PG8_SB(0, 0), b2, voffB); PG8_STAGE(PG8_SB(0, 1), b2 + hstepB, voffB); PG8_STAGE(PG8_SA(0, 0), a2, voffA);
;             PG8_WAIT_V(8); PG8_WAIT_L(0); PG8_BAR; PG8_MMA(1, 0, At, B0); PG8_MMA(1, 1, At, B1); PG8_BAR; PG8_SCHED;
.LBB0_1763:
	s_add_u32 s16, s48, 0xfff80080
	s_addc_u32 s17, s49, -1
	s_add_i32 s67, 0, 0x10000
	s_cmp_eq_u32 s41, 28
	s_cselect_b32 s53, s43, s17
	s_cselect_b32 s52, s42, s16
	v_add_u32_e32 v140, s67, v146
	s_cselect_b32 s55, s51, s39
	s_cselect_b32 s54, s50, s27
	s_add_i32 s16, 0, 0x14000
	ds_read_b128 v[148:151], v140
	ds_read_b128 v[152:155], v140 offset:1024
	ds_read_b128 v[156:159], v140 offset:2048
	ds_read_b128 v[160:163], v140 offset:3072
	v_add_u32_e32 v140, s16, v146
	ds_read_b128 v[164:167], v140
	ds_read_b128 v[168:171], v140 offset:1024
	ds_read_b128 v[172:175], v140 offset:2048
	ds_read_b128 v[176:179], v140 offset:3072
	v_lshl_add_u64 v[140:141], s[48:49], 0, v[136:137]
	s_add_i32 m0, s47, 0xc000
	ds_read_b128 v[180:183], v147
	ds_read_b128 v[184:187], v147 offset:1024
	ds_read_b128 v[188:191], v147 offset:2048
	ds_read_b128 v[192:195], v147 offset:3072
	ds_read_b128 v[196:199], v147 offset:4096
	ds_read_b128 v[200:203], v147 offset:5120
	ds_read_b128 v[204:207], v147 offset:6144
	ds_read_b128 v[208:211], v147 offset:7168
	global_load_lds_dwordx4 v[140:141], off
	v_lshl_add_u64 v[140:141], s[48:49], 0, v[138:139]
	s_add_i32 m0, s47, 0xe000
	s_nop 0
	global_load_lds_dwordx4 v[140:141], off
	s_waitcnt vmcnt(8)
	s_waitcnt lgkmcnt(0)
	s_barrier
	s_setprio 1
	v_mfma_f32_16x16x32_bf16 v[126:129], v[148:151], v[180:183], v[126:129]
	v_mfma_f32_16x16x32_bf16 v[122:125], v[156:159], v[180:183], v[122:125]
	v_mfma_f32_16x16x32_bf16 v[110:113], v[148:151], v[188:191], v[110:113]
	v_mfma_f32_16x16x32_bf16 v[106:109], v[156:159], v[188:191], v[106:109]
	v_mfma_f32_16x16x32_bf16 v[94:97], v[148:151], v[196:199], v[94:97]
	v_mfma_f32_16x16x32_bf16 v[90:93], v[156:159], v[196:199], v[90:93]
	v_mfma_f32_16x16x32_bf16 v[78:81], v[148:151], v[204:207], v[78:81]
	v_mfma_f32_16x16x32_bf16 v[74:77], v[156:159], v[204:207], v[74:77]
	v_mfma_f32_16x16x32_bf16 v[126:129], v[152:155], v[184:187], v[126:129]
	v_mfma_f32_16x16x32_bf16 v[122:125], v[160:163], v[184:187], v[122:125]
	v_mfma_f32_16x16x32_bf16 v[110:113], v[152:155], v[192:195], v[110:113]
	v_mfma_f32_16x16x32_bf16 v[106:109], v[160:163], v[192:195], v[106:109]
	v_mfma_f32_16x16x32_bf16 v[94:97], v[152:155], v[200:203], v[94:97]
	v_mfma_f32_16x16x32_bf16 v[90:93], v[160:163], v[200:203], v[90:93]
	v_mfma_f32_16x16x32_bf16 v[78:81], v[152:155], v[208:211], v[78:81]
	v_mfma_f32_16x16x32_bf16 v[74:77], v[160:163], v[208:211], v[74:77]
	s_setprio 0
	s_setprio 1
	v_mfma_f32_16x16x32_bf16 v[118:121], v[164:167], v[180:183], v[118:121]
	v_mfma_f32_16x16x32_bf16 v[114:117], v[172:175], v[180:183], v[114:117]
	v_mfma_f32_16x16x32_bf16 v[102:105], v[164:167], v[188:191], v[102:105]
	v_mfma_f32_16x16x32_bf16 v[98:101], v[172:175], v[188:191], v[98:101]
	v_mfma_f32_16x16x32_bf16 v[86:89], v[164:167], v[196:199], v[86:89]
	v_mfma_f32_16x16x32_bf16 v[82:85], v[172:175], v[196:199], v[82:85]
	v_mfma_f32_16x16x32_bf16 v[70:73], v[164:167], v[204:207], v[70:73]
	v_mfma_f32_16x16x32_bf16 v[66:69], v[172:175], v[204:207], v[66:69]
	v_mfma_f32_16x16x32_bf16 v[118:121], v[168:171], v[184:187], v[118:121]
	v_mfma_f32_16x16x32_bf16 v[114:117], v[176:179], v[184:187], v[114:117]
	v_mfma_f32_16x16x32_bf16 v[102:105], v[168:171], v[192:195], v[102:105]
	v_mfma_f32_16x16x32_bf16 v[98:101], v[176:179], v[192:195], v[98:101]
	v_mfma_f32_16x16x32_bf16 v[86:89], v[168:171], v[200:203], v[86:89]
	v_mfma_f32_16x16x32_bf16 v[82:85], v[176:179], v[200:203], v[82:85]
	v_mfma_f32_16x16x32_bf16 v[70:73], v[168:171], v[208:211], v[70:73]
	v_mfma_f32_16x16x32_bf16 v[66:69], v[176:179], v[208:211], v[66:69]
	s_setprio 0
	s_barrier
	s_add_i32 s17, s67, s45
	v_lshl_add_u64 v[140:141], s[54:55], 0, v[0:1]
	s_mov_b32 m0, s17
	ds_read_b128 v[180:183], v147 offset:16384
	ds_read_b128 v[184:187], v147 offset:17408
	ds_read_b128 v[188:191], v147 offset:18432
	ds_read_b128 v[192:195], v147 offset:19456
	ds_read_b128 v[196:199], v147 offset:20480
	ds_read_b128 v[200:203], v147 offset:21504
	ds_read_b128 v[204:207], v147 offset:22528
	ds_read_b128 v[208:211], v147 offset:23552
	global_load_lds_dwordx4 v[140:141], off
	s_add_i32 m0, s17, 0x2000
	s_add_u32 s70, s54, 0x80000
	v_lshl_add_u64 v[212:213], s[54:55], 0, v[130:131]
	s_addc_u32 s71, s55, 0
	s_add_i32 s16, s16, s45
	global_load_lds_dwordx4 v[212:213], off
	v_lshl_add_u64 v[214:215], s[70:71], 0, v[0:1]
	s_mov_b32 m0, s16
	v_lshl_add_u64 v[216:217], s[52:53], 0, v[132:133]
	global_load_lds_dwordx4 v[214:215], off
	v_lshl_add_u64 v[214:215], s[70:71], 0, v[130:131]
	s_add_i32 m0, s16, 0x2000
	s_nop 0
	global_load_lds_dwordx4 v[214:215], off
	v_lshl_add_u64 v[214:215], s[52:53], 0, v[134:135]
	s_mov_b32 m0, s47
	s_nop 0
	global_load_lds_dwordx4 v[214:215], off
	s_mov_b32 m0, s57
	s_nop 0
	global_load_lds_dwordx4 v[216:217], off
	s_waitcnt vmcnt(8)
	s_waitcnt lgkmcnt(0)
	s_barrier
; #define PG8_STAGE(bufoff, gbase, voff) do { _Pragma("unroll") for (int _i = 0; _i < 2; ++_i) \
;         __builtin_amdgcn_global_load_lds((const unsigned*)((const char*)(gbase) + (voff)[_i]), (LAS unsigned*)(lds + (bufoff) + ldsw + _i * 8192), 16, 0, 0); } while (0)
; #define PG8_LDA(dst, b, h) do { _Pragma("unroll") for (int m = 0; m < 4; ++m) _Pragma("unroll") for (int k = 0; k < 2; ++k) dst[m][k] = *(const LAS bf16x8*)(lds + PG8_SA(b, h) + aoff + m * 2048 + k * 1024); } while (0)
; #define PG8_LDB(dst, b, h) do { _Pragma("unroll") for (int n = 0; n < 2; ++n) _Pragma("unroll") for (int k = 0; k < 2; ++k) dst[n][k] = *(const LAS bf16x8*)(lds + PG8_SB(b, h) + boff + n * 2048 + k * 1024); } while (0)
; #define PG8_MMA(ai, bj, At, Bt) do { __builtin_amdgcn_s_setprio(1); _Pragma("unroll") for (int m = 0; m < 4; ++m) _Pragma("unroll") for (int n = 0; n < 2; ++n) _Pragma("unroll") for (int k = 0; k < 2; ++k) \
;         acc[ai][bj][m][n] = __builtin_amdgcn_mfma_f32_16x16x32_bf16(Bt[n][k], At[m][k], acc[ai][bj][m][n], 0, 0, 0); __builtin_amdgcn_s_setprio(0); } while (0)
; #define PG8_WAIT_V(n) asm volatile("s_waitcnt vmcnt(" #n ")" ::: "memory")
; #define PG8_WAIT_L(n) asm volatile("s_waitcnt lgkmcnt(" #n ")" ::: "memory")
; #define PG8_BAR __builtin_amdgcn_s_barrier()
; #define PG8_SCHED __builtin_amdgcn_sched_barrier(0)
; template <class Epi, class Sched, bool ALIGN_EPI, bool LAST_FUSED = false, bool PERM = false, bool CARRY = false>
; __device__ __forceinline__ void gemm_phase(LAS unsigned char* lds, const int tid, const int K, const int lda, const int ldb, const Sched& S, const Epi& E) {
;     ...
;             PG8_WAIT_V(8); PG8_WAIT_L(0); PG8_BAR; PG8_MMA(1, 0, At, B0); PG8_MMA(1, 1, At, B1); PG8_BAR; PG8_SCHED;
;             PG8_LDB(B0, 1, 0); PG8_LDB(B1, 1, 1); PG8_SCHED; PG8_LDA(At, 1, 0); PG8_STAGE(PG8_SA(0, 1), a2 + hstepA, voffA);
;             PG8_WAIT_V(8); PG8_WAIT_L(0); PG8_BAR; PG8_MMA(0, 0, At, B0); PG8_MMA(0, 1, At, B1); PG8_BAR; PG8_SCHED;
	s_setprio 1
	v_mfma_f32_16x16x32_bf16 v[62:65], v[148:151], v[180:183], v[62:65]
	v_mfma_f32_16x16x32_bf16 v[58:61], v[156:159], v[180:183], v[58:61]
	v_mfma_f32_16x16x32_bf16 v[46:49], v[148:151], v[188:191], v[46:49]
	v_mfma_f32_16x16x32_bf16 v[42:45], v[156:159], v[188:191], v[42:45]
	v_mfma_f32_16x16x32_bf16 v[30:33], v[148:151], v[196:199], v[30:33]
	v_mfma_f32_16x16x32_bf16 v[26:29], v[156:159], v[196:199], v[26:29]
	v_mfma_f32_16x16x32_bf16 v[14:17], v[148:151], v[204:207], v[14:17]
	v_mfma_f32_16x16x32_bf16 v[10:13], v[156:159], v[204:207], v[10:13]
	v_mfma_f32_16x16x32_bf16 v[62:65], v[152:155], v[184:187], v[62:65]
	v_mfma_f32_16x16x32_bf16 v[58:61], v[160:163], v[184:187], v[58:61]
	v_mfma_f32_16x16x32_bf16 v[46:49], v[152:155], v[192:195], v[46:49]
	v_mfma_f32_16x16x32_bf16 v[42:45], v[160:163], v[192:195], v[42:45]
	v_mfma_f32_16x16x32_bf16 v[30:33], v[152:155], v[200:203], v[30:33]
	v_mfma_f32_16x16x32_bf16 v[26:29], v[160:163], v[200:203], v[26:29]
	v_mfma_f32_16x16x32_bf16 v[14:17], v[152:155], v[208:211], v[14:17]
	v_mfma_f32_16x16x32_bf16 v[10:13], v[160:163], v[208:211], v[10:13]
	s_setprio 0
	s_setprio 1
	v_mfma_f32_16x16x32_bf16 v[54:57], v[164:167], v[180:183], v[54:57]
	v_mfma_f32_16x16x32_bf16 v[50:53], v[172:175], v[180:183], v[50:53]
	v_mfma_f32_16x16x32_bf16 v[38:41], v[164:167], v[188:191], v[38:41]
	v_mfma_f32_16x16x32_bf16 v[34:37], v[172:175], v[188:191], v[34:37]
	v_mfma_f32_16x16x32_bf16 v[22:25], v[164:167], v[196:199], v[22:25]
	v_mfma_f32_16x16x32_bf16 v[18:21], v[172:175], v[196:199], v[18:21]
	v_mfma_f32_16x16x32_bf16 v[6:9], v[164:167], v[204:207], v[6:9]
	v_mfma_f32_16x16x32_bf16 v[2:5], v[172:175], v[204:207], v[2:5]
	v_mfma_f32_16x16x32_bf16 v[54:57], v[168:171], v[184:187], v[54:57]
	v_mfma_f32_16x16x32_bf16 v[50:53], v[176:179], v[184:187], v[50:53]
	v_mfma_f32_16x16x32_bf16 v[38:41], v[168:171], v[192:195], v[38:41]
	v_mfma_f32_16x16x32_bf16 v[34:37], v[176:179], v[192:195], v[34:37]
	v_mfma_f32_16x16x32_bf16 v[22:25], v[168:171], v[200:203], v[22:25]
	v_mfma_f32_16x16x32_bf16 v[18:21], v[176:179], v[200:203], v[18:21]
	v_mfma_f32_16x16x32_bf16 v[6:9], v[168:171], v[208:211], v[6:9]
	v_mfma_f32_16x16x32_bf16 v[2:5], v[176:179], v[208:211], v[2:5]
	s_setprio 0
	s_barrier
	s_add_i32 s16, 0, 0x18000
	s_add_i32 s17, 0, 0x1c000
	v_add_u32_e32 v160, s16, v146
	v_add_u32_e32 v176, s17, v146
	ds_read_b128 v[148:151], v160
	ds_read_b128 v[152:155], v160 offset:1024
	ds_read_b128 v[156:159], v160 offset:2048
	ds_read_b128 v[160:163], v160 offset:3072
	ds_read_b128 v[164:167], v176
	ds_read_b128 v[168:171], v176 offset:1024
	ds_read_b128 v[172:175], v176 offset:2048
	ds_read_b128 v[176:179], v176 offset:3072
	s_add_u32 s52, s52, 0x80000
	s_addc_u32 s53, s53, 0
	s_mov_b32 m0, s58
	v_lshl_add_u64 v[218:219], s[52:53], 0, v[134:135]
	ds_read_b128 v[180:183], v147 offset:32768
	ds_read_b128 v[184:187], v147 offset:33792
	ds_read_b128 v[188:191], v147 offset:34816
	ds_read_b128 v[192:195], v147 offset:35840
	ds_read_b128 v[196:199], v147 offset:36864
	ds_read_b128 v[200:203], v147 offset:37888
	ds_read_b128 v[204:207], v147 offset:38912
	ds_read_b128 v[208:211], v147 offset:39936
	global_load_lds_dwordx4 v[218:219], off
	v_lshl_add_u64 v[218:219], s[52:53], 0, v[132:133]
	s_mov_b32 m0, s59
	s_nop 0
	global_load_lds_dwordx4 v[218:219], off
	s_waitcnt vmcnt(8)
	s_waitcnt lgkmcnt(0)
	s_barrier
	s_setprio 1
	v_mfma_f32_16x16x32_bf16 v[126:129], v[148:151], v[180:183], v[126:129]
	v_mfma_f32_16x16x32_bf16 v[122:125], v[156:159], v[180:183], v[122:125]
	v_mfma_f32_16x16x32_bf16 v[110:113], v[148:151], v[188:191], v[110:113]
	v_mfma_f32_16x16x32_bf16 v[106:109], v[156:159], v[188:191], v[106:109]
	v_mfma_f32_16x16x32_bf16 v[94:97], v[148:151], v[196:199], v[94:97]
	v_mfma_f32_16x16x32_bf16 v[90:93], v[156:159], v[196:199], v[90:93]
	v_mfma_f32_16x16x32_bf16 v[78:81], v[148:151], v[204:207], v[78:81]
	v_mfma_f32_16x16x32_bf16 v[74:77], v[156:159], v[204:207], v[74:77]
	v_mfma_f32_16x16x32_bf16 v[126:129], v[152:155], v[184:187], v[126:129]
	v_mfma_f32_16x16x32_bf16 v[122:125], v[160:163], v[184:187], v[122:125]
	v_mfma_f32_16x16x32_bf16 v[110:113], v[152:155], v[192:195], v[110:113]
	v_mfma_f32_16x16x32_bf16 v[106:109], v[160:163], v[192:195], v[106:109]
	v_mfma_f32_16x16x32_bf16 v[94:97], v[152:155], v[200:203], v[94:97]
	v_mfma_f32_16x16x32_bf16 v[90:93], v[160:163], v[200:203], v[90:93]
	v_mfma_f32_16x16x32_bf16 v[78:81], v[152:155], v[208:211], v[78:81]
	v_mfma_f32_16x16x32_bf16 v[74:77], v[160:163], v[208:211], v[74:77]
	s_setprio 0
	s_setprio 1
	v_mfma_f32_16x16x32_bf16 v[118:121], v[164:167], v[180:183], v[118:121]
	v_mfma_f32_16x16x32_bf16 v[114:117], v[172:175], v[180:183], v[114:117]
	v_mfma_f32_16x16x32_bf16 v[102:105], v[164:167], v[188:191], v[102:105]
	v_mfma_f32_16x16x32_bf16 v[98:101], v[172:175], v[188:191], v[98:101]
	v_mfma_f32_16x16x32_bf16 v[86:89], v[164:167], v[196:199], v[86:89]
	v_mfma_f32_16x16x32_bf16 v[82:85], v[172:175], v[196:199], v[82:85]
	v_mfma_f32_16x16x32_bf16 v[70:73], v[164:167], v[204:207], v[70:73]
	v_mfma_f32_16x16x32_bf16 v[66:69], v[172:175], v[204:207], v[66:69]
	v_mfma_f32_16x16x32_bf16 v[118:121], v[168:171], v[184:187], v[118:121]
	v_mfma_f32_16x16x32_bf16 v[114:117], v[176:179], v[184:187], v[114:117]
	v_mfma_f32_16x16x32_bf16 v[102:105], v[168:171], v[192:195], v[102:105]
	v_mfma_f32_16x16x32_bf16 v[98:101], v[176:179], v[192:195], v[98:101]
	v_mfma_f32_16x16x32_bf16 v[86:89], v[168:171], v[200:203], v[86:89]
	v_mfma_f32_16x16x32_bf16 v[82:85], v[176:179], v[200:203], v[82:85]
	v_mfma_f32_16x16x32_bf16 v[70:73], v[168:171], v[208:211], v[70:73]
	v_mfma_f32_16x16x32_bf16 v[66:69], v[176:179], v[208:211], v[66:69]
	s_setprio 0
	s_barrier
; #define PG8_STAGE(bufoff, gbase, voff) do { _Pragma("unroll") for (int _i = 0; _i < 2; ++_i) \
;         __builtin_amdgcn_global_load_lds((const unsigned*)((const char*)(gbase) + (voff)[_i]), (LAS unsigned*)(lds + (bufoff) + ldsw + _i * 8192), 16, 0, 0); } while (0)
; #define PG8_LDA(dst, b, h) do { _Pragma("unroll") for (int m = 0; m < 4; ++m) _Pragma("unroll") for (int k = 0; k < 2; ++k) dst[m][k] = *(const LAS bf16x8*)(lds + PG8_SA(b, h) + aoff + m * 2048 + k * 1024); } while (0)
; #define PG8_MMA(ai, bj, At, Bt) do { __builtin_amdgcn_s_setprio(1); _Pragma("unroll") for (int m = 0; m < 4; ++m) _Pragma("unroll") for (int n = 0; n < 2; ++n) _Pragma("unroll") for (int k = 0; k < 2; ++k) \
;         acc[ai][bj][m][n] = __builtin_amdgcn_mfma_f32_16x16x32_bf16(Bt[n][k], At[m][k], acc[ai][bj][m][n], 0, 0, 0); __builtin_amdgcn_s_setprio(0); } while (0)
; #define PG8_WAIT_V(n) asm volatile("s_waitcnt vmcnt(" #n ")" ::: "memory")
; #define PG8_WAIT_L(n) asm volatile("s_waitcnt lgkmcnt(" #n ")" ::: "memory")
; #define PG8_BAR __builtin_amdgcn_s_barrier()
; #define PG8_SCHED __builtin_amdgcn_sched_barrier(0)
; template <class Epi, class Sched, bool ALIGN_EPI, bool LAST_FUSED = false, bool PERM = false, bool CARRY = false>
; __device__ __forceinline__ void gemm_phase(LAS unsigned char* lds, const int tid, const int K, const int lda, const int ldb, const Sched& S, const Epi& E) {
;     ...
;             PG8_LDA(At, 1, 1); PG8_STAGE(PG8_SB(1, 0), b3, voffB); PG8_STAGE(PG8_SB(1, 1), b3 + hstepB, voffB); PG8_STAGE(PG8_SA(1, 0), a3, voffA);
;             PG8_WAIT_V(8); PG8_WAIT_L(0); PG8_BAR; PG8_MMA(1, 0, At, B0); PG8_MMA(1, 1, At, B1); PG8_BAR; PG8_SCHED;
;         }
;         if constexpr (ALIGN_EPI) { if (wr == 0) PG8_BAR; }
	s_add_i32 s16, s16, s45
	v_lshl_add_u64 v[140:141], v[140:141], 0, s[68:69]
	s_mov_b32 m0, s16
	ds_read_b128 v[180:183], v147 offset:49152
	ds_read_b128 v[184:187], v147 offset:50176
	ds_read_b128 v[188:191], v147 offset:51200
	ds_read_b128 v[192:195], v147 offset:52224
	ds_read_b128 v[196:199], v147 offset:53248
	ds_read_b128 v[200:203], v147 offset:54272
	ds_read_b128 v[204:207], v147 offset:55296
	ds_read_b128 v[208:211], v147 offset:56320
	global_load_lds_dwordx4 v[140:141], off
	s_add_i32 m0, s16, 0x2000
	s_add_u32 s52, s54, 0x80080
	v_lshl_add_u64 v[140:141], v[212:213], 0, s[68:69]
	s_addc_u32 s53, s55, 0
	s_add_i32 s16, s17, s45
	global_load_lds_dwordx4 v[140:141], off
	v_lshl_add_u64 v[140:141], s[52:53], 0, v[0:1]
	s_mov_b32 m0, s16
	s_nop 0
	global_load_lds_dwordx4 v[140:141], off
	v_lshl_add_u64 v[140:141], s[52:53], 0, v[130:131]
	s_add_i32 m0, s16, 0x2000
	s_nop 0
	global_load_lds_dwordx4 v[140:141], off
	v_lshl_add_u64 v[140:141], v[214:215], 0, s[68:69]
	s_mov_b32 m0, s61
	s_nop 0
	global_load_lds_dwordx4 v[140:141], off
	v_lshl_add_u64 v[140:141], v[216:217], 0, s[68:69]
	s_mov_b32 m0, s62
	s_nop 0
	global_load_lds_dwordx4 v[140:141], off
	s_waitcnt vmcnt(8)
	s_waitcnt lgkmcnt(0)
	s_barrier
	s_setprio 1
	v_mfma_f32_16x16x32_bf16 v[62:65], v[148:151], v[180:183], v[62:65]
	v_mfma_f32_16x16x32_bf16 v[58:61], v[156:159], v[180:183], v[58:61]
	v_mfma_f32_16x16x32_bf16 v[46:49], v[148:151], v[188:191], v[46:49]
	v_mfma_f32_16x16x32_bf16 v[42:45], v[156:159], v[188:191], v[42:45]
	v_mfma_f32_16x16x32_bf16 v[30:33], v[148:151], v[196:199], v[30:33]
	v_mfma_f32_16x16x32_bf16 v[26:29], v[156:159], v[196:199], v[26:29]
	v_mfma_f32_16x16x32_bf16 v[14:17], v[148:151], v[204:207], v[14:17]
	v_mfma_f32_16x16x32_bf16 v[10:13], v[156:159], v[204:207], v[10:13]
	v_mfma_f32_16x16x32_bf16 v[62:65], v[152:155], v[184:187], v[62:65]
	v_mfma_f32_16x16x32_bf16 v[58:61], v[160:163], v[184:187], v[58:61]
	v_mfma_f32_16x16x32_bf16 v[46:49], v[152:155], v[192:195], v[46:49]
	v_mfma_f32_16x16x32_bf16 v[42:45], v[160:163], v[192:195], v[42:45]
	v_mfma_f32_16x16x32_bf16 v[30:33], v[152:155], v[200:203], v[30:33]
	v_mfma_f32_16x16x32_bf16 v[26:29], v[160:163], v[200:203], v[26:29]
	v_mfma_f32_16x16x32_bf16 v[14:17], v[152:155], v[208:211], v[14:17]
	v_mfma_f32_16x16x32_bf16 v[10:13], v[160:163], v[208:211], v[10:13]
	s_setprio 0
	s_setprio 1
	v_mfma_f32_16x16x32_bf16 v[54:57], v[164:167], v[180:183], v[54:57]
	v_mfma_f32_16x16x32_bf16 v[50:53], v[172:175], v[180:183], v[50:53]
	v_mfma_f32_16x16x32_bf16 v[38:41], v[164:167], v[188:191], v[38:41]
	v_mfma_f32_16x16x32_bf16 v[34:37], v[172:175], v[188:191], v[34:37]
	v_mfma_f32_16x16x32_bf16 v[22:25], v[164:167], v[196:199], v[22:25]
	v_mfma_f32_16x16x32_bf16 v[18:21], v[172:175], v[196:199], v[18:21]
	v_mfma_f32_16x16x32_bf16 v[6:9], v[164:167], v[204:207], v[6:9]
	v_mfma_f32_16x16x32_bf16 v[2:5], v[172:175], v[204:207], v[2:5]
	v_mfma_f32_16x16x32_bf16 v[54:57], v[168:171], v[184:187], v[54:57]
	v_mfma_f32_16x16x32_bf16 v[50:53], v[176:179], v[184:187], v[50:53]
	v_mfma_f32_16x16x32_bf16 v[38:41], v[168:171], v[192:195], v[38:41]
	v_mfma_f32_16x16x32_bf16 v[34:37], v[176:179], v[192:195], v[34:37]
	v_mfma_f32_16x16x32_bf16 v[22:25], v[168:171], v[200:203], v[22:25]
	v_mfma_f32_16x16x32_bf16 v[18:21], v[176:179], v[200:203], v[18:21]
	v_mfma_f32_16x16x32_bf16 v[6:9], v[168:171], v[208:211], v[6:9]
	v_mfma_f32_16x16x32_bf16 v[2:5], v[176:179], v[208:211], v[2:5]
	s_setprio 0
	s_barrier
	s_add_i32 s41, s41, 2
	s_add_u32 s48, s48, 0x100
	s_addc_u32 s49, s49, 0
	s_add_u32 s27, s27, 0x100
	s_addc_u32 s39, s39, 0
	s_cmp_gt_u32 s41, 29
	s_cbranch_scc0 .LBB0_1763
	s_and_b64 vcc, exec, s[36:37]
	s_cbranch_vccz .LBB0_1766
	s_barrier

; #define PG8_STAGE(bufoff, gbase, voff) do { _Pragma("unroll") for (int _i = 0; _i < 2; ++_i) \
;         __builtin_amdgcn_global_load_lds((const unsigned*)((const char*)(gbase) + (voff)[_i]), (LAS unsigned*)(lds + (bufoff) + ldsw + _i * 8192), 16, 0, 0); } while (0)
; #define PG8_LDA(dst, b, h) do { _Pragma("unroll") for (int m = 0; m < 4; ++m) _Pragma("unroll") for (int k = 0; k < 2; ++k) dst[m][k] = *(const LAS bf16x8*)(lds + PG8_SA(b, h) + aoff + m * 2048 + k * 1024); } while (0)
; #define PG8_LDB(dst, b, h) do { _Pragma("unroll") for (int n = 0; n < 2; ++n) _Pragma("unroll") for (int k = 0; k < 2; ++k) dst[n][k] = *(const LAS bf16x8*)(lds + PG8_SB(b, h) + boff + n * 2048 + k * 1024); } while (0)
; #define PG8_MMA(ai, bj, At, Bt) do { __builtin_amdgcn_s_setprio(1); _Pragma("unroll") for (int m = 0; m < 4; ++m) _Pragma("unroll") for (int n = 0; n < 2; ++n) _Pragma("unroll") for (int k = 0; k < 2; ++k) \
;         acc[ai][bj][m][n] = __builtin_amdgcn_mfma_f32_16x16x32_bf16(Bt[n][k], At[m][k], acc[ai][bj][m][n], 0, 0, 0); __builtin_amdgcn_s_setprio(0); } while (0)
; #define PG8_WAIT_V(n) asm volatile("s_waitcnt vmcnt(" #n ")" ::: "memory")
; #define PG8_WAIT_L(n) asm volatile("s_waitcnt lgkmcnt(" #n ")" ::: "memory")
; #define PG8_BAR __builtin_amdgcn_s_barrier()
; template <class Epi, class Sched, bool ALIGN_EPI, bool LAST_FUSED = false, bool PERM = false, bool CARRY = false>
; __device__ __forceinline__ void gemm_phase(LAS unsigned char* lds, const int tid, const int K, const int lda, const int ldb, const Sched& S, const Epi& E) {
;     ...
;             const bool last = (t == nt - 2);
;             const char* a1 = cA + (size_t)(t + 1) * kstep;
;             const char* a2 = last ? nA : cA + (size_t)(t + 2) * kstep; const char* b2 = last ? nB : cB + (size_t)(t + 2) * kstep;
;             const char* a3 = a2 + kstep; const char* b3 = b2 + kstep;
;             PG8_LDB(B0, 0, 0); PG8_LDB(B1, 0, 1); PG8_SCHED; PG8_LDA(At, 0, 0); PG8_STAGE(PG8_SA(1, 1), a1 + hstepA, voffA);
;             PG8_WAIT_V(8); PG8_WAIT_L(0); PG8_BAR; PG8_MMA(0, 0, At, B0); PG8_MMA(0, 1, At, B1); PG8_BAR; PG8_SCHED;
;             PG8_LDA(At, 0, 1); PG8_STAGE(PG8_SB(0, 0), b2, voffB); PG8_STAGE(PG8_SB(0, 1), b2 + hstepB, voffB); PG8_STAGE(PG8_SA(0, 0), a2, voffA);
;             PG8_WAIT_V(8); PG8_WAIT_L(0); PG8_BAR; PG8_MMA(1, 0, At, B0); PG8_MMA(1, 1, At, B1); PG8_BAR; PG8_SCHED;
.LBB0_1854:
	s_add_u32 s16, s66, vcc_lo
	s_addc_u32 s17, s67, vcc_hi
	s_add_u32 s52, s50, vcc_lo
	s_addc_u32 s53, s51, vcc_hi
	s_add_i32 s92, 0, 0x10000
	s_cmp_eq_u32 s87, s60
	s_cselect_b32 s57, s24, s17
	s_cselect_b32 s56, s91, s16
	v_add_u32_e32 v154, s92, v140
	s_cselect_b32 s53, s70, s53
	s_cselect_b32 s52, s71, s52
	s_add_i32 s93, 0, 0x14000
	ds_read_b128 v[142:145], v154
	ds_read_b128 v[146:149], v154 offset:1024
	ds_read_b128 v[150:153], v154 offset:2048
	ds_read_b128 v[158:161], v154 offset:3072
	v_add_u32_e32 v154, s93, v140
	ds_read_b128 v[162:165], v154
	ds_read_b128 v[166:169], v154 offset:1024
	ds_read_b128 v[170:173], v154 offset:2048
	ds_read_b128 v[174:177], v154 offset:3072
	v_lshl_add_u64 v[154:155], s[66:67], 0, v[138:139]
	s_add_i32 m0, s28, 0xc000
	ds_read_b128 v[178:181], v141
	ds_read_b128 v[182:185], v141 offset:1024
	ds_read_b128 v[186:189], v141 offset:2048
	ds_read_b128 v[190:193], v141 offset:3072
	ds_read_b128 v[194:197], v141 offset:4096
	ds_read_b128 v[198:201], v141 offset:5120
	ds_read_b128 v[202:205], v141 offset:6144
	ds_read_b128 v[206:209], v141 offset:7168
	global_load_lds_dwordx4 v[154:155], off
	v_lshl_add_u64 v[154:155], s[66:67], 0, v[128:129]
	s_add_i32 m0, s28, 0xe000
	s_nop 0
	global_load_lds_dwordx4 v[154:155], off
	s_waitcnt vmcnt(8)
	s_waitcnt lgkmcnt(0)
	s_barrier
	s_setprio 1
	v_mfma_f32_16x16x32_bf16 v[118:121], v[142:145], v[178:181], v[118:121]
	v_mfma_f32_16x16x32_bf16 v[114:117], v[150:153], v[178:181], v[114:117]
	v_mfma_f32_16x16x32_bf16 v[110:113], v[142:145], v[186:189], v[110:113]
	v_mfma_f32_16x16x32_bf16 v[106:109], v[150:153], v[186:189], v[106:109]
	v_mfma_f32_16x16x32_bf16 v[86:89], v[142:145], v[194:197], v[86:89]
	v_mfma_f32_16x16x32_bf16 v[82:85], v[150:153], v[194:197], v[82:85]
	v_mfma_f32_16x16x32_bf16 v[78:81], v[142:145], v[202:205], v[78:81]
	v_mfma_f32_16x16x32_bf16 v[74:77], v[150:153], v[202:205], v[74:77]
	v_mfma_f32_16x16x32_bf16 v[118:121], v[146:149], v[182:185], v[118:121]
	v_mfma_f32_16x16x32_bf16 v[114:117], v[158:161], v[182:185], v[114:117]
	v_mfma_f32_16x16x32_bf16 v[110:113], v[146:149], v[190:193], v[110:113]
	v_mfma_f32_16x16x32_bf16 v[106:109], v[158:161], v[190:193], v[106:109]
	v_mfma_f32_16x16x32_bf16 v[86:89], v[146:149], v[198:201], v[86:89]
	v_mfma_f32_16x16x32_bf16 v[82:85], v[158:161], v[198:201], v[82:85]
	v_mfma_f32_16x16x32_bf16 v[78:81], v[146:149], v[206:209], v[78:81]
	v_mfma_f32_16x16x32_bf16 v[74:77], v[158:161], v[206:209], v[74:77]
	s_setprio 0
	s_setprio 1
	v_mfma_f32_16x16x32_bf16 v[98:101], v[162:165], v[178:181], v[98:101]
	v_mfma_f32_16x16x32_bf16 v[102:105], v[170:173], v[178:181], v[102:105]
	v_mfma_f32_16x16x32_bf16 v[90:93], v[162:165], v[186:189], v[90:93]
	v_mfma_f32_16x16x32_bf16 v[94:97], v[170:173], v[186:189], v[94:97]
	v_mfma_f32_16x16x32_bf16 v[66:69], v[162:165], v[194:197], v[66:69]
	v_mfma_f32_16x16x32_bf16 v[70:73], v[170:173], v[194:197], v[70:73]
	v_mfma_f32_16x16x32_bf16 v[50:53], v[162:165], v[202:205], v[50:53]
	v_mfma_f32_16x16x32_bf16 v[54:57], v[170:173], v[202:205], v[54:57]
	v_mfma_f32_16x16x32_bf16 v[98:101], v[166:169], v[182:185], v[98:101]
	v_mfma_f32_16x16x32_bf16 v[102:105], v[174:177], v[182:185], v[102:105]
	v_mfma_f32_16x16x32_bf16 v[90:93], v[166:169], v[190:193], v[90:93]
	v_mfma_f32_16x16x32_bf16 v[94:97], v[174:177], v[190:193], v[94:97]
	v_mfma_f32_16x16x32_bf16 v[66:69], v[166:169], v[198:201], v[66:69]
	v_mfma_f32_16x16x32_bf16 v[70:73], v[174:177], v[198:201], v[70:73]
	v_mfma_f32_16x16x32_bf16 v[50:53], v[166:169], v[206:209], v[50:53]
	v_mfma_f32_16x16x32_bf16 v[54:57], v[174:177], v[206:209], v[54:57]
	s_setprio 0
	s_barrier
	s_add_i32 s16, s92, s95
	v_lshl_add_u64 v[154:155], s[52:53], 0, v[0:1]
	s_mov_b32 m0, s16
	ds_read_b128 v[178:181], v141 offset:16384
	ds_read_b128 v[182:185], v141 offset:17408
	ds_read_b128 v[186:189], v141 offset:18432
	ds_read_b128 v[190:193], v141 offset:19456
	ds_read_b128 v[194:197], v141 offset:20480
	ds_read_b128 v[198:201], v141 offset:21504
	ds_read_b128 v[202:205], v141 offset:22528
	ds_read_b128 v[206:209], v141 offset:23552
	global_load_lds_dwordx4 v[154:155], off
	s_add_i32 m0, s16, 0x2000
	s_add_u32 s16, s52, 0x200000
	v_lshl_add_u64 v[210:211], s[52:53], 0, v[122:123]
	s_addc_u32 s17, s53, 0
	s_add_i32 s92, s93, s95
	global_load_lds_dwordx4 v[210:211], off
	v_lshl_add_u64 v[212:213], s[16:17], 0, v[0:1]
	s_mov_b32 m0, s92
	v_lshl_add_u64 v[214:215], s[56:57], 0, v[122:123]
	global_load_lds_dwordx4 v[212:213], off
	v_lshl_add_u64 v[212:213], s[16:17], 0, v[122:123]
	s_add_i32 m0, s92, 0x2000
	s_nop 0
	global_load_lds_dwordx4 v[212:213], off
	v_lshl_add_u64 v[212:213], s[56:57], 0, v[0:1]
	s_mov_b32 m0, s28
	s_nop 0
	global_load_lds_dwordx4 v[212:213], off
	s_mov_b32 m0, s29
	s_nop 0
	global_load_lds_dwordx4 v[214:215], off
	s_waitcnt vmcnt(8)
	s_waitcnt lgkmcnt(0)
	s_barrier
; #define PG8_STAGE(bufoff, gbase, voff) do { _Pragma("unroll") for (int _i = 0; _i < 2; ++_i) \
;         __builtin_amdgcn_global_load_lds((const unsigned*)((const char*)(gbase) + (voff)[_i]), (LAS unsigned*)(lds + (bufoff) + ldsw + _i * 8192), 16, 0, 0); } while (0)
; #define PG8_LDA(dst, b, h) do { _Pragma("unroll") for (int m = 0; m < 4; ++m) _Pragma("unroll") for (int k = 0; k < 2; ++k) dst[m][k] = *(const LAS bf16x8*)(lds + PG8_SA(b, h) + aoff + m * 2048 + k * 1024); } while (0)
; #define PG8_LDB(dst, b, h) do { _Pragma("unroll") for (int n = 0; n < 2; ++n) _Pragma("unroll") for (int k = 0; k < 2; ++k) dst[n][k] = *(const LAS bf16x8*)(lds + PG8_SB(b, h) + boff + n * 2048 + k * 1024); } while (0)
; #define PG8_MMA(ai, bj, At, Bt) do { __builtin_amdgcn_s_setprio(1); _Pragma("unroll") for (int m = 0; m < 4; ++m) _Pragma("unroll") for (int n = 0; n < 2; ++n) _Pragma("unroll") for (int k = 0; k < 2; ++k) \
;         acc[ai][bj][m][n] = __builtin_amdgcn_mfma_f32_16x16x32_bf16(Bt[n][k], At[m][k], acc[ai][bj][m][n], 0, 0, 0); __builtin_amdgcn_s_setprio(0); } while (0)
; #define PG8_WAIT_V(n) asm volatile("s_waitcnt vmcnt(" #n ")" ::: "memory")
; #define PG8_WAIT_L(n) asm volatile("s_waitcnt lgkmcnt(" #n ")" ::: "memory")
; #define PG8_BAR __builtin_amdgcn_s_barrier()
; #define PG8_SCHED __builtin_amdgcn_sched_barrier(0)
; template <class Epi, class Sched, bool ALIGN_EPI, bool LAST_FUSED = false, bool PERM = false, bool CARRY = false>
; __device__ __forceinline__ void gemm_phase(LAS unsigned char* lds, const int tid, const int K, const int lda, const int ldb, const Sched& S, const Epi& E) {
;     ...
;             PG8_WAIT_V(8); PG8_WAIT_L(0); PG8_BAR; PG8_MMA(1, 0, At, B0); PG8_MMA(1, 1, At, B1); PG8_BAR; PG8_SCHED;
;             PG8_LDB(B0, 1, 0); PG8_LDB(B1, 1, 1); PG8_SCHED; PG8_LDA(At, 1, 0); PG8_STAGE(PG8_SA(0, 1), a2 + hstepA, voffA);
;             PG8_WAIT_V(8); PG8_WAIT_L(0); PG8_BAR; PG8_MMA(0, 0, At, B0); PG8_MMA(0, 1, At, B1); PG8_BAR; PG8_SCHED;
	s_setprio 1
	v_mfma_f32_16x16x32_bf16 v[62:65], v[142:145], v[178:181], v[62:65]
	v_mfma_f32_16x16x32_bf16 v[58:61], v[150:153], v[178:181], v[58:61]
	v_mfma_f32_16x16x32_bf16 v[38:41], v[142:145], v[186:189], v[38:41]
	v_mfma_f32_16x16x32_bf16 v[34:37], v[150:153], v[186:189], v[34:37]
	v_mfma_f32_16x16x32_bf16 v[22:25], v[142:145], v[194:197], v[22:25]
	v_mfma_f32_16x16x32_bf16 v[18:21], v[150:153], v[194:197], v[18:21]
	v_mfma_f32_16x16x32_bf16 v[134:137], v[142:145], v[202:205], v[134:137]
	v_mfma_f32_16x16x32_bf16 v[130:133], v[150:153], v[202:205], v[130:133]
	v_mfma_f32_16x16x32_bf16 v[62:65], v[146:149], v[182:185], v[62:65]
	v_mfma_f32_16x16x32_bf16 v[58:61], v[158:161], v[182:185], v[58:61]
	v_mfma_f32_16x16x32_bf16 v[38:41], v[146:149], v[190:193], v[38:41]
	v_mfma_f32_16x16x32_bf16 v[34:37], v[158:161], v[190:193], v[34:37]
	v_mfma_f32_16x16x32_bf16 v[22:25], v[146:149], v[198:201], v[22:25]
	v_mfma_f32_16x16x32_bf16 v[18:21], v[158:161], v[198:201], v[18:21]
	v_mfma_f32_16x16x32_bf16 v[134:137], v[146:149], v[206:209], v[134:137]
	v_mfma_f32_16x16x32_bf16 v[130:133], v[158:161], v[206:209], v[130:133]
	s_setprio 0
	s_setprio 1
	v_mfma_f32_16x16x32_bf16 v[42:45], v[162:165], v[178:181], v[42:45]
	v_mfma_f32_16x16x32_bf16 v[46:49], v[170:173], v[178:181], v[46:49]
	v_mfma_f32_16x16x32_bf16 v[26:29], v[162:165], v[186:189], v[26:29]
	v_mfma_f32_16x16x32_bf16 v[30:33], v[170:173], v[186:189], v[30:33]
	v_mfma_f32_16x16x32_bf16 v[14:17], v[162:165], v[194:197], v[14:17]
	v_mfma_f32_16x16x32_bf16 v[10:13], v[170:173], v[194:197], v[10:13]
	v_mfma_f32_16x16x32_bf16 v[6:9], v[162:165], v[202:205], v[6:9]
	v_mfma_f32_16x16x32_bf16 v[2:5], v[170:173], v[202:205], v[2:5]
	v_mfma_f32_16x16x32_bf16 v[42:45], v[166:169], v[182:185], v[42:45]
	v_mfma_f32_16x16x32_bf16 v[46:49], v[174:177], v[182:185], v[46:49]
	v_mfma_f32_16x16x32_bf16 v[26:29], v[166:169], v[190:193], v[26:29]
	v_mfma_f32_16x16x32_bf16 v[30:33], v[174:177], v[190:193], v[30:33]
	v_mfma_f32_16x16x32_bf16 v[14:17], v[166:169], v[198:201], v[14:17]
	v_mfma_f32_16x16x32_bf16 v[10:13], v[174:177], v[198:201], v[10:13]
	v_mfma_f32_16x16x32_bf16 v[6:9], v[166:169], v[206:209], v[6:9]
	v_mfma_f32_16x16x32_bf16 v[2:5], v[174:177], v[206:209], v[2:5]
	s_setprio 0
	s_barrier
	s_add_i32 s92, 0, 0x18000
	s_add_i32 s93, 0, 0x1c000
	v_add_u32_e32 v158, s92, v140
	v_add_u32_e32 v174, s93, v140
	ds_read_b128 v[142:145], v158
	ds_read_b128 v[146:149], v158 offset:1024
	ds_read_b128 v[150:153], v158 offset:2048
	ds_read_b128 v[158:161], v158 offset:3072
	ds_read_b128 v[162:165], v174
	ds_read_b128 v[166:169], v174 offset:1024
	ds_read_b128 v[170:173], v174 offset:2048
	ds_read_b128 v[174:177], v174 offset:3072
	s_add_u32 s16, s56, 0x200000
	s_addc_u32 s17, s57, 0
	s_mov_b32 m0, s14
	v_lshl_add_u64 v[216:217], s[16:17], 0, v[0:1]
	ds_read_b128 v[178:181], v141 offset:32768
	ds_read_b128 v[182:185], v141 offset:33792
	ds_read_b128 v[186:189], v141 offset:34816
	ds_read_b128 v[190:193], v141 offset:35840
	ds_read_b128 v[194:197], v141 offset:36864
	ds_read_b128 v[198:201], v141 offset:37888
	ds_read_b128 v[202:205], v141 offset:38912
	ds_read_b128 v[206:209], v141 offset:39936
	global_load_lds_dwordx4 v[216:217], off
	v_lshl_add_u64 v[216:217], s[16:17], 0, v[122:123]
	s_mov_b32 m0, s22
	s_nop 0
	global_load_lds_dwordx4 v[216:217], off
	s_waitcnt vmcnt(8)
	s_waitcnt lgkmcnt(0)
	s_barrier
	s_setprio 1
	v_mfma_f32_16x16x32_bf16 v[118:121], v[142:145], v[178:181], v[118:121]
	v_mfma_f32_16x16x32_bf16 v[114:117], v[150:153], v[178:181], v[114:117]
	v_mfma_f32_16x16x32_bf16 v[110:113], v[142:145], v[186:189], v[110:113]
	v_mfma_f32_16x16x32_bf16 v[106:109], v[150:153], v[186:189], v[106:109]
	v_mfma_f32_16x16x32_bf16 v[86:89], v[142:145], v[194:197], v[86:89]
	v_mfma_f32_16x16x32_bf16 v[82:85], v[150:153], v[194:197], v[82:85]
	v_mfma_f32_16x16x32_bf16 v[78:81], v[142:145], v[202:205], v[78:81]
	v_mfma_f32_16x16x32_bf16 v[74:77], v[150:153], v[202:205], v[74:77]
	v_mfma_f32_16x16x32_bf16 v[118:121], v[146:149], v[182:185], v[118:121]
	v_mfma_f32_16x16x32_bf16 v[114:117], v[158:161], v[182:185], v[114:117]
	v_mfma_f32_16x16x32_bf16 v[110:113], v[146:149], v[190:193], v[110:113]
	v_mfma_f32_16x16x32_bf16 v[106:109], v[158:161], v[190:193], v[106:109]
	v_mfma_f32_16x16x32_bf16 v[86:89], v[146:149], v[198:201], v[86:89]
	v_mfma_f32_16x16x32_bf16 v[82:85], v[158:161], v[198:201], v[82:85]
	v_mfma_f32_16x16x32_bf16 v[78:81], v[146:149], v[206:209], v[78:81]
	v_mfma_f32_16x16x32_bf16 v[74:77], v[158:161], v[206:209], v[74:77]
	s_setprio 0
	s_setprio 1
	v_mfma_f32_16x16x32_bf16 v[98:101], v[162:165], v[178:181], v[98:101]
	v_mfma_f32_16x16x32_bf16 v[102:105], v[170:173], v[178:181], v[102:105]
	v_mfma_f32_16x16x32_bf16 v[90:93], v[162:165], v[186:189], v[90:93]
	v_mfma_f32_16x16x32_bf16 v[94:97], v[170:173], v[186:189], v[94:97]
	v_mfma_f32_16x16x32_bf16 v[66:69], v[162:165], v[194:197], v[66:69]
	v_mfma_f32_16x16x32_bf16 v[70:73], v[170:173], v[194:197], v[70:73]
	v_mfma_f32_16x16x32_bf16 v[50:53], v[162:165], v[202:205], v[50:53]
	v_mfma_f32_16x16x32_bf16 v[54:57], v[170:173], v[202:205], v[54:57]
	v_mfma_f32_16x16x32_bf16 v[98:101], v[166:169], v[182:185], v[98:101]
	v_mfma_f32_16x16x32_bf16 v[102:105], v[174:177], v[182:185], v[102:105]
	v_mfma_f32_16x16x32_bf16 v[90:93], v[166:169], v[190:193], v[90:93]
	v_mfma_f32_16x16x32_bf16 v[94:97], v[174:177], v[190:193], v[94:97]
	v_mfma_f32_16x16x32_bf16 v[66:69], v[166:169], v[198:201], v[66:69]
	v_mfma_f32_16x16x32_bf16 v[70:73], v[174:177], v[198:201], v[70:73]
	v_mfma_f32_16x16x32_bf16 v[50:53], v[166:169], v[206:209], v[50:53]
	v_mfma_f32_16x16x32_bf16 v[54:57], v[174:177], v[206:209], v[54:57]
	s_setprio 0
	s_barrier
; #define PG8_STAGE(bufoff, gbase, voff) do { _Pragma("unroll") for (int _i = 0; _i < 2; ++_i) \
;         __builtin_amdgcn_global_load_lds((const unsigned*)((const char*)(gbase) + (voff)[_i]), (LAS unsigned*)(lds + (bufoff) + ldsw + _i * 8192), 16, 0, 0); } while (0)
; #define PG8_LDA(dst, b, h) do { _Pragma("unroll") for (int m = 0; m < 4; ++m) _Pragma("unroll") for (int k = 0; k < 2; ++k) dst[m][k] = *(const LAS bf16x8*)(lds + PG8_SA(b, h) + aoff + m * 2048 + k * 1024); } while (0)
; #define PG8_MMA(ai, bj, At, Bt) do { __builtin_amdgcn_s_setprio(1); _Pragma("unroll") for (int m = 0; m < 4; ++m) _Pragma("unroll") for (int n = 0; n < 2; ++n) _Pragma("unroll") for (int k = 0; k < 2; ++k) \
;         acc[ai][bj][m][n] = __builtin_amdgcn_mfma_f32_16x16x32_bf16(Bt[n][k], At[m][k], acc[ai][bj][m][n], 0, 0, 0); __builtin_amdgcn_s_setprio(0); } while (0)
; #define PG8_WAIT_V(n) asm volatile("s_waitcnt vmcnt(" #n ")" ::: "memory")
; #define PG8_WAIT_L(n) asm volatile("s_waitcnt lgkmcnt(" #n ")" ::: "memory")
; #define PG8_BAR __builtin_amdgcn_s_barrier()
; #define PG8_SCHED __builtin_amdgcn_sched_barrier(0)
; template <class Epi, class Sched, bool ALIGN_EPI, bool LAST_FUSED = false, bool PERM = false, bool CARRY = false>
; __device__ __forceinline__ void gemm_phase(LAS unsigned char* lds, const int tid, const int K, const int lda, const int ldb, const Sched& S, const Epi& E) {
;     ...
;             PG8_LDA(At, 1, 1); PG8_STAGE(PG8_SB(1, 0), b3, voffB); PG8_STAGE(PG8_SB(1, 1), b3 + hstepB, voffB); PG8_STAGE(PG8_SA(1, 0), a3, voffA);
;             PG8_WAIT_V(8); PG8_WAIT_L(0); PG8_BAR; PG8_MMA(1, 0, At, B0); PG8_MMA(1, 1, At, B1); PG8_BAR; PG8_SCHED;
;         }
;         if constexpr (ALIGN_EPI) { if (wr == 0) PG8_BAR; }
	s_add_i32 s16, s92, s95
	v_lshl_add_u64 v[154:155], v[154:155], 0, s[68:69]
	s_mov_b32 m0, s16
	ds_read_b128 v[178:181], v141 offset:49152
	ds_read_b128 v[182:185], v141 offset:50176
	ds_read_b128 v[186:189], v141 offset:51200
	ds_read_b128 v[190:193], v141 offset:52224
	ds_read_b128 v[194:197], v141 offset:53248
	ds_read_b128 v[198:201], v141 offset:54272
	ds_read_b128 v[202:205], v141 offset:55296
	ds_read_b128 v[206:209], v141 offset:56320
	global_load_lds_dwordx4 v[154:155], off
	s_add_i32 m0, s16, 0x2000
	s_add_u32 s16, s52, 0x200080
	v_lshl_add_u64 v[154:155], v[210:211], 0, s[68:69]
	s_addc_u32 s17, s53, 0
	s_add_i32 s52, s93, s95
	global_load_lds_dwordx4 v[154:155], off
	v_lshl_add_u64 v[154:155], s[16:17], 0, v[0:1]
	s_mov_b32 m0, s52
	s_nop 0
	global_load_lds_dwordx4 v[154:155], off
	v_lshl_add_u64 v[154:155], s[16:17], 0, v[122:123]
	s_add_i32 m0, s52, 0x2000
	s_nop 0
	global_load_lds_dwordx4 v[154:155], off
	v_lshl_add_u64 v[154:155], v[212:213], 0, s[68:69]
	s_mov_b32 m0, s96
	s_nop 0
	global_load_lds_dwordx4 v[154:155], off
	v_lshl_add_u64 v[154:155], v[214:215], 0, s[68:69]
	s_mov_b32 m0, s97
	s_nop 0
	global_load_lds_dwordx4 v[154:155], off
	s_waitcnt vmcnt(8)
	s_waitcnt lgkmcnt(0)
	s_barrier
	s_setprio 1
	v_mfma_f32_16x16x32_bf16 v[62:65], v[142:145], v[178:181], v[62:65]
	v_mfma_f32_16x16x32_bf16 v[58:61], v[150:153], v[178:181], v[58:61]
	v_mfma_f32_16x16x32_bf16 v[38:41], v[142:145], v[186:189], v[38:41]
	v_mfma_f32_16x16x32_bf16 v[34:37], v[150:153], v[186:189], v[34:37]
	v_mfma_f32_16x16x32_bf16 v[22:25], v[142:145], v[194:197], v[22:25]
	v_mfma_f32_16x16x32_bf16 v[18:21], v[150:153], v[194:197], v[18:21]
	v_mfma_f32_16x16x32_bf16 v[134:137], v[142:145], v[202:205], v[134:137]
	v_mfma_f32_16x16x32_bf16 v[130:133], v[150:153], v[202:205], v[130:133]
	v_mfma_f32_16x16x32_bf16 v[62:65], v[146:149], v[182:185], v[62:65]
	v_mfma_f32_16x16x32_bf16 v[58:61], v[158:161], v[182:185], v[58:61]
	v_mfma_f32_16x16x32_bf16 v[38:41], v[146:149], v[190:193], v[38:41]
	v_mfma_f32_16x16x32_bf16 v[34:37], v[158:161], v[190:193], v[34:37]
	v_mfma_f32_16x16x32_bf16 v[22:25], v[146:149], v[198:201], v[22:25]
	v_mfma_f32_16x16x32_bf16 v[18:21], v[158:161], v[198:201], v[18:21]
	v_mfma_f32_16x16x32_bf16 v[134:137], v[146:149], v[206:209], v[134:137]
	v_mfma_f32_16x16x32_bf16 v[130:133], v[158:161], v[206:209], v[130:133]
	s_setprio 0
	s_setprio 1
	v_mfma_f32_16x16x32_bf16 v[42:45], v[162:165], v[178:181], v[42:45]
	v_mfma_f32_16x16x32_bf16 v[46:49], v[170:173], v[178:181], v[46:49]
	v_mfma_f32_16x16x32_bf16 v[26:29], v[162:165], v[186:189], v[26:29]
	v_mfma_f32_16x16x32_bf16 v[30:33], v[170:173], v[186:189], v[30:33]
	v_mfma_f32_16x16x32_bf16 v[14:17], v[162:165], v[194:197], v[14:17]
	v_mfma_f32_16x16x32_bf16 v[10:13], v[170:173], v[194:197], v[10:13]
	v_mfma_f32_16x16x32_bf16 v[6:9], v[162:165], v[202:205], v[6:9]
	v_mfma_f32_16x16x32_bf16 v[2:5], v[170:173], v[202:205], v[2:5]
	v_mfma_f32_16x16x32_bf16 v[42:45], v[166:169], v[182:185], v[42:45]
	v_mfma_f32_16x16x32_bf16 v[46:49], v[174:177], v[182:185], v[46:49]
	v_mfma_f32_16x16x32_bf16 v[26:29], v[166:169], v[190:193], v[26:29]
	v_mfma_f32_16x16x32_bf16 v[30:33], v[174:177], v[190:193], v[30:33]
	v_mfma_f32_16x16x32_bf16 v[14:17], v[166:169], v[198:201], v[14:17]
	v_mfma_f32_16x16x32_bf16 v[10:13], v[174:177], v[198:201], v[10:13]
	v_mfma_f32_16x16x32_bf16 v[6:9], v[166:169], v[206:209], v[6:9]
	v_mfma_f32_16x16x32_bf16 v[2:5], v[174:177], v[206:209], v[2:5]
	s_setprio 0
	s_barrier
	s_add_i32 s16, s60, 2
	s_add_u32 vcc_lo, vcc_lo, 0x100
	s_addc_u32 vcc_hi, vcc_hi, 0
	v_lshl_add_u64 v[138:139], v[138:139], 0, s[72:73]
	v_lshl_add_u64 v[128:129], v[128:129], 0, s[72:73]
	s_cmp_ge_i32 s60, s87
	s_mov_b32 s60, s16
	s_cbranch_scc0 .LBB0_1854
	s_and_b64 vcc, exec, s[40:41]
	s_cbranch_vccz .LBB0_1857
	s_barrier
